# v16 + GEMM K-loop load segments: LDS-DMA pieces issued first while the LDS is quiet, fragment ds_reads after them
# speedup vs baseline: 1.0038x; 1.0038x over previous
.LBB0_849:
	s_add_u32 s74, s72, 0xfff80080
	s_addc_u32 s75, s73, -1
	s_cmp_eq_u32 s85, 28
	s_cselect_b32 s77, s63, s75
	s_cselect_b32 s76, s69, s74
	s_cselect_b32 s75, s57, s84
	s_cselect_b32 s74, s71, s83
	v_lshl_add_u64 v[220:221], s[72:73], 0, v[138:139]
	s_add_i32 m0, s3, 0xc000
	s_nop 0
	global_load_lds_dwordx4 v[220:221], off
	v_lshl_add_u64 v[220:221], s[72:73], 0, v[140:141]
	s_add_i32 m0, s3, 0xe000
	s_nop 0
	global_load_lds_dwordx4 v[220:221], off
	ds_read_b128 v[146:149], v155
	ds_read_b128 v[160:163], v155 offset:1024
	ds_read_b128 v[164:167], v155 offset:2048
	ds_read_b128 v[168:171], v155 offset:3072
	ds_read_b128 v[172:175], v156
	ds_read_b128 v[176:179], v156 offset:1024
	ds_read_b128 v[180:183], v156 offset:2048
	ds_read_b128 v[184:187], v156 offset:3072
	ds_read_b128 v[188:191], v157
	ds_read_b128 v[192:195], v157 offset:1024
	ds_read_b128 v[196:199], v157 offset:2048
	ds_read_b128 v[200:203], v157 offset:3072
	ds_read_b128 v[204:207], v157 offset:4096
	ds_read_b128 v[208:211], v157 offset:5120
	ds_read_b128 v[212:215], v157 offset:6144
	ds_read_b128 v[216:219], v157 offset:7168
	s_waitcnt vmcnt(8)
	s_waitcnt lgkmcnt(0)
	s_barrier
	s_setprio 1
	s_waitcnt lgkmcnt(0)
	v_mfma_f32_16x16x32_bf16 v[124:127], v[146:149], v[188:191], v[124:127]
	v_mfma_f32_16x16x32_bf16 v[120:123], v[164:167], v[188:191], v[120:123]
	v_mfma_f32_16x16x32_bf16 v[108:111], v[146:149], v[196:199], v[108:111]
	v_mfma_f32_16x16x32_bf16 v[104:107], v[164:167], v[196:199], v[104:107]
	v_mfma_f32_16x16x32_bf16 v[92:95], v[146:149], v[204:207], v[92:95]
	v_mfma_f32_16x16x32_bf16 v[88:91], v[164:167], v[204:207], v[88:91]
	v_mfma_f32_16x16x32_bf16 v[76:79], v[146:149], v[212:215], v[76:79]
	v_mfma_f32_16x16x32_bf16 v[72:75], v[164:167], v[212:215], v[72:75]
	v_mfma_f32_16x16x32_bf16 v[124:127], v[160:163], v[192:195], v[124:127]
	v_mfma_f32_16x16x32_bf16 v[120:123], v[168:171], v[192:195], v[120:123]
	v_mfma_f32_16x16x32_bf16 v[108:111], v[160:163], v[200:203], v[108:111]
	v_mfma_f32_16x16x32_bf16 v[104:107], v[168:171], v[200:203], v[104:107]
	v_mfma_f32_16x16x32_bf16 v[92:95], v[160:163], v[208:211], v[92:95]
	v_mfma_f32_16x16x32_bf16 v[88:91], v[168:171], v[208:211], v[88:91]
	v_mfma_f32_16x16x32_bf16 v[76:79], v[160:163], v[216:219], v[76:79]
	v_mfma_f32_16x16x32_bf16 v[72:75], v[168:171], v[216:219], v[72:75]
	v_mfma_f32_16x16x32_bf16 v[116:119], v[172:175], v[188:191], v[116:119]
	v_mfma_f32_16x16x32_bf16 v[112:115], v[180:183], v[188:191], v[112:115]
	v_mfma_f32_16x16x32_bf16 v[100:103], v[172:175], v[196:199], v[100:103]
	v_mfma_f32_16x16x32_bf16 v[96:99], v[180:183], v[196:199], v[96:99]
	v_mfma_f32_16x16x32_bf16 v[84:87], v[172:175], v[204:207], v[84:87]
	v_mfma_f32_16x16x32_bf16 v[80:83], v[180:183], v[204:207], v[80:83]
	v_mfma_f32_16x16x32_bf16 v[68:71], v[172:175], v[212:215], v[68:71]
	v_mfma_f32_16x16x32_bf16 v[64:67], v[180:183], v[212:215], v[64:67]
	v_mfma_f32_16x16x32_bf16 v[116:119], v[176:179], v[192:195], v[116:119]
	v_mfma_f32_16x16x32_bf16 v[112:115], v[184:187], v[192:195], v[112:115]
	v_mfma_f32_16x16x32_bf16 v[100:103], v[176:179], v[200:203], v[100:103]
	v_mfma_f32_16x16x32_bf16 v[96:99], v[184:187], v[200:203], v[96:99]
	v_mfma_f32_16x16x32_bf16 v[84:87], v[176:179], v[208:211], v[84:87]
	v_mfma_f32_16x16x32_bf16 v[80:83], v[184:187], v[208:211], v[80:83]
	v_mfma_f32_16x16x32_bf16 v[68:71], v[176:179], v[216:219], v[68:71]
	v_mfma_f32_16x16x32_bf16 v[64:67], v[184:187], v[216:219], v[64:67]
	s_setprio 0
	s_barrier
	s_add_i32 s86, s79, s94
	v_lshl_add_u64 v[220:221], s[74:75], 0, v[130:131]
	s_mov_b32 m0, s86
	s_nop 0
	global_load_lds_dwordx4 v[220:221], off
	s_add_i32 m0, s86, 0x2000
	s_add_u32 s86, s74, 0x80000
	v_lshl_add_u64 v[222:223], s[74:75], 0, v[134:135]
	s_addc_u32 s87, s75, 0
	s_add_i32 s88, s81, s94
	global_load_lds_dwordx4 v[222:223], off
	v_lshl_add_u64 v[224:225], s[86:87], 0, v[130:131]
	s_mov_b32 m0, s88
	v_lshl_add_u64 v[226:227], s[76:77], 0, v[132:133]
	global_load_lds_dwordx4 v[224:225], off
	v_lshl_add_u64 v[224:225], s[86:87], 0, v[134:135]
	s_add_i32 m0, s88, 0x2000
	s_nop 0
	global_load_lds_dwordx4 v[224:225], off
	v_lshl_add_u64 v[224:225], s[76:77], 0, v[128:129]
	s_mov_b32 m0, s3
	s_nop 0
	global_load_lds_dwordx4 v[224:225], off
	s_mov_b32 m0, s6
	s_nop 0
	global_load_lds_dwordx4 v[226:227], off
	ds_read_b128 v[188:191], v157 offset:16384
	ds_read_b128 v[192:195], v157 offset:17408
	ds_read_b128 v[196:199], v157 offset:18432
	ds_read_b128 v[200:203], v157 offset:19456
	ds_read_b128 v[204:207], v157 offset:20480
	ds_read_b128 v[208:211], v157 offset:21504
	ds_read_b128 v[212:215], v157 offset:22528
	ds_read_b128 v[216:219], v157 offset:23552
	s_waitcnt vmcnt(8)
	s_waitcnt lgkmcnt(0)
	s_barrier
	s_setprio 1
	s_waitcnt lgkmcnt(0)
	v_mfma_f32_16x16x32_bf16 v[60:63], v[146:149], v[188:191], v[60:63]
	v_mfma_f32_16x16x32_bf16 v[56:59], v[164:167], v[188:191], v[56:59]
	v_mfma_f32_16x16x32_bf16 v[44:47], v[146:149], v[196:199], v[44:47]
	v_mfma_f32_16x16x32_bf16 v[40:43], v[164:167], v[196:199], v[40:43]
	v_mfma_f32_16x16x32_bf16 v[28:31], v[146:149], v[204:207], v[28:31]
	v_mfma_f32_16x16x32_bf16 v[24:27], v[164:167], v[204:207], v[24:27]
	v_mfma_f32_16x16x32_bf16 v[12:15], v[146:149], v[212:215], v[12:15]
	v_mfma_f32_16x16x32_bf16 v[8:11], v[164:167], v[212:215], v[8:11]
	v_mfma_f32_16x16x32_bf16 v[60:63], v[160:163], v[192:195], v[60:63]
	v_mfma_f32_16x16x32_bf16 v[56:59], v[168:171], v[192:195], v[56:59]
	v_mfma_f32_16x16x32_bf16 v[44:47], v[160:163], v[200:203], v[44:47]
	v_mfma_f32_16x16x32_bf16 v[40:43], v[168:171], v[200:203], v[40:43]
	v_mfma_f32_16x16x32_bf16 v[28:31], v[160:163], v[208:211], v[28:31]
	v_mfma_f32_16x16x32_bf16 v[24:27], v[168:171], v[208:211], v[24:27]
	v_mfma_f32_16x16x32_bf16 v[12:15], v[160:163], v[216:219], v[12:15]
	v_mfma_f32_16x16x32_bf16 v[8:11], v[168:171], v[216:219], v[8:11]
	v_mfma_f32_16x16x32_bf16 v[52:55], v[172:175], v[188:191], v[52:55]
	v_mfma_f32_16x16x32_bf16 v[48:51], v[180:183], v[188:191], v[48:51]
	v_mfma_f32_16x16x32_bf16 v[36:39], v[172:175], v[196:199], v[36:39]
	v_mfma_f32_16x16x32_bf16 v[32:35], v[180:183], v[196:199], v[32:35]
	v_mfma_f32_16x16x32_bf16 v[20:23], v[172:175], v[204:207], v[20:23]
	v_mfma_f32_16x16x32_bf16 v[16:19], v[180:183], v[204:207], v[16:19]
	v_mfma_f32_16x16x32_bf16 v[4:7], v[172:175], v[212:215], v[4:7]
	v_mfma_f32_16x16x32_bf16 v[0:3], v[180:183], v[212:215], v[0:3]
	v_mfma_f32_16x16x32_bf16 v[52:55], v[176:179], v[192:195], v[52:55]
	v_mfma_f32_16x16x32_bf16 v[48:51], v[184:187], v[192:195], v[48:51]
	v_mfma_f32_16x16x32_bf16 v[36:39], v[176:179], v[200:203], v[36:39]
	v_mfma_f32_16x16x32_bf16 v[32:35], v[184:187], v[200:203], v[32:35]
	v_mfma_f32_16x16x32_bf16 v[20:23], v[176:179], v[208:211], v[20:23]
	v_mfma_f32_16x16x32_bf16 v[16:19], v[184:187], v[208:211], v[16:19]
	v_mfma_f32_16x16x32_bf16 v[4:7], v[176:179], v[216:219], v[4:7]
	v_mfma_f32_16x16x32_bf16 v[0:3], v[184:187], v[216:219], v[0:3]
	s_setprio 0
	s_barrier
	s_add_i32 s86, 0, 0x18000
	v_add_u32_e32 v159, s86, v151
	s_add_i32 s87, 0, 0x1c000
	ds_read_b128 v[146:149], v159
	ds_read_b128 v[160:163], v159 offset:1024
	ds_read_b128 v[164:167], v159 offset:2048
	ds_read_b128 v[168:171], v159 offset:3072
	v_add_u32_e32 v159, s87, v151
	s_add_u32 s76, s76, 0x80000
	s_addc_u32 s77, s77, 0
	s_mov_b32 m0, s7
	v_lshl_add_u64 v[228:229], s[76:77], 0, v[128:129]
	global_load_lds_dwordx4 v[228:229], off
	v_lshl_add_u64 v[228:229], s[76:77], 0, v[132:133]
	s_mov_b32 m0, s29
	s_nop 0
	global_load_lds_dwordx4 v[228:229], off
	ds_read_b128 v[172:175], v159
	ds_read_b128 v[176:179], v159 offset:1024
	ds_read_b128 v[180:183], v159 offset:2048
	ds_read_b128 v[184:187], v159 offset:3072
	ds_read_b128 v[188:191], v157 offset:32768
	ds_read_b128 v[192:195], v157 offset:33792
	ds_read_b128 v[196:199], v157 offset:34816
	ds_read_b128 v[200:203], v157 offset:35840
	ds_read_b128 v[204:207], v157 offset:36864
	ds_read_b128 v[208:211], v157 offset:37888
	ds_read_b128 v[212:215], v157 offset:38912
	ds_read_b128 v[216:219], v157 offset:39936
	s_waitcnt vmcnt(8)
	s_waitcnt lgkmcnt(0)
	s_barrier
	s_setprio 1
	s_waitcnt lgkmcnt(0)
	v_mfma_f32_16x16x32_bf16 v[124:127], v[146:149], v[188:191], v[124:127]
	v_mfma_f32_16x16x32_bf16 v[120:123], v[164:167], v[188:191], v[120:123]
	v_mfma_f32_16x16x32_bf16 v[108:111], v[146:149], v[196:199], v[108:111]
	v_mfma_f32_16x16x32_bf16 v[104:107], v[164:167], v[196:199], v[104:107]
	v_mfma_f32_16x16x32_bf16 v[92:95], v[146:149], v[204:207], v[92:95]
	v_mfma_f32_16x16x32_bf16 v[88:91], v[164:167], v[204:207], v[88:91]
	v_mfma_f32_16x16x32_bf16 v[76:79], v[146:149], v[212:215], v[76:79]
	v_mfma_f32_16x16x32_bf16 v[72:75], v[164:167], v[212:215], v[72:75]
	v_mfma_f32_16x16x32_bf16 v[124:127], v[160:163], v[192:195], v[124:127]
	v_mfma_f32_16x16x32_bf16 v[120:123], v[168:171], v[192:195], v[120:123]
	v_mfma_f32_16x16x32_bf16 v[108:111], v[160:163], v[200:203], v[108:111]
	v_mfma_f32_16x16x32_bf16 v[104:107], v[168:171], v[200:203], v[104:107]
	v_mfma_f32_16x16x32_bf16 v[92:95], v[160:163], v[208:211], v[92:95]
	v_mfma_f32_16x16x32_bf16 v[88:91], v[168:171], v[208:211], v[88:91]
	v_mfma_f32_16x16x32_bf16 v[76:79], v[160:163], v[216:219], v[76:79]
	v_mfma_f32_16x16x32_bf16 v[72:75], v[168:171], v[216:219], v[72:75]
	v_mfma_f32_16x16x32_bf16 v[116:119], v[172:175], v[188:191], v[116:119]
	v_mfma_f32_16x16x32_bf16 v[112:115], v[180:183], v[188:191], v[112:115]
	v_mfma_f32_16x16x32_bf16 v[100:103], v[172:175], v[196:199], v[100:103]
	v_mfma_f32_16x16x32_bf16 v[96:99], v[180:183], v[196:199], v[96:99]
	v_mfma_f32_16x16x32_bf16 v[84:87], v[172:175], v[204:207], v[84:87]
	v_mfma_f32_16x16x32_bf16 v[80:83], v[180:183], v[204:207], v[80:83]
	v_mfma_f32_16x16x32_bf16 v[68:71], v[172:175], v[212:215], v[68:71]
	v_mfma_f32_16x16x32_bf16 v[64:67], v[180:183], v[212:215], v[64:67]
	v_mfma_f32_16x16x32_bf16 v[116:119], v[176:179], v[192:195], v[116:119]
	v_mfma_f32_16x16x32_bf16 v[112:115], v[184:187], v[192:195], v[112:115]
	v_mfma_f32_16x16x32_bf16 v[100:103], v[176:179], v[200:203], v[100:103]
	v_mfma_f32_16x16x32_bf16 v[96:99], v[184:187], v[200:203], v[96:99]
	v_mfma_f32_16x16x32_bf16 v[84:87], v[176:179], v[208:211], v[84:87]
	v_mfma_f32_16x16x32_bf16 v[80:83], v[184:187], v[208:211], v[80:83]
	v_mfma_f32_16x16x32_bf16 v[68:71], v[176:179], v[216:219], v[68:71]
	v_mfma_f32_16x16x32_bf16 v[64:67], v[184:187], v[216:219], v[64:67]
	s_setprio 0
	s_barrier
	s_add_i32 s76, s86, s94
	v_lshl_add_u64 v[220:221], v[220:221], 0, s[18:19]
	s_mov_b32 m0, s76
	s_nop 0
	global_load_lds_dwordx4 v[220:221], off
	s_add_i32 m0, s76, 0x2000
	s_add_u32 s74, s74, 0x80080
	v_lshl_add_u64 v[220:221], v[222:223], 0, s[18:19]
	s_addc_u32 s75, s75, 0
	s_add_i32 s76, s87, s94
	global_load_lds_dwordx4 v[220:221], off
	v_lshl_add_u64 v[220:221], s[74:75], 0, v[130:131]
	s_mov_b32 m0, s76
	s_nop 0
	global_load_lds_dwordx4 v[220:221], off
	v_lshl_add_u64 v[220:221], s[74:75], 0, v[134:135]
	s_add_i32 m0, s76, 0x2000
	s_nop 0
	global_load_lds_dwordx4 v[220:221], off
	v_lshl_add_u64 v[220:221], v[224:225], 0, s[18:19]
	s_mov_b32 m0, s34
	s_nop 0
	global_load_lds_dwordx4 v[220:221], off
	v_lshl_add_u64 v[220:221], v[226:227], 0, s[18:19]
	s_mov_b32 m0, s35
	s_nop 0
	global_load_lds_dwordx4 v[220:221], off
	ds_read_b128 v[188:191], v157 offset:49152
	ds_read_b128 v[192:195], v157 offset:50176
	ds_read_b128 v[196:199], v157 offset:51200
	ds_read_b128 v[200:203], v157 offset:52224
	ds_read_b128 v[204:207], v157 offset:53248
	ds_read_b128 v[208:211], v157 offset:54272
	ds_read_b128 v[212:215], v157 offset:55296
	ds_read_b128 v[216:219], v157 offset:56320
	s_waitcnt vmcnt(8)
	s_waitcnt lgkmcnt(0)
	s_barrier
	s_setprio 1
	s_waitcnt lgkmcnt(0)
	v_mfma_f32_16x16x32_bf16 v[60:63], v[146:149], v[188:191], v[60:63]
	v_mfma_f32_16x16x32_bf16 v[56:59], v[164:167], v[188:191], v[56:59]
	v_mfma_f32_16x16x32_bf16 v[44:47], v[146:149], v[196:199], v[44:47]
	v_mfma_f32_16x16x32_bf16 v[40:43], v[164:167], v[196:199], v[40:43]
	v_mfma_f32_16x16x32_bf16 v[28:31], v[146:149], v[204:207], v[28:31]
	v_mfma_f32_16x16x32_bf16 v[24:27], v[164:167], v[204:207], v[24:27]
	v_mfma_f32_16x16x32_bf16 v[12:15], v[146:149], v[212:215], v[12:15]
	v_mfma_f32_16x16x32_bf16 v[8:11], v[164:167], v[212:215], v[8:11]
	v_mfma_f32_16x16x32_bf16 v[60:63], v[160:163], v[192:195], v[60:63]
	v_mfma_f32_16x16x32_bf16 v[56:59], v[168:171], v[192:195], v[56:59]
	v_mfma_f32_16x16x32_bf16 v[44:47], v[160:163], v[200:203], v[44:47]
	v_mfma_f32_16x16x32_bf16 v[40:43], v[168:171], v[200:203], v[40:43]
	v_mfma_f32_16x16x32_bf16 v[28:31], v[160:163], v[208:211], v[28:31]
	v_mfma_f32_16x16x32_bf16 v[24:27], v[168:171], v[208:211], v[24:27]
	v_mfma_f32_16x16x32_bf16 v[12:15], v[160:163], v[216:219], v[12:15]
	v_mfma_f32_16x16x32_bf16 v[8:11], v[168:171], v[216:219], v[8:11]
	v_mfma_f32_16x16x32_bf16 v[52:55], v[172:175], v[188:191], v[52:55]
	v_mfma_f32_16x16x32_bf16 v[48:51], v[180:183], v[188:191], v[48:51]
	v_mfma_f32_16x16x32_bf16 v[36:39], v[172:175], v[196:199], v[36:39]
	v_mfma_f32_16x16x32_bf16 v[32:35], v[180:183], v[196:199], v[32:35]
	v_mfma_f32_16x16x32_bf16 v[20:23], v[172:175], v[204:207], v[20:23]
	v_mfma_f32_16x16x32_bf16 v[16:19], v[180:183], v[204:207], v[16:19]
	v_mfma_f32_16x16x32_bf16 v[4:7], v[172:175], v[212:215], v[4:7]
	v_mfma_f32_16x16x32_bf16 v[0:3], v[180:183], v[212:215], v[0:3]
	v_mfma_f32_16x16x32_bf16 v[52:55], v[176:179], v[192:195], v[52:55]
	v_mfma_f32_16x16x32_bf16 v[48:51], v[184:187], v[192:195], v[48:51]
	v_mfma_f32_16x16x32_bf16 v[36:39], v[176:179], v[200:203], v[36:39]
	v_mfma_f32_16x16x32_bf16 v[32:35], v[184:187], v[200:203], v[32:35]
	v_mfma_f32_16x16x32_bf16 v[20:23], v[176:179], v[208:211], v[20:23]
	v_mfma_f32_16x16x32_bf16 v[16:19], v[184:187], v[208:211], v[16:19]
	v_mfma_f32_16x16x32_bf16 v[4:7], v[176:179], v[216:219], v[4:7]
	v_mfma_f32_16x16x32_bf16 v[0:3], v[184:187], v[216:219], v[0:3]
	s_setprio 0
	s_barrier
	s_add_i32 s85, s85, 2
	s_add_u32 s72, s72, 0x100
	s_addc_u32 s73, s73, 0
	s_add_u32 s83, s83, 0x100
	s_addc_u32 s84, s84, 0
	s_cmp_gt_u32 s85, 29
	s_cbranch_scc0 .LBB0_849
	s_and_b64 vcc, exec, s[20:21]
	s_cbranch_vccz .LBB0_852
	s_barrier

.LBB0_946:
	s_add_u32 s18, s14, s16
	s_addc_u32 s19, s15, s17
	s_add_u32 s18, s18, 0x7498100
	s_addc_u32 s19, s19, 0
	s_add_u32 s20, s24, s16
	s_addc_u32 s21, s25, s17
	s_add_u32 s69, s20, 0x1308100
	s_addc_u32 s70, s21, 0
	s_cmpk_eq_i32 s16, 0xf00
	s_cselect_b32 s21, s11, s19
	s_cselect_b32 s20, s10, s18
	s_cselect_b32 s19, s9, s70
	s_cselect_b32 s18, s8, s69
	s_mov_b32 m0, s46
	v_lshl_add_u64 v[212:213], v[136:137], 0, s[16:17]
	global_load_lds_dwordx4 v[212:213], off
	v_lshl_add_u64 v[212:213], v[138:139], 0, s[16:17]
	s_mov_b32 m0, s56
	s_nop 0
	global_load_lds_dwordx4 v[212:213], off
	ds_read_b128 v[148:151], v143
	ds_read_b128 v[152:155], v143 offset:1024
	ds_read_b128 v[156:159], v143 offset:2048
	ds_read_b128 v[160:163], v143 offset:3072
	ds_read_b128 v[164:167], v144
	ds_read_b128 v[168:171], v144 offset:1024
	ds_read_b128 v[172:175], v144 offset:2048
	ds_read_b128 v[176:179], v144 offset:3072
	ds_read_b128 v[180:183], v145
	ds_read_b128 v[184:187], v145 offset:1024
	ds_read_b128 v[188:191], v145 offset:2048
	ds_read_b128 v[192:195], v145 offset:3072
	ds_read_b128 v[196:199], v145 offset:4096
	ds_read_b128 v[200:203], v145 offset:5120
	ds_read_b128 v[204:207], v145 offset:6144
	ds_read_b128 v[208:211], v145 offset:7168
	s_waitcnt vmcnt(8)
	s_waitcnt lgkmcnt(0)
	s_barrier
	s_setprio 1
	s_waitcnt lgkmcnt(0)
	v_mfma_f32_16x16x32_bf16 v[124:127], v[148:151], v[180:183], v[124:127]
	v_mfma_f32_16x16x32_bf16 v[120:123], v[156:159], v[180:183], v[120:123]
	v_mfma_f32_16x16x32_bf16 v[108:111], v[148:151], v[188:191], v[108:111]
	v_mfma_f32_16x16x32_bf16 v[104:107], v[156:159], v[188:191], v[104:107]
	v_mfma_f32_16x16x32_bf16 v[92:95], v[148:151], v[196:199], v[92:95]
	v_mfma_f32_16x16x32_bf16 v[88:91], v[156:159], v[196:199], v[88:91]
	v_mfma_f32_16x16x32_bf16 v[76:79], v[148:151], v[204:207], v[76:79]
	v_mfma_f32_16x16x32_bf16 v[72:75], v[156:159], v[204:207], v[72:75]
	v_mfma_f32_16x16x32_bf16 v[124:127], v[152:155], v[184:187], v[124:127]
	v_mfma_f32_16x16x32_bf16 v[120:123], v[160:163], v[184:187], v[120:123]
	v_mfma_f32_16x16x32_bf16 v[108:111], v[152:155], v[192:195], v[108:111]
	v_mfma_f32_16x16x32_bf16 v[104:107], v[160:163], v[192:195], v[104:107]
	v_mfma_f32_16x16x32_bf16 v[92:95], v[152:155], v[200:203], v[92:95]
	v_mfma_f32_16x16x32_bf16 v[88:91], v[160:163], v[200:203], v[88:91]
	v_mfma_f32_16x16x32_bf16 v[76:79], v[152:155], v[208:211], v[76:79]
	v_mfma_f32_16x16x32_bf16 v[72:75], v[160:163], v[208:211], v[72:75]
	v_mfma_f32_16x16x32_bf16 v[116:119], v[164:167], v[180:183], v[116:119]
	v_mfma_f32_16x16x32_bf16 v[112:115], v[172:175], v[180:183], v[112:115]
	v_mfma_f32_16x16x32_bf16 v[100:103], v[164:167], v[188:191], v[100:103]
	v_mfma_f32_16x16x32_bf16 v[96:99], v[172:175], v[188:191], v[96:99]
	v_mfma_f32_16x16x32_bf16 v[84:87], v[164:167], v[196:199], v[84:87]
	v_mfma_f32_16x16x32_bf16 v[80:83], v[172:175], v[196:199], v[80:83]
	v_mfma_f32_16x16x32_bf16 v[68:71], v[164:167], v[204:207], v[68:71]
	v_mfma_f32_16x16x32_bf16 v[64:67], v[172:175], v[204:207], v[64:67]
	v_mfma_f32_16x16x32_bf16 v[116:119], v[168:171], v[184:187], v[116:119]
	v_mfma_f32_16x16x32_bf16 v[112:115], v[176:179], v[184:187], v[112:115]
	v_mfma_f32_16x16x32_bf16 v[100:103], v[168:171], v[192:195], v[100:103]
	v_mfma_f32_16x16x32_bf16 v[96:99], v[176:179], v[192:195], v[96:99]
	v_mfma_f32_16x16x32_bf16 v[84:87], v[168:171], v[200:203], v[84:87]
	v_mfma_f32_16x16x32_bf16 v[80:83], v[176:179], v[200:203], v[80:83]
	v_mfma_f32_16x16x32_bf16 v[68:71], v[168:171], v[208:211], v[68:71]
	v_mfma_f32_16x16x32_bf16 v[64:67], v[176:179], v[208:211], v[64:67]
	s_setprio 0
	s_barrier
	s_mov_b32 m0, s57
	v_lshl_add_u64 v[212:213], s[18:19], 0, v[132:133]
	s_add_u32 s70, s18, 0x80000
	global_load_lds_dwordx4 v[212:213], off
	v_lshl_add_u64 v[214:215], s[18:19], 0, v[128:129]
	s_mov_b32 m0, s62
	s_addc_u32 s71, s19, 0
	global_load_lds_dwordx4 v[214:215], off
	v_lshl_add_u64 v[216:217], s[70:71], 0, v[132:133]
	s_mov_b32 m0, s63
	v_lshl_add_u64 v[218:219], s[20:21], 0, v[130:131]
	global_load_lds_dwordx4 v[216:217], off
	v_lshl_add_u64 v[216:217], s[70:71], 0, v[128:129]
	s_mov_b32 m0, s64
	s_nop 0
	global_load_lds_dwordx4 v[216:217], off
	v_lshl_add_u64 v[216:217], s[20:21], 0, v[134:135]
	s_mov_b32 m0, s3
	s_nop 0
	global_load_lds_dwordx4 v[216:217], off
	s_mov_b32 m0, s6
	s_nop 0
	global_load_lds_dwordx4 v[218:219], off
	ds_read_b128 v[180:183], v145 offset:16384
	ds_read_b128 v[184:187], v145 offset:17408
	ds_read_b128 v[188:191], v145 offset:18432
	ds_read_b128 v[192:195], v145 offset:19456
	ds_read_b128 v[196:199], v145 offset:20480
	ds_read_b128 v[200:203], v145 offset:21504
	ds_read_b128 v[204:207], v145 offset:22528
	ds_read_b128 v[208:211], v145 offset:23552
	s_waitcnt vmcnt(8)
	s_waitcnt lgkmcnt(0)
	s_barrier
	s_setprio 1
	s_waitcnt lgkmcnt(0)
	v_mfma_f32_16x16x32_bf16 v[60:63], v[148:151], v[180:183], v[60:63]
	v_mfma_f32_16x16x32_bf16 v[56:59], v[156:159], v[180:183], v[56:59]
	v_mfma_f32_16x16x32_bf16 v[44:47], v[148:151], v[188:191], v[44:47]
	v_mfma_f32_16x16x32_bf16 v[40:43], v[156:159], v[188:191], v[40:43]
	v_mfma_f32_16x16x32_bf16 v[28:31], v[148:151], v[196:199], v[28:31]
	v_mfma_f32_16x16x32_bf16 v[24:27], v[156:159], v[196:199], v[24:27]
	v_mfma_f32_16x16x32_bf16 v[12:15], v[148:151], v[204:207], v[12:15]
	v_mfma_f32_16x16x32_bf16 v[8:11], v[156:159], v[204:207], v[8:11]
	v_mfma_f32_16x16x32_bf16 v[60:63], v[152:155], v[184:187], v[60:63]
	v_mfma_f32_16x16x32_bf16 v[56:59], v[160:163], v[184:187], v[56:59]
	v_mfma_f32_16x16x32_bf16 v[44:47], v[152:155], v[192:195], v[44:47]
	v_mfma_f32_16x16x32_bf16 v[40:43], v[160:163], v[192:195], v[40:43]
	v_mfma_f32_16x16x32_bf16 v[28:31], v[152:155], v[200:203], v[28:31]
	v_mfma_f32_16x16x32_bf16 v[24:27], v[160:163], v[200:203], v[24:27]
	v_mfma_f32_16x16x32_bf16 v[12:15], v[152:155], v[208:211], v[12:15]
	v_mfma_f32_16x16x32_bf16 v[8:11], v[160:163], v[208:211], v[8:11]
	v_mfma_f32_16x16x32_bf16 v[52:55], v[164:167], v[180:183], v[52:55]
	v_mfma_f32_16x16x32_bf16 v[48:51], v[172:175], v[180:183], v[48:51]
	v_mfma_f32_16x16x32_bf16 v[36:39], v[164:167], v[188:191], v[36:39]
	v_mfma_f32_16x16x32_bf16 v[32:35], v[172:175], v[188:191], v[32:35]
	v_mfma_f32_16x16x32_bf16 v[20:23], v[164:167], v[196:199], v[20:23]
	v_mfma_f32_16x16x32_bf16 v[16:19], v[172:175], v[196:199], v[16:19]
	v_mfma_f32_16x16x32_bf16 v[4:7], v[164:167], v[204:207], v[4:7]
	v_mfma_f32_16x16x32_bf16 v[0:3], v[172:175], v[204:207], v[0:3]
	v_mfma_f32_16x16x32_bf16 v[52:55], v[168:171], v[184:187], v[52:55]
	v_mfma_f32_16x16x32_bf16 v[48:51], v[176:179], v[184:187], v[48:51]
	v_mfma_f32_16x16x32_bf16 v[36:39], v[168:171], v[192:195], v[36:39]
	v_mfma_f32_16x16x32_bf16 v[32:35], v[176:179], v[192:195], v[32:35]
	v_mfma_f32_16x16x32_bf16 v[20:23], v[168:171], v[200:203], v[20:23]
	v_mfma_f32_16x16x32_bf16 v[16:19], v[176:179], v[200:203], v[16:19]
	v_mfma_f32_16x16x32_bf16 v[4:7], v[168:171], v[208:211], v[4:7]
	v_mfma_f32_16x16x32_bf16 v[0:3], v[176:179], v[208:211], v[0:3]
	s_setprio 0
	s_barrier
	s_add_u32 s20, s20, 0x80000
	s_addc_u32 s21, s21, 0
	s_mov_b32 m0, s7
	v_lshl_add_u64 v[220:221], s[20:21], 0, v[134:135]
	global_load_lds_dwordx4 v[220:221], off
	v_lshl_add_u64 v[220:221], s[20:21], 0, v[130:131]
	s_mov_b32 m0, s29
	s_nop 0
	global_load_lds_dwordx4 v[220:221], off
	ds_read_b128 v[148:151], v146
	ds_read_b128 v[152:155], v146 offset:1024
	ds_read_b128 v[156:159], v146 offset:2048
	ds_read_b128 v[160:163], v146 offset:3072
	ds_read_b128 v[164:167], v147
	ds_read_b128 v[168:171], v147 offset:1024
	ds_read_b128 v[172:175], v147 offset:2048
	ds_read_b128 v[176:179], v147 offset:3072
	ds_read_b128 v[180:183], v145 offset:32768
	ds_read_b128 v[184:187], v145 offset:33792
	ds_read_b128 v[188:191], v145 offset:34816
	ds_read_b128 v[192:195], v145 offset:35840
	ds_read_b128 v[196:199], v145 offset:36864
	ds_read_b128 v[200:203], v145 offset:37888
	ds_read_b128 v[204:207], v145 offset:38912
	ds_read_b128 v[208:211], v145 offset:39936
	s_waitcnt vmcnt(8)
	s_waitcnt lgkmcnt(0)
	s_barrier
	s_setprio 1
	s_waitcnt lgkmcnt(0)
	v_mfma_f32_16x16x32_bf16 v[124:127], v[148:151], v[180:183], v[124:127]
	v_mfma_f32_16x16x32_bf16 v[120:123], v[156:159], v[180:183], v[120:123]
	v_mfma_f32_16x16x32_bf16 v[108:111], v[148:151], v[188:191], v[108:111]
	v_mfma_f32_16x16x32_bf16 v[104:107], v[156:159], v[188:191], v[104:107]
	v_mfma_f32_16x16x32_bf16 v[92:95], v[148:151], v[196:199], v[92:95]
	v_mfma_f32_16x16x32_bf16 v[88:91], v[156:159], v[196:199], v[88:91]
	v_mfma_f32_16x16x32_bf16 v[76:79], v[148:151], v[204:207], v[76:79]
	v_mfma_f32_16x16x32_bf16 v[72:75], v[156:159], v[204:207], v[72:75]
	v_mfma_f32_16x16x32_bf16 v[124:127], v[152:155], v[184:187], v[124:127]
	v_mfma_f32_16x16x32_bf16 v[120:123], v[160:163], v[184:187], v[120:123]
	v_mfma_f32_16x16x32_bf16 v[108:111], v[152:155], v[192:195], v[108:111]
	v_mfma_f32_16x16x32_bf16 v[104:107], v[160:163], v[192:195], v[104:107]
	v_mfma_f32_16x16x32_bf16 v[92:95], v[152:155], v[200:203], v[92:95]
	v_mfma_f32_16x16x32_bf16 v[88:91], v[160:163], v[200:203], v[88:91]
	v_mfma_f32_16x16x32_bf16 v[76:79], v[152:155], v[208:211], v[76:79]
	v_mfma_f32_16x16x32_bf16 v[72:75], v[160:163], v[208:211], v[72:75]
	v_mfma_f32_16x16x32_bf16 v[116:119], v[164:167], v[180:183], v[116:119]
	v_mfma_f32_16x16x32_bf16 v[112:115], v[172:175], v[180:183], v[112:115]
	v_mfma_f32_16x16x32_bf16 v[100:103], v[164:167], v[188:191], v[100:103]
	v_mfma_f32_16x16x32_bf16 v[96:99], v[172:175], v[188:191], v[96:99]
	v_mfma_f32_16x16x32_bf16 v[84:87], v[164:167], v[196:199], v[84:87]
	v_mfma_f32_16x16x32_bf16 v[80:83], v[172:175], v[196:199], v[80:83]
	v_mfma_f32_16x16x32_bf16 v[68:71], v[164:167], v[204:207], v[68:71]
	v_mfma_f32_16x16x32_bf16 v[64:67], v[172:175], v[204:207], v[64:67]
	v_mfma_f32_16x16x32_bf16 v[116:119], v[168:171], v[184:187], v[116:119]
	v_mfma_f32_16x16x32_bf16 v[112:115], v[176:179], v[184:187], v[112:115]
	v_mfma_f32_16x16x32_bf16 v[100:103], v[168:171], v[192:195], v[100:103]
	v_mfma_f32_16x16x32_bf16 v[96:99], v[176:179], v[192:195], v[96:99]
	v_mfma_f32_16x16x32_bf16 v[84:87], v[168:171], v[200:203], v[84:87]
	v_mfma_f32_16x16x32_bf16 v[80:83], v[176:179], v[200:203], v[80:83]
	v_mfma_f32_16x16x32_bf16 v[68:71], v[168:171], v[208:211], v[68:71]
	v_mfma_f32_16x16x32_bf16 v[64:67], v[176:179], v[208:211], v[64:67]
	s_setprio 0
	s_barrier
	s_mov_b32 m0, s65
	v_lshl_add_u64 v[212:213], v[212:213], 0, s[12:13]
	s_add_u32 s18, s18, 0x80080
	global_load_lds_dwordx4 v[212:213], off
	v_lshl_add_u64 v[212:213], v[214:215], 0, s[12:13]
	s_mov_b32 m0, s66
	s_addc_u32 s19, s19, 0
	global_load_lds_dwordx4 v[212:213], off
	v_lshl_add_u64 v[212:213], s[18:19], 0, v[132:133]
	s_mov_b32 m0, s67
	s_nop 0
	global_load_lds_dwordx4 v[212:213], off
	v_lshl_add_u64 v[212:213], s[18:19], 0, v[128:129]
	s_mov_b32 m0, s68
	s_nop 0
	global_load_lds_dwordx4 v[212:213], off
	v_lshl_add_u64 v[212:213], v[216:217], 0, s[12:13]
	s_mov_b32 m0, s30
	s_nop 0
	global_load_lds_dwordx4 v[212:213], off
	v_lshl_add_u64 v[212:213], v[218:219], 0, s[12:13]
	s_mov_b32 m0, s34
	s_nop 0
	global_load_lds_dwordx4 v[212:213], off
	ds_read_b128 v[180:183], v145 offset:49152
	ds_read_b128 v[184:187], v145 offset:50176
	ds_read_b128 v[188:191], v145 offset:51200
	ds_read_b128 v[192:195], v145 offset:52224
	ds_read_b128 v[196:199], v145 offset:53248
	ds_read_b128 v[200:203], v145 offset:54272
	ds_read_b128 v[204:207], v145 offset:55296
	ds_read_b128 v[208:211], v145 offset:56320
	s_waitcnt vmcnt(8)
	s_waitcnt lgkmcnt(0)
	s_barrier
	s_setprio 1
	s_waitcnt lgkmcnt(0)
	v_mfma_f32_16x16x32_bf16 v[60:63], v[148:151], v[180:183], v[60:63]
	v_mfma_f32_16x16x32_bf16 v[56:59], v[156:159], v[180:183], v[56:59]
	v_mfma_f32_16x16x32_bf16 v[44:47], v[148:151], v[188:191], v[44:47]
	v_mfma_f32_16x16x32_bf16 v[40:43], v[156:159], v[188:191], v[40:43]
	v_mfma_f32_16x16x32_bf16 v[28:31], v[148:151], v[196:199], v[28:31]
	v_mfma_f32_16x16x32_bf16 v[24:27], v[156:159], v[196:199], v[24:27]
	v_mfma_f32_16x16x32_bf16 v[12:15], v[148:151], v[204:207], v[12:15]
	v_mfma_f32_16x16x32_bf16 v[8:11], v[156:159], v[204:207], v[8:11]
	v_mfma_f32_16x16x32_bf16 v[60:63], v[152:155], v[184:187], v[60:63]
	v_mfma_f32_16x16x32_bf16 v[56:59], v[160:163], v[184:187], v[56:59]
	v_mfma_f32_16x16x32_bf16 v[44:47], v[152:155], v[192:195], v[44:47]
	v_mfma_f32_16x16x32_bf16 v[40:43], v[160:163], v[192:195], v[40:43]
	v_mfma_f32_16x16x32_bf16 v[28:31], v[152:155], v[200:203], v[28:31]
	v_mfma_f32_16x16x32_bf16 v[24:27], v[160:163], v[200:203], v[24:27]
	v_mfma_f32_16x16x32_bf16 v[12:15], v[152:155], v[208:211], v[12:15]
	v_mfma_f32_16x16x32_bf16 v[8:11], v[160:163], v[208:211], v[8:11]
	v_mfma_f32_16x16x32_bf16 v[52:55], v[164:167], v[180:183], v[52:55]
	v_mfma_f32_16x16x32_bf16 v[48:51], v[172:175], v[180:183], v[48:51]
	v_mfma_f32_16x16x32_bf16 v[36:39], v[164:167], v[188:191], v[36:39]
	v_mfma_f32_16x16x32_bf16 v[32:35], v[172:175], v[188:191], v[32:35]
	v_mfma_f32_16x16x32_bf16 v[20:23], v[164:167], v[196:199], v[20:23]
	v_mfma_f32_16x16x32_bf16 v[16:19], v[172:175], v[196:199], v[16:19]
	v_mfma_f32_16x16x32_bf16 v[4:7], v[164:167], v[204:207], v[4:7]
	v_mfma_f32_16x16x32_bf16 v[0:3], v[172:175], v[204:207], v[0:3]
	v_mfma_f32_16x16x32_bf16 v[52:55], v[168:171], v[184:187], v[52:55]
	v_mfma_f32_16x16x32_bf16 v[48:51], v[176:179], v[184:187], v[48:51]
	v_mfma_f32_16x16x32_bf16 v[36:39], v[168:171], v[192:195], v[36:39]
	v_mfma_f32_16x16x32_bf16 v[32:35], v[176:179], v[192:195], v[32:35]
	v_mfma_f32_16x16x32_bf16 v[20:23], v[168:171], v[200:203], v[20:23]
	v_mfma_f32_16x16x32_bf16 v[16:19], v[176:179], v[200:203], v[16:19]
	v_mfma_f32_16x16x32_bf16 v[4:7], v[168:171], v[208:211], v[4:7]
	v_mfma_f32_16x16x32_bf16 v[0:3], v[176:179], v[208:211], v[0:3]
	s_setprio 0
	s_barrier
	s_add_i32 s35, s35, 2
	s_add_u32 s16, s16, 0x100
	s_addc_u32 s17, s17, 0
	s_cmp_gt_u32 s35, 29
	s_cbranch_scc0 .LBB0_946
	s_cmpk_lt_u32 s80, 0x100
	s_cbranch_scc0 .LBB0_949
	s_barrier

.LBB0_1693:
	s_add_u32 s76, s74, 0xfff80080
	s_addc_u32 s77, s75, -1
	s_cmp_eq_u32 s86, 28
	s_cselect_b32 s79, s67, s77
	s_cselect_b32 s78, s73, s76
	s_cselect_b32 s77, s65, s85
	s_cselect_b32 s76, s83, s84
	v_lshl_add_u64 v[212:213], s[74:75], 0, v[132:133]
	s_add_i32 m0, s6, 0xc000
	s_nop 0
	global_load_lds_dwordx4 v[212:213], off
	v_lshl_add_u64 v[212:213], s[74:75], 0, v[134:135]
	s_add_i32 m0, s6, 0xe000
	s_nop 0
	global_load_lds_dwordx4 v[212:213], off
	ds_read_b128 v[140:143], v149
	ds_read_b128 v[152:155], v149 offset:1024
	ds_read_b128 v[156:159], v149 offset:2048
	ds_read_b128 v[160:163], v149 offset:3072
	ds_read_b128 v[164:167], v150
	ds_read_b128 v[168:171], v150 offset:1024
	ds_read_b128 v[172:175], v150 offset:2048
	ds_read_b128 v[176:179], v150 offset:3072
	ds_read_b128 v[180:183], v151
	ds_read_b128 v[184:187], v151 offset:1024
	ds_read_b128 v[188:191], v151 offset:2048
	ds_read_b128 v[192:195], v151 offset:3072
	ds_read_b128 v[196:199], v151 offset:4096
	ds_read_b128 v[200:203], v151 offset:5120
	ds_read_b128 v[204:207], v151 offset:6144
	ds_read_b128 v[208:211], v151 offset:7168
	s_waitcnt vmcnt(8)
	s_waitcnt lgkmcnt(0)
	s_barrier
	s_setprio 1
	s_waitcnt lgkmcnt(0)
	v_mfma_f32_16x16x32_bf16 v[124:127], v[140:143], v[180:183], v[124:127]
	v_mfma_f32_16x16x32_bf16 v[120:123], v[156:159], v[180:183], v[120:123]
	v_mfma_f32_16x16x32_bf16 v[108:111], v[140:143], v[188:191], v[108:111]
	v_mfma_f32_16x16x32_bf16 v[104:107], v[156:159], v[188:191], v[104:107]
	v_mfma_f32_16x16x32_bf16 v[92:95], v[140:143], v[196:199], v[92:95]
	v_mfma_f32_16x16x32_bf16 v[88:91], v[156:159], v[196:199], v[88:91]
	v_mfma_f32_16x16x32_bf16 v[76:79], v[140:143], v[204:207], v[76:79]
	v_mfma_f32_16x16x32_bf16 v[72:75], v[156:159], v[204:207], v[72:75]
	v_mfma_f32_16x16x32_bf16 v[124:127], v[152:155], v[184:187], v[124:127]
	v_mfma_f32_16x16x32_bf16 v[120:123], v[160:163], v[184:187], v[120:123]
	v_mfma_f32_16x16x32_bf16 v[108:111], v[152:155], v[192:195], v[108:111]
	v_mfma_f32_16x16x32_bf16 v[104:107], v[160:163], v[192:195], v[104:107]
	v_mfma_f32_16x16x32_bf16 v[92:95], v[152:155], v[200:203], v[92:95]
	v_mfma_f32_16x16x32_bf16 v[88:91], v[160:163], v[200:203], v[88:91]
	v_mfma_f32_16x16x32_bf16 v[76:79], v[152:155], v[208:211], v[76:79]
	v_mfma_f32_16x16x32_bf16 v[72:75], v[160:163], v[208:211], v[72:75]
	v_mfma_f32_16x16x32_bf16 v[116:119], v[164:167], v[180:183], v[116:119]
	v_mfma_f32_16x16x32_bf16 v[112:115], v[172:175], v[180:183], v[112:115]
	v_mfma_f32_16x16x32_bf16 v[100:103], v[164:167], v[188:191], v[100:103]
	v_mfma_f32_16x16x32_bf16 v[96:99], v[172:175], v[188:191], v[96:99]
	v_mfma_f32_16x16x32_bf16 v[84:87], v[164:167], v[196:199], v[84:87]
	v_mfma_f32_16x16x32_bf16 v[80:83], v[172:175], v[196:199], v[80:83]
	v_mfma_f32_16x16x32_bf16 v[68:71], v[164:167], v[204:207], v[68:71]
	v_mfma_f32_16x16x32_bf16 v[64:67], v[172:175], v[204:207], v[64:67]
	v_mfma_f32_16x16x32_bf16 v[116:119], v[168:171], v[184:187], v[116:119]
	v_mfma_f32_16x16x32_bf16 v[112:115], v[176:179], v[184:187], v[112:115]
	v_mfma_f32_16x16x32_bf16 v[100:103], v[168:171], v[192:195], v[100:103]
	v_mfma_f32_16x16x32_bf16 v[96:99], v[176:179], v[192:195], v[96:99]
	v_mfma_f32_16x16x32_bf16 v[84:87], v[168:171], v[200:203], v[84:87]
	v_mfma_f32_16x16x32_bf16 v[80:83], v[176:179], v[200:203], v[80:83]
	v_mfma_f32_16x16x32_bf16 v[68:71], v[168:171], v[208:211], v[68:71]
	v_mfma_f32_16x16x32_bf16 v[64:67], v[176:179], v[208:211], v[64:67]
	s_setprio 0
	s_barrier
	s_add_i32 s87, s57, s94
	v_lshl_add_u64 v[212:213], s[76:77], 0, v[128:129]
	s_mov_b32 m0, s87
	s_nop 0
	global_load_lds_dwordx4 v[212:213], off
	s_add_i32 m0, s87, 0x2000
	s_add_u32 s88, s76, 0x80000
	v_lshl_add_u64 v[214:215], s[76:77], 0, v[130:131]
	s_addc_u32 s89, s77, 0
	s_add_i32 s87, s81, s94
	global_load_lds_dwordx4 v[214:215], off
	v_lshl_add_u64 v[216:217], s[88:89], 0, v[128:129]
	s_mov_b32 m0, s87
	v_lshl_add_u64 v[218:219], s[78:79], 0, v[130:131]
	global_load_lds_dwordx4 v[216:217], off
	v_lshl_add_u64 v[216:217], s[88:89], 0, v[130:131]
	s_add_i32 m0, s87, 0x2000
	s_nop 0
	global_load_lds_dwordx4 v[216:217], off
	v_lshl_add_u64 v[216:217], s[78:79], 0, v[128:129]
	s_mov_b32 m0, s6
	s_nop 0
	global_load_lds_dwordx4 v[216:217], off
	s_mov_b32 m0, s7
	s_nop 0
	global_load_lds_dwordx4 v[218:219], off
	ds_read_b128 v[180:183], v151 offset:16384
	ds_read_b128 v[184:187], v151 offset:17408
	ds_read_b128 v[188:191], v151 offset:18432
	ds_read_b128 v[192:195], v151 offset:19456
	ds_read_b128 v[196:199], v151 offset:20480
	ds_read_b128 v[200:203], v151 offset:21504
	ds_read_b128 v[204:207], v151 offset:22528
	ds_read_b128 v[208:211], v151 offset:23552
	s_waitcnt vmcnt(8)
	s_waitcnt lgkmcnt(0)
	s_barrier
	s_setprio 1
	s_waitcnt lgkmcnt(0)
	v_mfma_f32_16x16x32_bf16 v[60:63], v[140:143], v[180:183], v[60:63]
	v_mfma_f32_16x16x32_bf16 v[56:59], v[156:159], v[180:183], v[56:59]
	v_mfma_f32_16x16x32_bf16 v[44:47], v[140:143], v[188:191], v[44:47]
	v_mfma_f32_16x16x32_bf16 v[40:43], v[156:159], v[188:191], v[40:43]
	v_mfma_f32_16x16x32_bf16 v[28:31], v[140:143], v[196:199], v[28:31]
	v_mfma_f32_16x16x32_bf16 v[24:27], v[156:159], v[196:199], v[24:27]
	v_mfma_f32_16x16x32_bf16 v[12:15], v[140:143], v[204:207], v[12:15]
	v_mfma_f32_16x16x32_bf16 v[8:11], v[156:159], v[204:207], v[8:11]
	v_mfma_f32_16x16x32_bf16 v[60:63], v[152:155], v[184:187], v[60:63]
	v_mfma_f32_16x16x32_bf16 v[56:59], v[160:163], v[184:187], v[56:59]
	v_mfma_f32_16x16x32_bf16 v[44:47], v[152:155], v[192:195], v[44:47]
	v_mfma_f32_16x16x32_bf16 v[40:43], v[160:163], v[192:195], v[40:43]
	v_mfma_f32_16x16x32_bf16 v[28:31], v[152:155], v[200:203], v[28:31]
	v_mfma_f32_16x16x32_bf16 v[24:27], v[160:163], v[200:203], v[24:27]
	v_mfma_f32_16x16x32_bf16 v[12:15], v[152:155], v[208:211], v[12:15]
	v_mfma_f32_16x16x32_bf16 v[8:11], v[160:163], v[208:211], v[8:11]
	v_mfma_f32_16x16x32_bf16 v[52:55], v[164:167], v[180:183], v[52:55]
	v_mfma_f32_16x16x32_bf16 v[48:51], v[172:175], v[180:183], v[48:51]
	v_mfma_f32_16x16x32_bf16 v[36:39], v[164:167], v[188:191], v[36:39]
	v_mfma_f32_16x16x32_bf16 v[32:35], v[172:175], v[188:191], v[32:35]
	v_mfma_f32_16x16x32_bf16 v[20:23], v[164:167], v[196:199], v[20:23]
	v_mfma_f32_16x16x32_bf16 v[16:19], v[172:175], v[196:199], v[16:19]
	v_mfma_f32_16x16x32_bf16 v[4:7], v[164:167], v[204:207], v[4:7]
	v_mfma_f32_16x16x32_bf16 v[0:3], v[172:175], v[204:207], v[0:3]
	v_mfma_f32_16x16x32_bf16 v[52:55], v[168:171], v[184:187], v[52:55]
	v_mfma_f32_16x16x32_bf16 v[48:51], v[176:179], v[184:187], v[48:51]
	v_mfma_f32_16x16x32_bf16 v[36:39], v[168:171], v[192:195], v[36:39]
	v_mfma_f32_16x16x32_bf16 v[32:35], v[176:179], v[192:195], v[32:35]
	v_mfma_f32_16x16x32_bf16 v[20:23], v[168:171], v[200:203], v[20:23]
	v_mfma_f32_16x16x32_bf16 v[16:19], v[176:179], v[200:203], v[16:19]
	v_mfma_f32_16x16x32_bf16 v[4:7], v[168:171], v[208:211], v[4:7]
	v_mfma_f32_16x16x32_bf16 v[0:3], v[176:179], v[208:211], v[0:3]
	s_setprio 0
	s_barrier
	s_add_i32 s87, 0, 0x18000
	s_add_i32 s88, 0, 0x1c000
	v_add_u32_e32 v160, s87, v145
	v_add_u32_e32 v176, s88, v145
	s_add_u32 s78, s78, 0x80000
	s_addc_u32 s79, s79, 0
	s_mov_b32 m0, s29
	v_lshl_add_u64 v[220:221], s[78:79], 0, v[128:129]
	global_load_lds_dwordx4 v[220:221], off
	v_lshl_add_u64 v[220:221], s[78:79], 0, v[130:131]
	s_mov_b32 m0, s30
	s_nop 0
	global_load_lds_dwordx4 v[220:221], off
	ds_read_b128 v[140:143], v160
	ds_read_b128 v[152:155], v160 offset:1024
	ds_read_b128 v[156:159], v160 offset:2048
	ds_read_b128 v[160:163], v160 offset:3072
	ds_read_b128 v[164:167], v176
	ds_read_b128 v[168:171], v176 offset:1024
	ds_read_b128 v[172:175], v176 offset:2048
	ds_read_b128 v[176:179], v176 offset:3072
	ds_read_b128 v[180:183], v151 offset:32768
	ds_read_b128 v[184:187], v151 offset:33792
	ds_read_b128 v[188:191], v151 offset:34816
	ds_read_b128 v[192:195], v151 offset:35840
	ds_read_b128 v[196:199], v151 offset:36864
	ds_read_b128 v[200:203], v151 offset:37888
	ds_read_b128 v[204:207], v151 offset:38912
	ds_read_b128 v[208:211], v151 offset:39936
	s_waitcnt vmcnt(8)
	s_waitcnt lgkmcnt(0)
	s_barrier
	s_setprio 1
	s_waitcnt lgkmcnt(0)
	v_mfma_f32_16x16x32_bf16 v[124:127], v[140:143], v[180:183], v[124:127]
	v_mfma_f32_16x16x32_bf16 v[120:123], v[156:159], v[180:183], v[120:123]
	v_mfma_f32_16x16x32_bf16 v[108:111], v[140:143], v[188:191], v[108:111]
	v_mfma_f32_16x16x32_bf16 v[104:107], v[156:159], v[188:191], v[104:107]
	v_mfma_f32_16x16x32_bf16 v[92:95], v[140:143], v[196:199], v[92:95]
	v_mfma_f32_16x16x32_bf16 v[88:91], v[156:159], v[196:199], v[88:91]
	v_mfma_f32_16x16x32_bf16 v[76:79], v[140:143], v[204:207], v[76:79]
	v_mfma_f32_16x16x32_bf16 v[72:75], v[156:159], v[204:207], v[72:75]
	v_mfma_f32_16x16x32_bf16 v[124:127], v[152:155], v[184:187], v[124:127]
	v_mfma_f32_16x16x32_bf16 v[120:123], v[160:163], v[184:187], v[120:123]
	v_mfma_f32_16x16x32_bf16 v[108:111], v[152:155], v[192:195], v[108:111]
	v_mfma_f32_16x16x32_bf16 v[104:107], v[160:163], v[192:195], v[104:107]
	v_mfma_f32_16x16x32_bf16 v[92:95], v[152:155], v[200:203], v[92:95]
	v_mfma_f32_16x16x32_bf16 v[88:91], v[160:163], v[200:203], v[88:91]
	v_mfma_f32_16x16x32_bf16 v[76:79], v[152:155], v[208:211], v[76:79]
	v_mfma_f32_16x16x32_bf16 v[72:75], v[160:163], v[208:211], v[72:75]
	v_mfma_f32_16x16x32_bf16 v[116:119], v[164:167], v[180:183], v[116:119]
	v_mfma_f32_16x16x32_bf16 v[112:115], v[172:175], v[180:183], v[112:115]
	v_mfma_f32_16x16x32_bf16 v[100:103], v[164:167], v[188:191], v[100:103]
	v_mfma_f32_16x16x32_bf16 v[96:99], v[172:175], v[188:191], v[96:99]
	v_mfma_f32_16x16x32_bf16 v[84:87], v[164:167], v[196:199], v[84:87]
	v_mfma_f32_16x16x32_bf16 v[80:83], v[172:175], v[196:199], v[80:83]
	v_mfma_f32_16x16x32_bf16 v[68:71], v[164:167], v[204:207], v[68:71]
	v_mfma_f32_16x16x32_bf16 v[64:67], v[172:175], v[204:207], v[64:67]
	v_mfma_f32_16x16x32_bf16 v[116:119], v[168:171], v[184:187], v[116:119]
	v_mfma_f32_16x16x32_bf16 v[112:115], v[176:179], v[184:187], v[112:115]
	v_mfma_f32_16x16x32_bf16 v[100:103], v[168:171], v[192:195], v[100:103]
	v_mfma_f32_16x16x32_bf16 v[96:99], v[176:179], v[192:195], v[96:99]
	v_mfma_f32_16x16x32_bf16 v[84:87], v[168:171], v[200:203], v[84:87]
	v_mfma_f32_16x16x32_bf16 v[80:83], v[176:179], v[200:203], v[80:83]
	v_mfma_f32_16x16x32_bf16 v[68:71], v[168:171], v[208:211], v[68:71]
	v_mfma_f32_16x16x32_bf16 v[64:67], v[176:179], v[208:211], v[64:67]
	s_setprio 0
	s_barrier
	s_add_i32 s78, s87, s94
	v_lshl_add_u64 v[212:213], v[212:213], 0, s[58:59]
	s_mov_b32 m0, s78
	s_nop 0
	global_load_lds_dwordx4 v[212:213], off
	s_add_i32 m0, s78, 0x2000
	s_add_u32 s76, s76, 0x80080
	v_lshl_add_u64 v[212:213], v[214:215], 0, s[58:59]
	s_addc_u32 s77, s77, 0
	s_add_i32 s78, s88, s94
	global_load_lds_dwordx4 v[212:213], off
	v_lshl_add_u64 v[212:213], s[76:77], 0, v[128:129]
	s_mov_b32 m0, s78
	s_nop 0
	global_load_lds_dwordx4 v[212:213], off
	v_lshl_add_u64 v[212:213], s[76:77], 0, v[130:131]
	s_add_i32 m0, s78, 0x2000
	s_nop 0
	global_load_lds_dwordx4 v[212:213], off
	v_lshl_add_u64 v[212:213], v[216:217], 0, s[58:59]
	s_mov_b32 m0, s34
	s_nop 0
	global_load_lds_dwordx4 v[212:213], off
	v_lshl_add_u64 v[212:213], v[218:219], 0, s[58:59]
	s_mov_b32 m0, s35
	s_nop 0
	global_load_lds_dwordx4 v[212:213], off
	ds_read_b128 v[180:183], v151 offset:49152
	ds_read_b128 v[184:187], v151 offset:50176
	ds_read_b128 v[188:191], v151 offset:51200
	ds_read_b128 v[192:195], v151 offset:52224
	ds_read_b128 v[196:199], v151 offset:53248
	ds_read_b128 v[200:203], v151 offset:54272
	ds_read_b128 v[204:207], v151 offset:55296
	ds_read_b128 v[208:211], v151 offset:56320
	s_waitcnt vmcnt(8)
	s_waitcnt lgkmcnt(0)
	s_barrier
	s_setprio 1
	s_waitcnt lgkmcnt(0)
	v_mfma_f32_16x16x32_bf16 v[60:63], v[140:143], v[180:183], v[60:63]
	v_mfma_f32_16x16x32_bf16 v[56:59], v[156:159], v[180:183], v[56:59]
	v_mfma_f32_16x16x32_bf16 v[44:47], v[140:143], v[188:191], v[44:47]
	v_mfma_f32_16x16x32_bf16 v[40:43], v[156:159], v[188:191], v[40:43]
	v_mfma_f32_16x16x32_bf16 v[28:31], v[140:143], v[196:199], v[28:31]
	v_mfma_f32_16x16x32_bf16 v[24:27], v[156:159], v[196:199], v[24:27]
	v_mfma_f32_16x16x32_bf16 v[12:15], v[140:143], v[204:207], v[12:15]
	v_mfma_f32_16x16x32_bf16 v[8:11], v[156:159], v[204:207], v[8:11]
	v_mfma_f32_16x16x32_bf16 v[60:63], v[152:155], v[184:187], v[60:63]
	v_mfma_f32_16x16x32_bf16 v[56:59], v[160:163], v[184:187], v[56:59]
	v_mfma_f32_16x16x32_bf16 v[44:47], v[152:155], v[192:195], v[44:47]
	v_mfma_f32_16x16x32_bf16 v[40:43], v[160:163], v[192:195], v[40:43]
	v_mfma_f32_16x16x32_bf16 v[28:31], v[152:155], v[200:203], v[28:31]
	v_mfma_f32_16x16x32_bf16 v[24:27], v[160:163], v[200:203], v[24:27]
	v_mfma_f32_16x16x32_bf16 v[12:15], v[152:155], v[208:211], v[12:15]
	v_mfma_f32_16x16x32_bf16 v[8:11], v[160:163], v[208:211], v[8:11]
	v_mfma_f32_16x16x32_bf16 v[52:55], v[164:167], v[180:183], v[52:55]
	v_mfma_f32_16x16x32_bf16 v[48:51], v[172:175], v[180:183], v[48:51]
	v_mfma_f32_16x16x32_bf16 v[36:39], v[164:167], v[188:191], v[36:39]
	v_mfma_f32_16x16x32_bf16 v[32:35], v[172:175], v[188:191], v[32:35]
	v_mfma_f32_16x16x32_bf16 v[20:23], v[164:167], v[196:199], v[20:23]
	v_mfma_f32_16x16x32_bf16 v[16:19], v[172:175], v[196:199], v[16:19]
	v_mfma_f32_16x16x32_bf16 v[4:7], v[164:167], v[204:207], v[4:7]
	v_mfma_f32_16x16x32_bf16 v[0:3], v[172:175], v[204:207], v[0:3]
	v_mfma_f32_16x16x32_bf16 v[52:55], v[168:171], v[184:187], v[52:55]
	v_mfma_f32_16x16x32_bf16 v[48:51], v[176:179], v[184:187], v[48:51]
	v_mfma_f32_16x16x32_bf16 v[36:39], v[168:171], v[192:195], v[36:39]
	v_mfma_f32_16x16x32_bf16 v[32:35], v[176:179], v[192:195], v[32:35]
	v_mfma_f32_16x16x32_bf16 v[20:23], v[168:171], v[200:203], v[20:23]
	v_mfma_f32_16x16x32_bf16 v[16:19], v[176:179], v[200:203], v[16:19]
	v_mfma_f32_16x16x32_bf16 v[4:7], v[168:171], v[208:211], v[4:7]
	v_mfma_f32_16x16x32_bf16 v[0:3], v[176:179], v[208:211], v[0:3]
	s_setprio 0
	s_barrier
	s_add_i32 s86, s86, 2
	s_add_u32 s74, s74, 0x100
	s_addc_u32 s75, s75, 0
	s_add_u32 s84, s84, 0x100
	s_addc_u32 s85, s85, 0
	s_cmp_gt_u32 s86, 29
	s_cbranch_scc0 .LBB0_1693
	s_and_b64 vcc, exec, s[60:61]
	s_cbranch_vccz .LBB0_1696
	s_barrier

.LBB0_1785:
	s_add_u32 s60, s72, 0xfff80080
	s_addc_u32 s61, s73, -1
	s_cmp_eq_u32 s78, 28
	s_cselect_b32 s77, s56, s61
	s_cselect_b32 s76, s57, s60
	s_cselect_b32 s75, s23, s71
	s_cselect_b32 s74, s63, s69
	v_lshl_add_u64 v[220:221], s[72:73], 0, v[138:139]
	s_add_i32 m0, s6, 0xc000
	s_nop 0
	global_load_lds_dwordx4 v[220:221], off
	v_lshl_add_u64 v[220:221], s[72:73], 0, v[140:141]
	s_add_i32 m0, s6, 0xe000
	s_nop 0
	global_load_lds_dwordx4 v[220:221], off
	ds_read_b128 v[146:149], v155
	ds_read_b128 v[160:163], v155 offset:1024
	ds_read_b128 v[164:167], v155 offset:2048
	ds_read_b128 v[168:171], v155 offset:3072
	ds_read_b128 v[172:175], v156
	ds_read_b128 v[176:179], v156 offset:1024
	ds_read_b128 v[180:183], v156 offset:2048
	ds_read_b128 v[184:187], v156 offset:3072
	ds_read_b128 v[188:191], v157
	ds_read_b128 v[192:195], v157 offset:1024
	ds_read_b128 v[196:199], v157 offset:2048
	ds_read_b128 v[200:203], v157 offset:3072
	ds_read_b128 v[204:207], v157 offset:4096
	ds_read_b128 v[208:211], v157 offset:5120
	ds_read_b128 v[212:215], v157 offset:6144
	ds_read_b128 v[216:219], v157 offset:7168
	s_waitcnt vmcnt(8)
	s_waitcnt lgkmcnt(0)
	s_barrier
	s_setprio 1
	s_waitcnt lgkmcnt(0)
	v_mfma_f32_16x16x32_bf16 v[124:127], v[146:149], v[188:191], v[124:127]
	v_mfma_f32_16x16x32_bf16 v[120:123], v[164:167], v[188:191], v[120:123]
	v_mfma_f32_16x16x32_bf16 v[108:111], v[146:149], v[196:199], v[108:111]
	v_mfma_f32_16x16x32_bf16 v[104:107], v[164:167], v[196:199], v[104:107]
	v_mfma_f32_16x16x32_bf16 v[92:95], v[146:149], v[204:207], v[92:95]
	v_mfma_f32_16x16x32_bf16 v[88:91], v[164:167], v[204:207], v[88:91]
	v_mfma_f32_16x16x32_bf16 v[76:79], v[146:149], v[212:215], v[76:79]
	v_mfma_f32_16x16x32_bf16 v[72:75], v[164:167], v[212:215], v[72:75]
	v_mfma_f32_16x16x32_bf16 v[124:127], v[160:163], v[192:195], v[124:127]
	v_mfma_f32_16x16x32_bf16 v[120:123], v[168:171], v[192:195], v[120:123]
	v_mfma_f32_16x16x32_bf16 v[108:111], v[160:163], v[200:203], v[108:111]
	v_mfma_f32_16x16x32_bf16 v[104:107], v[168:171], v[200:203], v[104:107]
	v_mfma_f32_16x16x32_bf16 v[92:95], v[160:163], v[208:211], v[92:95]
	v_mfma_f32_16x16x32_bf16 v[88:91], v[168:171], v[208:211], v[88:91]
	v_mfma_f32_16x16x32_bf16 v[76:79], v[160:163], v[216:219], v[76:79]
	v_mfma_f32_16x16x32_bf16 v[72:75], v[168:171], v[216:219], v[72:75]
	v_mfma_f32_16x16x32_bf16 v[116:119], v[172:175], v[188:191], v[116:119]
	v_mfma_f32_16x16x32_bf16 v[112:115], v[180:183], v[188:191], v[112:115]
	v_mfma_f32_16x16x32_bf16 v[100:103], v[172:175], v[196:199], v[100:103]
	v_mfma_f32_16x16x32_bf16 v[96:99], v[180:183], v[196:199], v[96:99]
	v_mfma_f32_16x16x32_bf16 v[84:87], v[172:175], v[204:207], v[84:87]
	v_mfma_f32_16x16x32_bf16 v[80:83], v[180:183], v[204:207], v[80:83]
	v_mfma_f32_16x16x32_bf16 v[68:71], v[172:175], v[212:215], v[68:71]
	v_mfma_f32_16x16x32_bf16 v[64:67], v[180:183], v[212:215], v[64:67]
	v_mfma_f32_16x16x32_bf16 v[116:119], v[176:179], v[192:195], v[116:119]
	v_mfma_f32_16x16x32_bf16 v[112:115], v[184:187], v[192:195], v[112:115]
	v_mfma_f32_16x16x32_bf16 v[100:103], v[176:179], v[200:203], v[100:103]
	v_mfma_f32_16x16x32_bf16 v[96:99], v[184:187], v[200:203], v[96:99]
	v_mfma_f32_16x16x32_bf16 v[84:87], v[176:179], v[208:211], v[84:87]
	v_mfma_f32_16x16x32_bf16 v[80:83], v[184:187], v[208:211], v[80:83]
	v_mfma_f32_16x16x32_bf16 v[68:71], v[176:179], v[216:219], v[68:71]
	v_mfma_f32_16x16x32_bf16 v[64:67], v[184:187], v[216:219], v[64:67]
	s_setprio 0
	s_barrier
	s_add_i32 s60, s35, s94
	v_lshl_add_u64 v[220:221], s[74:75], 0, v[130:131]
	s_mov_b32 m0, s60
	s_nop 0
	global_load_lds_dwordx4 v[220:221], off
	s_add_i32 m0, s60, 0x2000
	s_add_u32 s80, s74, 0x80000
	v_lshl_add_u64 v[222:223], s[74:75], 0, v[134:135]
	s_addc_u32 s81, s75, 0
	s_add_i32 s60, s46, s94
	global_load_lds_dwordx4 v[222:223], off
	v_lshl_add_u64 v[224:225], s[80:81], 0, v[130:131]
	s_mov_b32 m0, s60
	v_lshl_add_u64 v[226:227], s[76:77], 0, v[132:133]
	global_load_lds_dwordx4 v[224:225], off
	v_lshl_add_u64 v[224:225], s[80:81], 0, v[134:135]
	s_add_i32 m0, s60, 0x2000
	s_nop 0
	global_load_lds_dwordx4 v[224:225], off
	v_lshl_add_u64 v[224:225], s[76:77], 0, v[128:129]
	s_mov_b32 m0, s6
	s_nop 0
	global_load_lds_dwordx4 v[224:225], off
	s_mov_b32 m0, s7
	s_nop 0
	global_load_lds_dwordx4 v[226:227], off
	ds_read_b128 v[188:191], v157 offset:16384
	ds_read_b128 v[192:195], v157 offset:17408
	ds_read_b128 v[196:199], v157 offset:18432
	ds_read_b128 v[200:203], v157 offset:19456
	ds_read_b128 v[204:207], v157 offset:20480
	ds_read_b128 v[208:211], v157 offset:21504
	ds_read_b128 v[212:215], v157 offset:22528
	ds_read_b128 v[216:219], v157 offset:23552
	s_waitcnt vmcnt(8)
	s_waitcnt lgkmcnt(0)
	s_barrier
	s_setprio 1
	s_waitcnt lgkmcnt(0)
	v_mfma_f32_16x16x32_bf16 v[60:63], v[146:149], v[188:191], v[60:63]
	v_mfma_f32_16x16x32_bf16 v[56:59], v[164:167], v[188:191], v[56:59]
	v_mfma_f32_16x16x32_bf16 v[44:47], v[146:149], v[196:199], v[44:47]
	v_mfma_f32_16x16x32_bf16 v[40:43], v[164:167], v[196:199], v[40:43]
	v_mfma_f32_16x16x32_bf16 v[28:31], v[146:149], v[204:207], v[28:31]
	v_mfma_f32_16x16x32_bf16 v[24:27], v[164:167], v[204:207], v[24:27]
	v_mfma_f32_16x16x32_bf16 v[12:15], v[146:149], v[212:215], v[12:15]
	v_mfma_f32_16x16x32_bf16 v[8:11], v[164:167], v[212:215], v[8:11]
	v_mfma_f32_16x16x32_bf16 v[60:63], v[160:163], v[192:195], v[60:63]
	v_mfma_f32_16x16x32_bf16 v[56:59], v[168:171], v[192:195], v[56:59]
	v_mfma_f32_16x16x32_bf16 v[44:47], v[160:163], v[200:203], v[44:47]
	v_mfma_f32_16x16x32_bf16 v[40:43], v[168:171], v[200:203], v[40:43]
	v_mfma_f32_16x16x32_bf16 v[28:31], v[160:163], v[208:211], v[28:31]
	v_mfma_f32_16x16x32_bf16 v[24:27], v[168:171], v[208:211], v[24:27]
	v_mfma_f32_16x16x32_bf16 v[12:15], v[160:163], v[216:219], v[12:15]
	v_mfma_f32_16x16x32_bf16 v[8:11], v[168:171], v[216:219], v[8:11]
	v_mfma_f32_16x16x32_bf16 v[52:55], v[172:175], v[188:191], v[52:55]
	v_mfma_f32_16x16x32_bf16 v[48:51], v[180:183], v[188:191], v[48:51]
	v_mfma_f32_16x16x32_bf16 v[36:39], v[172:175], v[196:199], v[36:39]
	v_mfma_f32_16x16x32_bf16 v[32:35], v[180:183], v[196:199], v[32:35]
	v_mfma_f32_16x16x32_bf16 v[20:23], v[172:175], v[204:207], v[20:23]
	v_mfma_f32_16x16x32_bf16 v[16:19], v[180:183], v[204:207], v[16:19]
	v_mfma_f32_16x16x32_bf16 v[4:7], v[172:175], v[212:215], v[4:7]
	v_mfma_f32_16x16x32_bf16 v[0:3], v[180:183], v[212:215], v[0:3]
	v_mfma_f32_16x16x32_bf16 v[52:55], v[176:179], v[192:195], v[52:55]
	v_mfma_f32_16x16x32_bf16 v[48:51], v[184:187], v[192:195], v[48:51]
	v_mfma_f32_16x16x32_bf16 v[36:39], v[176:179], v[200:203], v[36:39]
	v_mfma_f32_16x16x32_bf16 v[32:35], v[184:187], v[200:203], v[32:35]
	v_mfma_f32_16x16x32_bf16 v[20:23], v[176:179], v[208:211], v[20:23]
	v_mfma_f32_16x16x32_bf16 v[16:19], v[184:187], v[208:211], v[16:19]
	v_mfma_f32_16x16x32_bf16 v[4:7], v[176:179], v[216:219], v[4:7]
	v_mfma_f32_16x16x32_bf16 v[0:3], v[184:187], v[216:219], v[0:3]
	s_setprio 0
	s_barrier
	s_add_i32 s60, 0, 0x18000
	v_add_u32_e32 v159, s60, v151
	s_add_i32 s61, 0, 0x1c000
	ds_read_b128 v[146:149], v159
	ds_read_b128 v[160:163], v159 offset:1024
	ds_read_b128 v[164:167], v159 offset:2048
	ds_read_b128 v[168:171], v159 offset:3072
	v_add_u32_e32 v159, s61, v151
	s_add_u32 s76, s76, 0x80000
	s_addc_u32 s77, s77, 0
	s_mov_b32 m0, s12
	v_lshl_add_u64 v[228:229], s[76:77], 0, v[128:129]
	global_load_lds_dwordx4 v[228:229], off
	v_lshl_add_u64 v[228:229], s[76:77], 0, v[132:133]
	s_mov_b32 m0, s13
	s_nop 0
	global_load_lds_dwordx4 v[228:229], off
	ds_read_b128 v[172:175], v159
	ds_read_b128 v[176:179], v159 offset:1024
	ds_read_b128 v[180:183], v159 offset:2048
	ds_read_b128 v[184:187], v159 offset:3072
	ds_read_b128 v[188:191], v157 offset:32768
	ds_read_b128 v[192:195], v157 offset:33792
	ds_read_b128 v[196:199], v157 offset:34816
	ds_read_b128 v[200:203], v157 offset:35840
	ds_read_b128 v[204:207], v157 offset:36864
	ds_read_b128 v[208:211], v157 offset:37888
	ds_read_b128 v[212:215], v157 offset:38912
	ds_read_b128 v[216:219], v157 offset:39936
	s_waitcnt vmcnt(8)
	s_waitcnt lgkmcnt(0)
	s_barrier
	s_setprio 1
	s_waitcnt lgkmcnt(0)
	v_mfma_f32_16x16x32_bf16 v[124:127], v[146:149], v[188:191], v[124:127]
	v_mfma_f32_16x16x32_bf16 v[120:123], v[164:167], v[188:191], v[120:123]
	v_mfma_f32_16x16x32_bf16 v[108:111], v[146:149], v[196:199], v[108:111]
	v_mfma_f32_16x16x32_bf16 v[104:107], v[164:167], v[196:199], v[104:107]
	v_mfma_f32_16x16x32_bf16 v[92:95], v[146:149], v[204:207], v[92:95]
	v_mfma_f32_16x16x32_bf16 v[88:91], v[164:167], v[204:207], v[88:91]
	v_mfma_f32_16x16x32_bf16 v[76:79], v[146:149], v[212:215], v[76:79]
	v_mfma_f32_16x16x32_bf16 v[72:75], v[164:167], v[212:215], v[72:75]
	v_mfma_f32_16x16x32_bf16 v[124:127], v[160:163], v[192:195], v[124:127]
	v_mfma_f32_16x16x32_bf16 v[120:123], v[168:171], v[192:195], v[120:123]
	v_mfma_f32_16x16x32_bf16 v[108:111], v[160:163], v[200:203], v[108:111]
	v_mfma_f32_16x16x32_bf16 v[104:107], v[168:171], v[200:203], v[104:107]
	v_mfma_f32_16x16x32_bf16 v[92:95], v[160:163], v[208:211], v[92:95]
	v_mfma_f32_16x16x32_bf16 v[88:91], v[168:171], v[208:211], v[88:91]
	v_mfma_f32_16x16x32_bf16 v[76:79], v[160:163], v[216:219], v[76:79]
	v_mfma_f32_16x16x32_bf16 v[72:75], v[168:171], v[216:219], v[72:75]
	v_mfma_f32_16x16x32_bf16 v[116:119], v[172:175], v[188:191], v[116:119]
	v_mfma_f32_16x16x32_bf16 v[112:115], v[180:183], v[188:191], v[112:115]
	v_mfma_f32_16x16x32_bf16 v[100:103], v[172:175], v[196:199], v[100:103]
	v_mfma_f32_16x16x32_bf16 v[96:99], v[180:183], v[196:199], v[96:99]
	v_mfma_f32_16x16x32_bf16 v[84:87], v[172:175], v[204:207], v[84:87]
	v_mfma_f32_16x16x32_bf16 v[80:83], v[180:183], v[204:207], v[80:83]
	v_mfma_f32_16x16x32_bf16 v[68:71], v[172:175], v[212:215], v[68:71]
	v_mfma_f32_16x16x32_bf16 v[64:67], v[180:183], v[212:215], v[64:67]
	v_mfma_f32_16x16x32_bf16 v[116:119], v[176:179], v[192:195], v[116:119]
	v_mfma_f32_16x16x32_bf16 v[112:115], v[184:187], v[192:195], v[112:115]
	v_mfma_f32_16x16x32_bf16 v[100:103], v[176:179], v[200:203], v[100:103]
	v_mfma_f32_16x16x32_bf16 v[96:99], v[184:187], v[200:203], v[96:99]
	v_mfma_f32_16x16x32_bf16 v[84:87], v[176:179], v[208:211], v[84:87]
	v_mfma_f32_16x16x32_bf16 v[80:83], v[184:187], v[208:211], v[80:83]
	v_mfma_f32_16x16x32_bf16 v[68:71], v[176:179], v[216:219], v[68:71]
	v_mfma_f32_16x16x32_bf16 v[64:67], v[184:187], v[216:219], v[64:67]
	s_setprio 0
	s_barrier
	s_add_i32 s60, s60, s94
	v_lshl_add_u64 v[220:221], v[220:221], 0, s[20:21]
	s_mov_b32 m0, s60
	s_nop 0
	global_load_lds_dwordx4 v[220:221], off
	s_add_i32 m0, s60, 0x2000
	s_add_u32 s74, s74, 0x80080
	v_lshl_add_u64 v[220:221], v[222:223], 0, s[20:21]
	s_addc_u32 s75, s75, 0
	s_add_i32 s60, s61, s94
	global_load_lds_dwordx4 v[220:221], off
	v_lshl_add_u64 v[220:221], s[74:75], 0, v[130:131]
	s_mov_b32 m0, s60
	s_nop 0
	global_load_lds_dwordx4 v[220:221], off
	v_lshl_add_u64 v[220:221], s[74:75], 0, v[134:135]
	s_add_i32 m0, s60, 0x2000
	s_nop 0
	global_load_lds_dwordx4 v[220:221], off
	v_lshl_add_u64 v[220:221], v[224:225], 0, s[20:21]
	s_mov_b32 m0, s30
	s_nop 0
	global_load_lds_dwordx4 v[220:221], off
	v_lshl_add_u64 v[220:221], v[226:227], 0, s[20:21]
	s_mov_b32 m0, s34
	s_nop 0
	global_load_lds_dwordx4 v[220:221], off
	ds_read_b128 v[188:191], v157 offset:49152
	ds_read_b128 v[192:195], v157 offset:50176
	ds_read_b128 v[196:199], v157 offset:51200
	ds_read_b128 v[200:203], v157 offset:52224
	ds_read_b128 v[204:207], v157 offset:53248
	ds_read_b128 v[208:211], v157 offset:54272
	ds_read_b128 v[212:215], v157 offset:55296
	ds_read_b128 v[216:219], v157 offset:56320
	s_waitcnt vmcnt(8)
	s_waitcnt lgkmcnt(0)
	s_barrier
	s_setprio 1
	s_waitcnt lgkmcnt(0)
	v_mfma_f32_16x16x32_bf16 v[60:63], v[146:149], v[188:191], v[60:63]
	v_mfma_f32_16x16x32_bf16 v[56:59], v[164:167], v[188:191], v[56:59]
	v_mfma_f32_16x16x32_bf16 v[44:47], v[146:149], v[196:199], v[44:47]
	v_mfma_f32_16x16x32_bf16 v[40:43], v[164:167], v[196:199], v[40:43]
	v_mfma_f32_16x16x32_bf16 v[28:31], v[146:149], v[204:207], v[28:31]
	v_mfma_f32_16x16x32_bf16 v[24:27], v[164:167], v[204:207], v[24:27]
	v_mfma_f32_16x16x32_bf16 v[12:15], v[146:149], v[212:215], v[12:15]
	v_mfma_f32_16x16x32_bf16 v[8:11], v[164:167], v[212:215], v[8:11]
	v_mfma_f32_16x16x32_bf16 v[60:63], v[160:163], v[192:195], v[60:63]
	v_mfma_f32_16x16x32_bf16 v[56:59], v[168:171], v[192:195], v[56:59]
	v_mfma_f32_16x16x32_bf16 v[44:47], v[160:163], v[200:203], v[44:47]
	v_mfma_f32_16x16x32_bf16 v[40:43], v[168:171], v[200:203], v[40:43]
	v_mfma_f32_16x16x32_bf16 v[28:31], v[160:163], v[208:211], v[28:31]
	v_mfma_f32_16x16x32_bf16 v[24:27], v[168:171], v[208:211], v[24:27]
	v_mfma_f32_16x16x32_bf16 v[12:15], v[160:163], v[216:219], v[12:15]
	v_mfma_f32_16x16x32_bf16 v[8:11], v[168:171], v[216:219], v[8:11]
	v_mfma_f32_16x16x32_bf16 v[52:55], v[172:175], v[188:191], v[52:55]
	v_mfma_f32_16x16x32_bf16 v[48:51], v[180:183], v[188:191], v[48:51]
	v_mfma_f32_16x16x32_bf16 v[36:39], v[172:175], v[196:199], v[36:39]
	v_mfma_f32_16x16x32_bf16 v[32:35], v[180:183], v[196:199], v[32:35]
	v_mfma_f32_16x16x32_bf16 v[20:23], v[172:175], v[204:207], v[20:23]
	v_mfma_f32_16x16x32_bf16 v[16:19], v[180:183], v[204:207], v[16:19]
	v_mfma_f32_16x16x32_bf16 v[4:7], v[172:175], v[212:215], v[4:7]
	v_mfma_f32_16x16x32_bf16 v[0:3], v[180:183], v[212:215], v[0:3]
	v_mfma_f32_16x16x32_bf16 v[52:55], v[176:179], v[192:195], v[52:55]
	v_mfma_f32_16x16x32_bf16 v[48:51], v[184:187], v[192:195], v[48:51]
	v_mfma_f32_16x16x32_bf16 v[36:39], v[176:179], v[200:203], v[36:39]
	v_mfma_f32_16x16x32_bf16 v[32:35], v[184:187], v[200:203], v[32:35]
	v_mfma_f32_16x16x32_bf16 v[20:23], v[176:179], v[208:211], v[20:23]
	v_mfma_f32_16x16x32_bf16 v[16:19], v[184:187], v[208:211], v[16:19]
	v_mfma_f32_16x16x32_bf16 v[4:7], v[176:179], v[216:219], v[4:7]
	v_mfma_f32_16x16x32_bf16 v[0:3], v[184:187], v[216:219], v[0:3]
	s_setprio 0
	s_barrier
	s_add_i32 s78, s78, 2
	s_add_u32 s72, s72, 0x100
	s_addc_u32 s73, s73, 0
	s_add_u32 s69, s69, 0x100
	s_addc_u32 s71, s71, 0
	s_cmp_gt_u32 s78, 29
	s_cbranch_scc0 .LBB0_1785
	s_and_b64 vcc, exec, s[58:59]
	s_cbranch_vccz .LBB0_1788
	s_barrier

.LBB0_1897:
	s_add_u32 s60, s72, 0xffe00080
	s_addc_u32 s61, s73, -1
	s_cmpk_eq_i32 s79, 0x7c
	s_cselect_b32 s77, s56, s61
	s_cselect_b32 s76, s57, s60
	s_cselect_b32 s75, s63, s78
	s_cselect_b32 s74, s65, s71
	v_lshl_add_u64 v[212:213], s[72:73], 0, v[132:133]
	s_add_i32 m0, s6, 0xc000
	s_nop 0
	global_load_lds_dwordx4 v[212:213], off
	v_lshl_add_u64 v[212:213], s[72:73], 0, v[134:135]
	s_add_i32 m0, s6, 0xe000
	s_nop 0
	global_load_lds_dwordx4 v[212:213], off
	ds_read_b128 v[140:143], v149
	ds_read_b128 v[152:155], v149 offset:1024
	ds_read_b128 v[156:159], v149 offset:2048
	ds_read_b128 v[160:163], v149 offset:3072
	ds_read_b128 v[164:167], v150
	ds_read_b128 v[168:171], v150 offset:1024
	ds_read_b128 v[172:175], v150 offset:2048
	ds_read_b128 v[176:179], v150 offset:3072
	ds_read_b128 v[180:183], v151
	ds_read_b128 v[184:187], v151 offset:1024
	ds_read_b128 v[188:191], v151 offset:2048
	ds_read_b128 v[192:195], v151 offset:3072
	ds_read_b128 v[196:199], v151 offset:4096
	ds_read_b128 v[200:203], v151 offset:5120
	ds_read_b128 v[204:207], v151 offset:6144
	ds_read_b128 v[208:211], v151 offset:7168
	s_waitcnt vmcnt(8)
	s_waitcnt lgkmcnt(0)
	s_barrier
	s_setprio 1
	s_waitcnt lgkmcnt(0)
	v_mfma_f32_16x16x32_bf16 v[124:127], v[140:143], v[180:183], v[124:127]
	v_mfma_f32_16x16x32_bf16 v[120:123], v[156:159], v[180:183], v[120:123]
	v_mfma_f32_16x16x32_bf16 v[108:111], v[140:143], v[188:191], v[108:111]
	v_mfma_f32_16x16x32_bf16 v[104:107], v[156:159], v[188:191], v[104:107]
	v_mfma_f32_16x16x32_bf16 v[92:95], v[140:143], v[196:199], v[92:95]
	v_mfma_f32_16x16x32_bf16 v[88:91], v[156:159], v[196:199], v[88:91]
	v_mfma_f32_16x16x32_bf16 v[76:79], v[140:143], v[204:207], v[76:79]
	v_mfma_f32_16x16x32_bf16 v[72:75], v[156:159], v[204:207], v[72:75]
	v_mfma_f32_16x16x32_bf16 v[124:127], v[152:155], v[184:187], v[124:127]
	v_mfma_f32_16x16x32_bf16 v[120:123], v[160:163], v[184:187], v[120:123]
	v_mfma_f32_16x16x32_bf16 v[108:111], v[152:155], v[192:195], v[108:111]
	v_mfma_f32_16x16x32_bf16 v[104:107], v[160:163], v[192:195], v[104:107]
	v_mfma_f32_16x16x32_bf16 v[92:95], v[152:155], v[200:203], v[92:95]
	v_mfma_f32_16x16x32_bf16 v[88:91], v[160:163], v[200:203], v[88:91]
	v_mfma_f32_16x16x32_bf16 v[76:79], v[152:155], v[208:211], v[76:79]
	v_mfma_f32_16x16x32_bf16 v[72:75], v[160:163], v[208:211], v[72:75]
	v_mfma_f32_16x16x32_bf16 v[116:119], v[164:167], v[180:183], v[116:119]
	v_mfma_f32_16x16x32_bf16 v[112:115], v[172:175], v[180:183], v[112:115]
	v_mfma_f32_16x16x32_bf16 v[100:103], v[164:167], v[188:191], v[100:103]
	v_mfma_f32_16x16x32_bf16 v[96:99], v[172:175], v[188:191], v[96:99]
	v_mfma_f32_16x16x32_bf16 v[84:87], v[164:167], v[196:199], v[84:87]
	v_mfma_f32_16x16x32_bf16 v[80:83], v[172:175], v[196:199], v[80:83]
	v_mfma_f32_16x16x32_bf16 v[68:71], v[164:167], v[204:207], v[68:71]
	v_mfma_f32_16x16x32_bf16 v[64:67], v[172:175], v[204:207], v[64:67]
	v_mfma_f32_16x16x32_bf16 v[116:119], v[168:171], v[184:187], v[116:119]
	v_mfma_f32_16x16x32_bf16 v[112:115], v[176:179], v[184:187], v[112:115]
	v_mfma_f32_16x16x32_bf16 v[100:103], v[168:171], v[192:195], v[100:103]
	v_mfma_f32_16x16x32_bf16 v[96:99], v[176:179], v[192:195], v[96:99]
	v_mfma_f32_16x16x32_bf16 v[84:87], v[168:171], v[200:203], v[84:87]
	v_mfma_f32_16x16x32_bf16 v[80:83], v[176:179], v[200:203], v[80:83]
	v_mfma_f32_16x16x32_bf16 v[68:71], v[168:171], v[208:211], v[68:71]
	v_mfma_f32_16x16x32_bf16 v[64:67], v[176:179], v[208:211], v[64:67]
	s_setprio 0
	s_barrier
	s_add_i32 s60, s34, s94
	v_lshl_add_u64 v[212:213], s[74:75], 0, v[128:129]
	s_mov_b32 m0, s60
	s_nop 0
	global_load_lds_dwordx4 v[212:213], off
	s_add_i32 m0, s60, 0x2000
	s_add_u32 s80, s74, 0x200000
	v_lshl_add_u64 v[214:215], s[74:75], 0, v[130:131]
	s_addc_u32 s81, s75, 0
	s_add_i32 s60, s35, s94
	global_load_lds_dwordx4 v[214:215], off
	v_lshl_add_u64 v[216:217], s[80:81], 0, v[128:129]
	s_mov_b32 m0, s60
	v_lshl_add_u64 v[218:219], s[76:77], 0, v[130:131]
	global_load_lds_dwordx4 v[216:217], off
	v_lshl_add_u64 v[216:217], s[80:81], 0, v[130:131]
	s_add_i32 m0, s60, 0x2000
	s_nop 0
	global_load_lds_dwordx4 v[216:217], off
	v_lshl_add_u64 v[216:217], s[76:77], 0, v[128:129]
	s_mov_b32 m0, s6
	s_nop 0
	global_load_lds_dwordx4 v[216:217], off
	s_mov_b32 m0, s7
	s_nop 0
	global_load_lds_dwordx4 v[218:219], off
	ds_read_b128 v[180:183], v151 offset:16384
	ds_read_b128 v[184:187], v151 offset:17408
	ds_read_b128 v[188:191], v151 offset:18432
	ds_read_b128 v[192:195], v151 offset:19456
	ds_read_b128 v[196:199], v151 offset:20480
	ds_read_b128 v[200:203], v151 offset:21504
	ds_read_b128 v[204:207], v151 offset:22528
	ds_read_b128 v[208:211], v151 offset:23552
	s_waitcnt vmcnt(8)
	s_waitcnt lgkmcnt(0)
	s_barrier
	s_setprio 1
	s_waitcnt lgkmcnt(0)
	v_mfma_f32_16x16x32_bf16 v[60:63], v[140:143], v[180:183], v[60:63]
	v_mfma_f32_16x16x32_bf16 v[56:59], v[156:159], v[180:183], v[56:59]
	v_mfma_f32_16x16x32_bf16 v[44:47], v[140:143], v[188:191], v[44:47]
	v_mfma_f32_16x16x32_bf16 v[40:43], v[156:159], v[188:191], v[40:43]
	v_mfma_f32_16x16x32_bf16 v[28:31], v[140:143], v[196:199], v[28:31]
	v_mfma_f32_16x16x32_bf16 v[24:27], v[156:159], v[196:199], v[24:27]
	v_mfma_f32_16x16x32_bf16 v[12:15], v[140:143], v[204:207], v[12:15]
	v_mfma_f32_16x16x32_bf16 v[8:11], v[156:159], v[204:207], v[8:11]
	v_mfma_f32_16x16x32_bf16 v[60:63], v[152:155], v[184:187], v[60:63]
	v_mfma_f32_16x16x32_bf16 v[56:59], v[160:163], v[184:187], v[56:59]
	v_mfma_f32_16x16x32_bf16 v[44:47], v[152:155], v[192:195], v[44:47]
	v_mfma_f32_16x16x32_bf16 v[40:43], v[160:163], v[192:195], v[40:43]
	v_mfma_f32_16x16x32_bf16 v[28:31], v[152:155], v[200:203], v[28:31]
	v_mfma_f32_16x16x32_bf16 v[24:27], v[160:163], v[200:203], v[24:27]
	v_mfma_f32_16x16x32_bf16 v[12:15], v[152:155], v[208:211], v[12:15]
	v_mfma_f32_16x16x32_bf16 v[8:11], v[160:163], v[208:211], v[8:11]
	v_mfma_f32_16x16x32_bf16 v[52:55], v[164:167], v[180:183], v[52:55]
	v_mfma_f32_16x16x32_bf16 v[48:51], v[172:175], v[180:183], v[48:51]
	v_mfma_f32_16x16x32_bf16 v[36:39], v[164:167], v[188:191], v[36:39]
	v_mfma_f32_16x16x32_bf16 v[32:35], v[172:175], v[188:191], v[32:35]
	v_mfma_f32_16x16x32_bf16 v[20:23], v[164:167], v[196:199], v[20:23]
	v_mfma_f32_16x16x32_bf16 v[16:19], v[172:175], v[196:199], v[16:19]
	v_mfma_f32_16x16x32_bf16 v[4:7], v[164:167], v[204:207], v[4:7]
	v_mfma_f32_16x16x32_bf16 v[0:3], v[172:175], v[204:207], v[0:3]
	v_mfma_f32_16x16x32_bf16 v[52:55], v[168:171], v[184:187], v[52:55]
	v_mfma_f32_16x16x32_bf16 v[48:51], v[176:179], v[184:187], v[48:51]
	v_mfma_f32_16x16x32_bf16 v[36:39], v[168:171], v[192:195], v[36:39]
	v_mfma_f32_16x16x32_bf16 v[32:35], v[176:179], v[192:195], v[32:35]
	v_mfma_f32_16x16x32_bf16 v[20:23], v[168:171], v[200:203], v[20:23]
	v_mfma_f32_16x16x32_bf16 v[16:19], v[176:179], v[200:203], v[16:19]
	v_mfma_f32_16x16x32_bf16 v[4:7], v[168:171], v[208:211], v[4:7]
	v_mfma_f32_16x16x32_bf16 v[0:3], v[176:179], v[208:211], v[0:3]
	s_setprio 0
	s_barrier
	s_add_i32 s60, 0, 0x18000
	s_add_i32 s61, 0, 0x1c000
	v_add_u32_e32 v160, s60, v145
	v_add_u32_e32 v176, s61, v145
	s_add_u32 s76, s76, 0x200000
	s_addc_u32 s77, s77, 0
	s_mov_b32 m0, s12
	v_lshl_add_u64 v[220:221], s[76:77], 0, v[128:129]
	global_load_lds_dwordx4 v[220:221], off
	v_lshl_add_u64 v[220:221], s[76:77], 0, v[130:131]
	s_mov_b32 m0, s13
	s_nop 0
	global_load_lds_dwordx4 v[220:221], off
	ds_read_b128 v[140:143], v160
	ds_read_b128 v[152:155], v160 offset:1024
	ds_read_b128 v[156:159], v160 offset:2048
	ds_read_b128 v[160:163], v160 offset:3072
	ds_read_b128 v[164:167], v176
	ds_read_b128 v[168:171], v176 offset:1024
	ds_read_b128 v[172:175], v176 offset:2048
	ds_read_b128 v[176:179], v176 offset:3072
	ds_read_b128 v[180:183], v151 offset:32768
	ds_read_b128 v[184:187], v151 offset:33792
	ds_read_b128 v[188:191], v151 offset:34816
	ds_read_b128 v[192:195], v151 offset:35840
	ds_read_b128 v[196:199], v151 offset:36864
	ds_read_b128 v[200:203], v151 offset:37888
	ds_read_b128 v[204:207], v151 offset:38912
	ds_read_b128 v[208:211], v151 offset:39936
	s_waitcnt vmcnt(8)
	s_waitcnt lgkmcnt(0)
	s_barrier
	s_setprio 1
	s_waitcnt lgkmcnt(0)
	v_mfma_f32_16x16x32_bf16 v[124:127], v[140:143], v[180:183], v[124:127]
	v_mfma_f32_16x16x32_bf16 v[120:123], v[156:159], v[180:183], v[120:123]
	v_mfma_f32_16x16x32_bf16 v[108:111], v[140:143], v[188:191], v[108:111]
	v_mfma_f32_16x16x32_bf16 v[104:107], v[156:159], v[188:191], v[104:107]
	v_mfma_f32_16x16x32_bf16 v[92:95], v[140:143], v[196:199], v[92:95]
	v_mfma_f32_16x16x32_bf16 v[88:91], v[156:159], v[196:199], v[88:91]
	v_mfma_f32_16x16x32_bf16 v[76:79], v[140:143], v[204:207], v[76:79]
	v_mfma_f32_16x16x32_bf16 v[72:75], v[156:159], v[204:207], v[72:75]
	v_mfma_f32_16x16x32_bf16 v[124:127], v[152:155], v[184:187], v[124:127]
	v_mfma_f32_16x16x32_bf16 v[120:123], v[160:163], v[184:187], v[120:123]
	v_mfma_f32_16x16x32_bf16 v[108:111], v[152:155], v[192:195], v[108:111]
	v_mfma_f32_16x16x32_bf16 v[104:107], v[160:163], v[192:195], v[104:107]
	v_mfma_f32_16x16x32_bf16 v[92:95], v[152:155], v[200:203], v[92:95]
	v_mfma_f32_16x16x32_bf16 v[88:91], v[160:163], v[200:203], v[88:91]
	v_mfma_f32_16x16x32_bf16 v[76:79], v[152:155], v[208:211], v[76:79]
	v_mfma_f32_16x16x32_bf16 v[72:75], v[160:163], v[208:211], v[72:75]
	v_mfma_f32_16x16x32_bf16 v[116:119], v[164:167], v[180:183], v[116:119]
	v_mfma_f32_16x16x32_bf16 v[112:115], v[172:175], v[180:183], v[112:115]
	v_mfma_f32_16x16x32_bf16 v[100:103], v[164:167], v[188:191], v[100:103]
	v_mfma_f32_16x16x32_bf16 v[96:99], v[172:175], v[188:191], v[96:99]
	v_mfma_f32_16x16x32_bf16 v[84:87], v[164:167], v[196:199], v[84:87]
	v_mfma_f32_16x16x32_bf16 v[80:83], v[172:175], v[196:199], v[80:83]
	v_mfma_f32_16x16x32_bf16 v[68:71], v[164:167], v[204:207], v[68:71]
	v_mfma_f32_16x16x32_bf16 v[64:67], v[172:175], v[204:207], v[64:67]
	v_mfma_f32_16x16x32_bf16 v[116:119], v[168:171], v[184:187], v[116:119]
	v_mfma_f32_16x16x32_bf16 v[112:115], v[176:179], v[184:187], v[112:115]
	v_mfma_f32_16x16x32_bf16 v[100:103], v[168:171], v[192:195], v[100:103]
	v_mfma_f32_16x16x32_bf16 v[96:99], v[176:179], v[192:195], v[96:99]
	v_mfma_f32_16x16x32_bf16 v[84:87], v[168:171], v[200:203], v[84:87]
	v_mfma_f32_16x16x32_bf16 v[80:83], v[176:179], v[200:203], v[80:83]
	v_mfma_f32_16x16x32_bf16 v[68:71], v[168:171], v[208:211], v[68:71]
	v_mfma_f32_16x16x32_bf16 v[64:67], v[176:179], v[208:211], v[64:67]
	s_setprio 0
	s_barrier
	s_add_i32 s60, s60, s94
	v_lshl_add_u64 v[212:213], v[212:213], 0, s[22:23]
	s_mov_b32 m0, s60
	s_nop 0
	global_load_lds_dwordx4 v[212:213], off
	s_add_i32 m0, s60, 0x2000
	s_add_u32 s74, s74, 0x200080
	v_lshl_add_u64 v[212:213], v[214:215], 0, s[22:23]
	s_addc_u32 s75, s75, 0
	s_add_i32 s60, s61, s94
	global_load_lds_dwordx4 v[212:213], off
	v_lshl_add_u64 v[212:213], s[74:75], 0, v[128:129]
	s_mov_b32 m0, s60
	s_nop 0
	global_load_lds_dwordx4 v[212:213], off
	v_lshl_add_u64 v[212:213], s[74:75], 0, v[130:131]
	s_add_i32 m0, s60, 0x2000
	s_nop 0
	global_load_lds_dwordx4 v[212:213], off
	v_lshl_add_u64 v[212:213], v[216:217], 0, s[22:23]
	s_mov_b32 m0, s29
	s_nop 0
	global_load_lds_dwordx4 v[212:213], off
	v_lshl_add_u64 v[212:213], v[218:219], 0, s[22:23]
	s_mov_b32 m0, s30
	s_nop 0
	global_load_lds_dwordx4 v[212:213], off
	ds_read_b128 v[180:183], v151 offset:49152
	ds_read_b128 v[184:187], v151 offset:50176
	ds_read_b128 v[188:191], v151 offset:51200
	ds_read_b128 v[192:195], v151 offset:52224
	ds_read_b128 v[196:199], v151 offset:53248
	ds_read_b128 v[200:203], v151 offset:54272
	ds_read_b128 v[204:207], v151 offset:55296
	ds_read_b128 v[208:211], v151 offset:56320
	s_waitcnt vmcnt(8)
	s_waitcnt lgkmcnt(0)
	s_barrier
	s_setprio 1
	s_waitcnt lgkmcnt(0)
	v_mfma_f32_16x16x32_bf16 v[60:63], v[140:143], v[180:183], v[60:63]
	v_mfma_f32_16x16x32_bf16 v[56:59], v[156:159], v[180:183], v[56:59]
	v_mfma_f32_16x16x32_bf16 v[44:47], v[140:143], v[188:191], v[44:47]
	v_mfma_f32_16x16x32_bf16 v[40:43], v[156:159], v[188:191], v[40:43]
	v_mfma_f32_16x16x32_bf16 v[28:31], v[140:143], v[196:199], v[28:31]
	v_mfma_f32_16x16x32_bf16 v[24:27], v[156:159], v[196:199], v[24:27]
	v_mfma_f32_16x16x32_bf16 v[12:15], v[140:143], v[204:207], v[12:15]
	v_mfma_f32_16x16x32_bf16 v[8:11], v[156:159], v[204:207], v[8:11]
	v_mfma_f32_16x16x32_bf16 v[60:63], v[152:155], v[184:187], v[60:63]
	v_mfma_f32_16x16x32_bf16 v[56:59], v[160:163], v[184:187], v[56:59]
	v_mfma_f32_16x16x32_bf16 v[44:47], v[152:155], v[192:195], v[44:47]
	v_mfma_f32_16x16x32_bf16 v[40:43], v[160:163], v[192:195], v[40:43]
	v_mfma_f32_16x16x32_bf16 v[28:31], v[152:155], v[200:203], v[28:31]
	v_mfma_f32_16x16x32_bf16 v[24:27], v[160:163], v[200:203], v[24:27]
	v_mfma_f32_16x16x32_bf16 v[12:15], v[152:155], v[208:211], v[12:15]
	v_mfma_f32_16x16x32_bf16 v[8:11], v[160:163], v[208:211], v[8:11]
	v_mfma_f32_16x16x32_bf16 v[52:55], v[164:167], v[180:183], v[52:55]
	v_mfma_f32_16x16x32_bf16 v[48:51], v[172:175], v[180:183], v[48:51]
	v_mfma_f32_16x16x32_bf16 v[36:39], v[164:167], v[188:191], v[36:39]
	v_mfma_f32_16x16x32_bf16 v[32:35], v[172:175], v[188:191], v[32:35]
	v_mfma_f32_16x16x32_bf16 v[20:23], v[164:167], v[196:199], v[20:23]
	v_mfma_f32_16x16x32_bf16 v[16:19], v[172:175], v[196:199], v[16:19]
	v_mfma_f32_16x16x32_bf16 v[4:7], v[164:167], v[204:207], v[4:7]
	v_mfma_f32_16x16x32_bf16 v[0:3], v[172:175], v[204:207], v[0:3]
	v_mfma_f32_16x16x32_bf16 v[52:55], v[168:171], v[184:187], v[52:55]
	v_mfma_f32_16x16x32_bf16 v[48:51], v[176:179], v[184:187], v[48:51]
	v_mfma_f32_16x16x32_bf16 v[36:39], v[168:171], v[192:195], v[36:39]
	v_mfma_f32_16x16x32_bf16 v[32:35], v[176:179], v[192:195], v[32:35]
	v_mfma_f32_16x16x32_bf16 v[20:23], v[168:171], v[200:203], v[20:23]
	v_mfma_f32_16x16x32_bf16 v[16:19], v[176:179], v[200:203], v[16:19]
	v_mfma_f32_16x16x32_bf16 v[4:7], v[168:171], v[208:211], v[4:7]
	v_mfma_f32_16x16x32_bf16 v[0:3], v[176:179], v[208:211], v[0:3]
	s_setprio 0
	s_barrier
	s_add_i32 s79, s79, 2
	s_add_u32 s72, s72, 0x100
	s_addc_u32 s73, s73, 0
	s_add_u32 s71, s71, 0x100
	s_addc_u32 s78, s78, 0
	s_cmpk_gt_u32 s79, 0x7d
	s_cbranch_scc0 .LBB0_1897
	s_and_b64 vcc, exec, s[58:59]
	s_cbranch_vccz .LBB0_1900
	s_barrier

.LBB0_2128:
	s_add_u32 s60, s84, 0xfff80080
	s_addc_u32 s61, s85, -1
	s_cmp_eq_u32 s95, 28
	s_cselect_b32 s89, s23, s61
	s_cselect_b32 s88, s79, s60
	s_cselect_b32 s87, s77, s97
	s_cselect_b32 s86, vcc_lo, vcc_hi
	v_lshl_add_u64 v[172:173], s[84:85], 0, v[140:141]
	s_add_i32 m0, s6, 0xc000
	s_nop 0
	global_load_lds_dwordx4 v[172:173], off
	v_lshl_add_u64 v[172:173], s[84:85], 0, v[142:143]
	s_add_i32 m0, s6, 0xe000
	s_nop 0
	global_load_lds_dwordx4 v[172:173], off
	ds_read_b128 v[148:151], v179
	ds_read_b128 v[152:155], v179 offset:1024
	ds_read_b128 v[156:159], v179 offset:2048
	ds_read_b128 v[160:163], v179 offset:3072
	ds_read_b128 v[164:167], v180
	ds_read_b128 v[168:171], v180 offset:1024
	ds_read_b128 v[184:187], v180 offset:2048
	ds_read_b128 v[188:191], v180 offset:3072
	ds_read_b128 v[192:195], v181
	ds_read_b128 v[196:199], v181 offset:1024
	ds_read_b128 v[200:203], v181 offset:2048
	ds_read_b128 v[204:207], v181 offset:3072
	ds_read_b128 v[208:211], v181 offset:4096
	ds_read_b128 v[212:215], v181 offset:5120
	ds_read_b128 v[216:219], v181 offset:6144
	ds_read_b128 v[220:223], v181 offset:7168
	s_waitcnt vmcnt(8)
	s_waitcnt lgkmcnt(0)
	s_barrier
	s_setprio 1
	s_waitcnt lgkmcnt(0)
	v_mfma_f32_16x16x32_bf16 v[124:127], v[148:151], v[192:195], v[124:127]
	v_mfma_f32_16x16x32_bf16 v[120:123], v[156:159], v[192:195], v[120:123]
	v_mfma_f32_16x16x32_bf16 v[108:111], v[148:151], v[200:203], v[108:111]
	v_mfma_f32_16x16x32_bf16 v[104:107], v[156:159], v[200:203], v[104:107]
	v_mfma_f32_16x16x32_bf16 v[92:95], v[148:151], v[208:211], v[92:95]
	v_mfma_f32_16x16x32_bf16 v[88:91], v[156:159], v[208:211], v[88:91]
	v_mfma_f32_16x16x32_bf16 v[76:79], v[148:151], v[216:219], v[76:79]
	v_mfma_f32_16x16x32_bf16 v[72:75], v[156:159], v[216:219], v[72:75]
	v_mfma_f32_16x16x32_bf16 v[124:127], v[152:155], v[196:199], v[124:127]
	v_mfma_f32_16x16x32_bf16 v[120:123], v[160:163], v[196:199], v[120:123]
	v_mfma_f32_16x16x32_bf16 v[108:111], v[152:155], v[204:207], v[108:111]
	v_mfma_f32_16x16x32_bf16 v[104:107], v[160:163], v[204:207], v[104:107]
	v_mfma_f32_16x16x32_bf16 v[92:95], v[152:155], v[212:215], v[92:95]
	v_mfma_f32_16x16x32_bf16 v[88:91], v[160:163], v[212:215], v[88:91]
	v_mfma_f32_16x16x32_bf16 v[76:79], v[152:155], v[220:223], v[76:79]
	v_mfma_f32_16x16x32_bf16 v[72:75], v[160:163], v[220:223], v[72:75]
	v_mfma_f32_16x16x32_bf16 v[116:119], v[164:167], v[192:195], v[116:119]
	v_mfma_f32_16x16x32_bf16 v[112:115], v[184:187], v[192:195], v[112:115]
	v_mfma_f32_16x16x32_bf16 v[100:103], v[164:167], v[200:203], v[100:103]
	v_mfma_f32_16x16x32_bf16 v[96:99], v[184:187], v[200:203], v[96:99]
	v_mfma_f32_16x16x32_bf16 v[84:87], v[164:167], v[208:211], v[84:87]
	v_mfma_f32_16x16x32_bf16 v[80:83], v[184:187], v[208:211], v[80:83]
	v_mfma_f32_16x16x32_bf16 v[68:71], v[164:167], v[216:219], v[68:71]
	v_mfma_f32_16x16x32_bf16 v[64:67], v[184:187], v[216:219], v[64:67]
	v_mfma_f32_16x16x32_bf16 v[116:119], v[168:171], v[196:199], v[116:119]
	v_mfma_f32_16x16x32_bf16 v[112:115], v[188:191], v[196:199], v[112:115]
	v_mfma_f32_16x16x32_bf16 v[100:103], v[168:171], v[204:207], v[100:103]
	v_mfma_f32_16x16x32_bf16 v[96:99], v[188:191], v[204:207], v[96:99]
	v_mfma_f32_16x16x32_bf16 v[84:87], v[168:171], v[212:215], v[84:87]
	v_mfma_f32_16x16x32_bf16 v[80:83], v[188:191], v[212:215], v[80:83]
	v_mfma_f32_16x16x32_bf16 v[68:71], v[168:171], v[220:223], v[68:71]
	v_mfma_f32_16x16x32_bf16 v[64:67], v[188:191], v[220:223], v[64:67]
	s_setprio 0
	s_barrier
	s_add_i32 s60, s12, s94
	v_lshl_add_u64 v[172:173], s[86:87], 0, v[130:131]
	s_mov_b32 m0, s60
	s_nop 0
	global_load_lds_dwordx4 v[172:173], off
	s_add_i32 m0, s60, 0x2000
	s_add_u32 s60, s86, 0x80000
	v_lshl_add_u64 v[224:225], s[86:87], 0, v[134:135]
	s_addc_u32 s61, s87, 0
	s_add_i32 s96, s13, s94
	global_load_lds_dwordx4 v[224:225], off
	v_lshl_add_u64 v[226:227], s[60:61], 0, v[130:131]
	s_mov_b32 m0, s96
	v_lshl_add_u64 v[228:229], s[88:89], 0, v[132:133]
	global_load_lds_dwordx4 v[226:227], off
	v_lshl_add_u64 v[226:227], s[60:61], 0, v[134:135]
	s_add_i32 m0, s96, 0x2000
	s_nop 0
	global_load_lds_dwordx4 v[226:227], off
	v_lshl_add_u64 v[226:227], s[88:89], 0, v[128:129]
	s_mov_b32 m0, s6
	s_nop 0
	global_load_lds_dwordx4 v[226:227], off
	s_mov_b32 m0, s7
	s_nop 0
	global_load_lds_dwordx4 v[228:229], off
	ds_read_b128 v[192:195], v181 offset:16384
	ds_read_b128 v[196:199], v181 offset:17408
	ds_read_b128 v[200:203], v181 offset:18432
	ds_read_b128 v[204:207], v181 offset:19456
	ds_read_b128 v[208:211], v181 offset:20480
	ds_read_b128 v[212:215], v181 offset:21504
	ds_read_b128 v[216:219], v181 offset:22528
	ds_read_b128 v[220:223], v181 offset:23552
	s_waitcnt vmcnt(8)
	s_waitcnt lgkmcnt(0)
	s_barrier
	s_setprio 1
	s_waitcnt lgkmcnt(0)
	v_mfma_f32_16x16x32_bf16 v[60:63], v[148:151], v[192:195], v[60:63]
	v_mfma_f32_16x16x32_bf16 v[56:59], v[156:159], v[192:195], v[56:59]
	v_mfma_f32_16x16x32_bf16 v[44:47], v[148:151], v[200:203], v[44:47]
	v_mfma_f32_16x16x32_bf16 v[40:43], v[156:159], v[200:203], v[40:43]
	v_mfma_f32_16x16x32_bf16 v[28:31], v[148:151], v[208:211], v[28:31]
	v_mfma_f32_16x16x32_bf16 v[24:27], v[156:159], v[208:211], v[24:27]
	v_mfma_f32_16x16x32_bf16 v[12:15], v[148:151], v[216:219], v[12:15]
	v_mfma_f32_16x16x32_bf16 v[8:11], v[156:159], v[216:219], v[8:11]
	v_mfma_f32_16x16x32_bf16 v[60:63], v[152:155], v[196:199], v[60:63]
	v_mfma_f32_16x16x32_bf16 v[56:59], v[160:163], v[196:199], v[56:59]
	v_mfma_f32_16x16x32_bf16 v[44:47], v[152:155], v[204:207], v[44:47]
	v_mfma_f32_16x16x32_bf16 v[40:43], v[160:163], v[204:207], v[40:43]
	v_mfma_f32_16x16x32_bf16 v[28:31], v[152:155], v[212:215], v[28:31]
	v_mfma_f32_16x16x32_bf16 v[24:27], v[160:163], v[212:215], v[24:27]
	v_mfma_f32_16x16x32_bf16 v[12:15], v[152:155], v[220:223], v[12:15]
	v_mfma_f32_16x16x32_bf16 v[8:11], v[160:163], v[220:223], v[8:11]
	v_mfma_f32_16x16x32_bf16 v[52:55], v[164:167], v[192:195], v[52:55]
	v_mfma_f32_16x16x32_bf16 v[48:51], v[184:187], v[192:195], v[48:51]
	v_mfma_f32_16x16x32_bf16 v[36:39], v[164:167], v[200:203], v[36:39]
	v_mfma_f32_16x16x32_bf16 v[32:35], v[184:187], v[200:203], v[32:35]
	v_mfma_f32_16x16x32_bf16 v[20:23], v[164:167], v[208:211], v[20:23]
	v_mfma_f32_16x16x32_bf16 v[16:19], v[184:187], v[208:211], v[16:19]
	v_mfma_f32_16x16x32_bf16 v[4:7], v[164:167], v[216:219], v[4:7]
	v_mfma_f32_16x16x32_bf16 v[0:3], v[184:187], v[216:219], v[0:3]
	v_mfma_f32_16x16x32_bf16 v[52:55], v[168:171], v[196:199], v[52:55]
	v_mfma_f32_16x16x32_bf16 v[48:51], v[188:191], v[196:199], v[48:51]
	v_mfma_f32_16x16x32_bf16 v[36:39], v[168:171], v[204:207], v[36:39]
	v_mfma_f32_16x16x32_bf16 v[32:35], v[188:191], v[204:207], v[32:35]
	v_mfma_f32_16x16x32_bf16 v[20:23], v[168:171], v[212:215], v[20:23]
	v_mfma_f32_16x16x32_bf16 v[16:19], v[188:191], v[212:215], v[16:19]
	v_mfma_f32_16x16x32_bf16 v[4:7], v[168:171], v[220:223], v[4:7]
	v_mfma_f32_16x16x32_bf16 v[0:3], v[188:191], v[220:223], v[0:3]
	s_setprio 0
	s_barrier
	s_add_i32 s96, 0, 0x18000
	v_add_u32_e32 v136, s96, v175
	s_add_i32 s8, 0, 0x1c000
	ds_read_b128 v[148:151], v136
	ds_read_b128 v[152:155], v136 offset:1024
	ds_read_b128 v[156:159], v136 offset:2048
	ds_read_b128 v[160:163], v136 offset:3072
	v_add_u32_e32 v136, s8, v175
	s_add_u32 s60, s88, 0x80000
	s_addc_u32 s61, s89, 0
	s_mov_b32 m0, s34
	v_lshl_add_u64 v[230:231], s[60:61], 0, v[128:129]
	global_load_lds_dwordx4 v[230:231], off
	v_lshl_add_u64 v[230:231], s[60:61], 0, v[132:133]
	s_mov_b32 m0, s46
	s_nop 0
	global_load_lds_dwordx4 v[230:231], off
	ds_read_b128 v[164:167], v136
	ds_read_b128 v[168:171], v136 offset:1024
	ds_read_b128 v[184:187], v136 offset:2048
	ds_read_b128 v[188:191], v136 offset:3072
	ds_read_b128 v[192:195], v181 offset:32768
	ds_read_b128 v[196:199], v181 offset:33792
	ds_read_b128 v[200:203], v181 offset:34816
	ds_read_b128 v[204:207], v181 offset:35840
	ds_read_b128 v[208:211], v181 offset:36864
	ds_read_b128 v[212:215], v181 offset:37888
	ds_read_b128 v[216:219], v181 offset:38912
	ds_read_b128 v[220:223], v181 offset:39936
	s_waitcnt vmcnt(8)
	s_waitcnt lgkmcnt(0)
	s_barrier
	s_setprio 1
	s_waitcnt lgkmcnt(0)
	v_mfma_f32_16x16x32_bf16 v[124:127], v[148:151], v[192:195], v[124:127]
	v_mfma_f32_16x16x32_bf16 v[120:123], v[156:159], v[192:195], v[120:123]
	v_mfma_f32_16x16x32_bf16 v[108:111], v[148:151], v[200:203], v[108:111]
	v_mfma_f32_16x16x32_bf16 v[104:107], v[156:159], v[200:203], v[104:107]
	v_mfma_f32_16x16x32_bf16 v[92:95], v[148:151], v[208:211], v[92:95]
	v_mfma_f32_16x16x32_bf16 v[88:91], v[156:159], v[208:211], v[88:91]
	v_mfma_f32_16x16x32_bf16 v[76:79], v[148:151], v[216:219], v[76:79]
	v_mfma_f32_16x16x32_bf16 v[72:75], v[156:159], v[216:219], v[72:75]
	v_mfma_f32_16x16x32_bf16 v[124:127], v[152:155], v[196:199], v[124:127]
	v_mfma_f32_16x16x32_bf16 v[120:123], v[160:163], v[196:199], v[120:123]
	v_mfma_f32_16x16x32_bf16 v[108:111], v[152:155], v[204:207], v[108:111]
	v_mfma_f32_16x16x32_bf16 v[104:107], v[160:163], v[204:207], v[104:107]
	v_mfma_f32_16x16x32_bf16 v[92:95], v[152:155], v[212:215], v[92:95]
	v_mfma_f32_16x16x32_bf16 v[88:91], v[160:163], v[212:215], v[88:91]
	v_mfma_f32_16x16x32_bf16 v[76:79], v[152:155], v[220:223], v[76:79]
	v_mfma_f32_16x16x32_bf16 v[72:75], v[160:163], v[220:223], v[72:75]
	v_mfma_f32_16x16x32_bf16 v[116:119], v[164:167], v[192:195], v[116:119]
	v_mfma_f32_16x16x32_bf16 v[112:115], v[184:187], v[192:195], v[112:115]
	v_mfma_f32_16x16x32_bf16 v[100:103], v[164:167], v[200:203], v[100:103]
	v_mfma_f32_16x16x32_bf16 v[96:99], v[184:187], v[200:203], v[96:99]
	v_mfma_f32_16x16x32_bf16 v[84:87], v[164:167], v[208:211], v[84:87]
	v_mfma_f32_16x16x32_bf16 v[80:83], v[184:187], v[208:211], v[80:83]
	v_mfma_f32_16x16x32_bf16 v[68:71], v[164:167], v[216:219], v[68:71]
	v_mfma_f32_16x16x32_bf16 v[64:67], v[184:187], v[216:219], v[64:67]
	v_mfma_f32_16x16x32_bf16 v[116:119], v[168:171], v[196:199], v[116:119]
	v_mfma_f32_16x16x32_bf16 v[112:115], v[188:191], v[196:199], v[112:115]
	v_mfma_f32_16x16x32_bf16 v[100:103], v[168:171], v[204:207], v[100:103]
	v_mfma_f32_16x16x32_bf16 v[96:99], v[188:191], v[204:207], v[96:99]
	v_mfma_f32_16x16x32_bf16 v[84:87], v[168:171], v[212:215], v[84:87]
	v_mfma_f32_16x16x32_bf16 v[80:83], v[188:191], v[212:215], v[80:83]
	v_mfma_f32_16x16x32_bf16 v[68:71], v[168:171], v[220:223], v[68:71]
	v_mfma_f32_16x16x32_bf16 v[64:67], v[188:191], v[220:223], v[64:67]
	s_setprio 0
	s_barrier
	s_add_i32 s9, s96, s94
	v_lshl_add_u64 v[172:173], v[172:173], 0, s[74:75]
	s_mov_b32 m0, s9
	s_nop 0
	global_load_lds_dwordx4 v[172:173], off
	s_add_i32 m0, s9, 0x2000
	s_add_u32 s60, s86, 0x80080
	v_lshl_add_u64 v[172:173], v[224:225], 0, s[74:75]
	s_addc_u32 s61, s87, 0
	s_add_i32 s8, s8, s94
	global_load_lds_dwordx4 v[172:173], off
	v_lshl_add_u64 v[172:173], s[60:61], 0, v[130:131]
	s_mov_b32 m0, s8
	s_nop 0
	global_load_lds_dwordx4 v[172:173], off
	v_lshl_add_u64 v[172:173], s[60:61], 0, v[134:135]
	s_add_i32 m0, s8, 0x2000
	s_nop 0
	global_load_lds_dwordx4 v[172:173], off
	v_lshl_add_u64 v[172:173], v[226:227], 0, s[74:75]
	s_mov_b32 m0, s56
	s_nop 0
	global_load_lds_dwordx4 v[172:173], off
	v_lshl_add_u64 v[172:173], v[228:229], 0, s[74:75]
	s_mov_b32 m0, s57
	s_nop 0
	global_load_lds_dwordx4 v[172:173], off
	ds_read_b128 v[192:195], v181 offset:49152
	ds_read_b128 v[196:199], v181 offset:50176
	ds_read_b128 v[200:203], v181 offset:51200
	ds_read_b128 v[204:207], v181 offset:52224
	ds_read_b128 v[208:211], v181 offset:53248
	ds_read_b128 v[212:215], v181 offset:54272
	ds_read_b128 v[216:219], v181 offset:55296
	ds_read_b128 v[220:223], v181 offset:56320
	s_waitcnt vmcnt(8)
	s_waitcnt lgkmcnt(0)
	s_barrier
	s_setprio 1
	s_waitcnt lgkmcnt(0)
	v_mfma_f32_16x16x32_bf16 v[60:63], v[148:151], v[192:195], v[60:63]
	v_mfma_f32_16x16x32_bf16 v[56:59], v[156:159], v[192:195], v[56:59]
	v_mfma_f32_16x16x32_bf16 v[44:47], v[148:151], v[200:203], v[44:47]
	v_mfma_f32_16x16x32_bf16 v[40:43], v[156:159], v[200:203], v[40:43]
	v_mfma_f32_16x16x32_bf16 v[28:31], v[148:151], v[208:211], v[28:31]
	v_mfma_f32_16x16x32_bf16 v[24:27], v[156:159], v[208:211], v[24:27]
	v_mfma_f32_16x16x32_bf16 v[12:15], v[148:151], v[216:219], v[12:15]
	v_mfma_f32_16x16x32_bf16 v[8:11], v[156:159], v[216:219], v[8:11]
	v_mfma_f32_16x16x32_bf16 v[60:63], v[152:155], v[196:199], v[60:63]
	v_mfma_f32_16x16x32_bf16 v[56:59], v[160:163], v[196:199], v[56:59]
	v_mfma_f32_16x16x32_bf16 v[44:47], v[152:155], v[204:207], v[44:47]
	v_mfma_f32_16x16x32_bf16 v[40:43], v[160:163], v[204:207], v[40:43]
	v_mfma_f32_16x16x32_bf16 v[28:31], v[152:155], v[212:215], v[28:31]
	v_mfma_f32_16x16x32_bf16 v[24:27], v[160:163], v[212:215], v[24:27]
	v_mfma_f32_16x16x32_bf16 v[12:15], v[152:155], v[220:223], v[12:15]
	v_mfma_f32_16x16x32_bf16 v[8:11], v[160:163], v[220:223], v[8:11]
	v_mfma_f32_16x16x32_bf16 v[52:55], v[164:167], v[192:195], v[52:55]
	v_mfma_f32_16x16x32_bf16 v[48:51], v[184:187], v[192:195], v[48:51]
	v_mfma_f32_16x16x32_bf16 v[36:39], v[164:167], v[200:203], v[36:39]
	v_mfma_f32_16x16x32_bf16 v[32:35], v[184:187], v[200:203], v[32:35]
	v_mfma_f32_16x16x32_bf16 v[20:23], v[164:167], v[208:211], v[20:23]
	v_mfma_f32_16x16x32_bf16 v[16:19], v[184:187], v[208:211], v[16:19]
	v_mfma_f32_16x16x32_bf16 v[4:7], v[164:167], v[216:219], v[4:7]
	v_mfma_f32_16x16x32_bf16 v[0:3], v[184:187], v[216:219], v[0:3]
	v_mfma_f32_16x16x32_bf16 v[52:55], v[168:171], v[196:199], v[52:55]
	v_mfma_f32_16x16x32_bf16 v[48:51], v[188:191], v[196:199], v[48:51]
	v_mfma_f32_16x16x32_bf16 v[36:39], v[168:171], v[204:207], v[36:39]
	v_mfma_f32_16x16x32_bf16 v[32:35], v[188:191], v[204:207], v[32:35]
	v_mfma_f32_16x16x32_bf16 v[20:23], v[168:171], v[212:215], v[20:23]
	v_mfma_f32_16x16x32_bf16 v[16:19], v[188:191], v[212:215], v[16:19]
	v_mfma_f32_16x16x32_bf16 v[4:7], v[168:171], v[220:223], v[4:7]
	v_mfma_f32_16x16x32_bf16 v[0:3], v[188:191], v[220:223], v[0:3]
	s_setprio 0
	s_barrier
	s_add_i32 s95, s95, 2
	s_add_u32 s84, s84, 0x100
	s_addc_u32 s85, s85, 0
	s_add_u32 vcc_hi, vcc_hi, 0x100
	s_addc_u32 s97, s97, 0
	s_cmp_gt_u32 s95, 29
	s_cbranch_scc0 .LBB0_2128
	s_and_b64 vcc, exec, s[58:59]
	s_cbranch_vccz .LBB0_2131
	s_barrier

.LBB0_2459:
	s_add_u32 s16, s70, 0x100
	s_addc_u32 s17, s71, 0
	s_cmp_eq_u32 s86, 8
	s_cselect_b32 s75, s23, s17
	s_cselect_b32 s74, s22, s16
	s_cselect_b32 s73, s49, s85
	s_cselect_b32 s72, s48, s84
	v_lshl_add_u64 v[156:157], s[70:71], 0, v[140:141]
	s_add_i32 m0, s12, 0xc000
	s_nop 0
	global_load_lds_dwordx4 v[156:157], off
	v_lshl_add_u64 v[156:157], s[70:71], 0, v[142:143]
	s_add_i32 m0, s12, 0xe000
	s_nop 0
	global_load_lds_dwordx4 v[156:157], off
	ds_read_b128 v[148:151], v163
	ds_read_b128 v[152:155], v163 offset:1024
	ds_read_b128 v[168:171], v163 offset:2048
	ds_read_b128 v[172:175], v163 offset:3072
	ds_read_b128 v[176:179], v164
	ds_read_b128 v[180:183], v164 offset:1024
	ds_read_b128 v[184:187], v164 offset:2048
	ds_read_b128 v[188:191], v164 offset:3072
	ds_read_b128 v[192:195], v165
	ds_read_b128 v[196:199], v165 offset:1024
	ds_read_b128 v[200:203], v165 offset:2048
	ds_read_b128 v[204:207], v165 offset:3072
	ds_read_b128 v[208:211], v165 offset:4096
	ds_read_b128 v[212:215], v165 offset:5120
	ds_read_b128 v[216:219], v165 offset:6144
	ds_read_b128 v[220:223], v165 offset:7168
	s_waitcnt vmcnt(8)
	s_waitcnt lgkmcnt(0)
	s_barrier
	s_setprio 1
	s_waitcnt lgkmcnt(0)
	v_mfma_f32_16x16x32_bf16 v[124:127], v[148:151], v[192:195], v[124:127]
	v_mfma_f32_16x16x32_bf16 v[120:123], v[168:171], v[192:195], v[120:123]
	v_mfma_f32_16x16x32_bf16 v[108:111], v[148:151], v[200:203], v[108:111]
	v_mfma_f32_16x16x32_bf16 v[104:107], v[168:171], v[200:203], v[104:107]
	v_mfma_f32_16x16x32_bf16 v[92:95], v[148:151], v[208:211], v[92:95]
	v_mfma_f32_16x16x32_bf16 v[88:91], v[168:171], v[208:211], v[88:91]
	v_mfma_f32_16x16x32_bf16 v[76:79], v[148:151], v[216:219], v[76:79]
	v_mfma_f32_16x16x32_bf16 v[72:75], v[168:171], v[216:219], v[72:75]
	v_mfma_f32_16x16x32_bf16 v[124:127], v[152:155], v[196:199], v[124:127]
	v_mfma_f32_16x16x32_bf16 v[120:123], v[172:175], v[196:199], v[120:123]
	v_mfma_f32_16x16x32_bf16 v[108:111], v[152:155], v[204:207], v[108:111]
	v_mfma_f32_16x16x32_bf16 v[104:107], v[172:175], v[204:207], v[104:107]
	v_mfma_f32_16x16x32_bf16 v[92:95], v[152:155], v[212:215], v[92:95]
	v_mfma_f32_16x16x32_bf16 v[88:91], v[172:175], v[212:215], v[88:91]
	v_mfma_f32_16x16x32_bf16 v[76:79], v[152:155], v[220:223], v[76:79]
	v_mfma_f32_16x16x32_bf16 v[72:75], v[172:175], v[220:223], v[72:75]
	v_mfma_f32_16x16x32_bf16 v[116:119], v[176:179], v[192:195], v[116:119]
	v_mfma_f32_16x16x32_bf16 v[112:115], v[184:187], v[192:195], v[112:115]
	v_mfma_f32_16x16x32_bf16 v[100:103], v[176:179], v[200:203], v[100:103]
	v_mfma_f32_16x16x32_bf16 v[96:99], v[184:187], v[200:203], v[96:99]
	v_mfma_f32_16x16x32_bf16 v[84:87], v[176:179], v[208:211], v[84:87]
	v_mfma_f32_16x16x32_bf16 v[80:83], v[184:187], v[208:211], v[80:83]
	v_mfma_f32_16x16x32_bf16 v[68:71], v[176:179], v[216:219], v[68:71]
	v_mfma_f32_16x16x32_bf16 v[64:67], v[184:187], v[216:219], v[64:67]
	v_mfma_f32_16x16x32_bf16 v[116:119], v[180:183], v[196:199], v[116:119]
	v_mfma_f32_16x16x32_bf16 v[112:115], v[188:191], v[196:199], v[112:115]
	v_mfma_f32_16x16x32_bf16 v[100:103], v[180:183], v[204:207], v[100:103]
	v_mfma_f32_16x16x32_bf16 v[96:99], v[188:191], v[204:207], v[96:99]
	v_mfma_f32_16x16x32_bf16 v[84:87], v[180:183], v[212:215], v[84:87]
	v_mfma_f32_16x16x32_bf16 v[80:83], v[188:191], v[212:215], v[80:83]
	v_mfma_f32_16x16x32_bf16 v[68:71], v[180:183], v[220:223], v[68:71]
	v_mfma_f32_16x16x32_bf16 v[64:67], v[188:191], v[220:223], v[64:67]
	s_setprio 0
	s_barrier
	s_add_i32 s8, s76, s94
	v_lshl_add_u64 v[156:157], s[72:73], 0, v[130:131]
	s_mov_b32 m0, s8
	s_nop 0
	global_load_lds_dwordx4 v[156:157], off
	s_add_i32 m0, s8, 0x2000
	s_add_u32 s60, s72, 0x30000
	v_lshl_add_u64 v[224:225], s[72:73], 0, v[134:135]
	s_addc_u32 s61, s73, 0
	s_add_i32 s8, s77, s94
	global_load_lds_dwordx4 v[224:225], off
	v_lshl_add_u64 v[226:227], s[60:61], 0, v[130:131]
	s_mov_b32 m0, s8
	v_lshl_add_u64 v[228:229], s[74:75], 0, v[132:133]
	global_load_lds_dwordx4 v[226:227], off
	v_lshl_add_u64 v[226:227], s[60:61], 0, v[134:135]
	s_add_i32 m0, s8, 0x2000
	s_nop 0
	global_load_lds_dwordx4 v[226:227], off
	v_lshl_add_u64 v[226:227], s[74:75], 0, v[128:129]
	s_mov_b32 m0, s12
	s_nop 0
	global_load_lds_dwordx4 v[226:227], off
	s_mov_b32 m0, s13
	s_nop 0
	global_load_lds_dwordx4 v[228:229], off
	ds_read_b128 v[192:195], v165 offset:16384
	ds_read_b128 v[196:199], v165 offset:17408
	ds_read_b128 v[200:203], v165 offset:18432
	ds_read_b128 v[204:207], v165 offset:19456
	ds_read_b128 v[208:211], v165 offset:20480
	ds_read_b128 v[212:215], v165 offset:21504
	ds_read_b128 v[216:219], v165 offset:22528
	ds_read_b128 v[220:223], v165 offset:23552
	s_waitcnt vmcnt(8)
	s_waitcnt lgkmcnt(0)
	s_barrier
	s_setprio 1
	s_waitcnt lgkmcnt(0)
	v_mfma_f32_16x16x32_bf16 v[60:63], v[148:151], v[192:195], v[60:63]
	v_mfma_f32_16x16x32_bf16 v[56:59], v[168:171], v[192:195], v[56:59]
	v_mfma_f32_16x16x32_bf16 v[44:47], v[148:151], v[200:203], v[44:47]
	v_mfma_f32_16x16x32_bf16 v[40:43], v[168:171], v[200:203], v[40:43]
	v_mfma_f32_16x16x32_bf16 v[28:31], v[148:151], v[208:211], v[28:31]
	v_mfma_f32_16x16x32_bf16 v[24:27], v[168:171], v[208:211], v[24:27]
	v_mfma_f32_16x16x32_bf16 v[12:15], v[148:151], v[216:219], v[12:15]
	v_mfma_f32_16x16x32_bf16 v[8:11], v[168:171], v[216:219], v[8:11]
	v_mfma_f32_16x16x32_bf16 v[60:63], v[152:155], v[196:199], v[60:63]
	v_mfma_f32_16x16x32_bf16 v[56:59], v[172:175], v[196:199], v[56:59]
	v_mfma_f32_16x16x32_bf16 v[44:47], v[152:155], v[204:207], v[44:47]
	v_mfma_f32_16x16x32_bf16 v[40:43], v[172:175], v[204:207], v[40:43]
	v_mfma_f32_16x16x32_bf16 v[28:31], v[152:155], v[212:215], v[28:31]
	v_mfma_f32_16x16x32_bf16 v[24:27], v[172:175], v[212:215], v[24:27]
	v_mfma_f32_16x16x32_bf16 v[12:15], v[152:155], v[220:223], v[12:15]
	v_mfma_f32_16x16x32_bf16 v[8:11], v[172:175], v[220:223], v[8:11]
	v_mfma_f32_16x16x32_bf16 v[52:55], v[176:179], v[192:195], v[52:55]
	v_mfma_f32_16x16x32_bf16 v[48:51], v[184:187], v[192:195], v[48:51]
	v_mfma_f32_16x16x32_bf16 v[36:39], v[176:179], v[200:203], v[36:39]
	v_mfma_f32_16x16x32_bf16 v[32:35], v[184:187], v[200:203], v[32:35]
	v_mfma_f32_16x16x32_bf16 v[20:23], v[176:179], v[208:211], v[20:23]
	v_mfma_f32_16x16x32_bf16 v[16:19], v[184:187], v[208:211], v[16:19]
	v_mfma_f32_16x16x32_bf16 v[4:7], v[176:179], v[216:219], v[4:7]
	v_mfma_f32_16x16x32_bf16 v[0:3], v[184:187], v[216:219], v[0:3]
	v_mfma_f32_16x16x32_bf16 v[52:55], v[180:183], v[196:199], v[52:55]
	v_mfma_f32_16x16x32_bf16 v[48:51], v[188:191], v[196:199], v[48:51]
	v_mfma_f32_16x16x32_bf16 v[36:39], v[180:183], v[204:207], v[36:39]
	v_mfma_f32_16x16x32_bf16 v[32:35], v[188:191], v[204:207], v[32:35]
	v_mfma_f32_16x16x32_bf16 v[20:23], v[180:183], v[212:215], v[20:23]
	v_mfma_f32_16x16x32_bf16 v[16:19], v[188:191], v[212:215], v[16:19]
	v_mfma_f32_16x16x32_bf16 v[4:7], v[180:183], v[220:223], v[4:7]
	v_mfma_f32_16x16x32_bf16 v[0:3], v[188:191], v[220:223], v[0:3]
	s_setprio 0
	s_barrier
	s_add_i32 s8, 0, 0x18000
	v_add_u32_e32 v136, s8, v159
	s_add_i32 s9, 0, 0x1c000
	ds_read_b128 v[148:151], v136
	ds_read_b128 v[152:155], v136 offset:1024
	ds_read_b128 v[168:171], v136 offset:2048
	ds_read_b128 v[172:175], v136 offset:3072
	v_add_u32_e32 v136, s9, v159
	s_add_u32 s60, s74, 0x60000
	s_addc_u32 s61, s75, 0
	s_mov_b32 m0, s29
	v_lshl_add_u64 v[230:231], s[60:61], 0, v[128:129]
	global_load_lds_dwordx4 v[230:231], off
	v_lshl_add_u64 v[230:231], s[60:61], 0, v[132:133]
	s_mov_b32 m0, s30
	s_nop 0
	global_load_lds_dwordx4 v[230:231], off
	ds_read_b128 v[176:179], v136
	ds_read_b128 v[180:183], v136 offset:1024
	ds_read_b128 v[184:187], v136 offset:2048
	ds_read_b128 v[188:191], v136 offset:3072
	ds_read_b128 v[192:195], v165 offset:32768
	ds_read_b128 v[196:199], v165 offset:33792
	ds_read_b128 v[200:203], v165 offset:34816
	ds_read_b128 v[204:207], v165 offset:35840
	ds_read_b128 v[208:211], v165 offset:36864
	ds_read_b128 v[212:215], v165 offset:37888
	ds_read_b128 v[216:219], v165 offset:38912
	ds_read_b128 v[220:223], v165 offset:39936
	s_waitcnt vmcnt(8)
	s_waitcnt lgkmcnt(0)
	s_barrier
	s_setprio 1
	s_waitcnt lgkmcnt(0)
	v_mfma_f32_16x16x32_bf16 v[124:127], v[148:151], v[192:195], v[124:127]
	v_mfma_f32_16x16x32_bf16 v[120:123], v[168:171], v[192:195], v[120:123]
	v_mfma_f32_16x16x32_bf16 v[108:111], v[148:151], v[200:203], v[108:111]
	v_mfma_f32_16x16x32_bf16 v[104:107], v[168:171], v[200:203], v[104:107]
	v_mfma_f32_16x16x32_bf16 v[92:95], v[148:151], v[208:211], v[92:95]
	v_mfma_f32_16x16x32_bf16 v[88:91], v[168:171], v[208:211], v[88:91]
	v_mfma_f32_16x16x32_bf16 v[76:79], v[148:151], v[216:219], v[76:79]
	v_mfma_f32_16x16x32_bf16 v[72:75], v[168:171], v[216:219], v[72:75]
	v_mfma_f32_16x16x32_bf16 v[124:127], v[152:155], v[196:199], v[124:127]
	v_mfma_f32_16x16x32_bf16 v[120:123], v[172:175], v[196:199], v[120:123]
	v_mfma_f32_16x16x32_bf16 v[108:111], v[152:155], v[204:207], v[108:111]
	v_mfma_f32_16x16x32_bf16 v[104:107], v[172:175], v[204:207], v[104:107]
	v_mfma_f32_16x16x32_bf16 v[92:95], v[152:155], v[212:215], v[92:95]
	v_mfma_f32_16x16x32_bf16 v[88:91], v[172:175], v[212:215], v[88:91]
	v_mfma_f32_16x16x32_bf16 v[76:79], v[152:155], v[220:223], v[76:79]
	v_mfma_f32_16x16x32_bf16 v[72:75], v[172:175], v[220:223], v[72:75]
	v_mfma_f32_16x16x32_bf16 v[116:119], v[176:179], v[192:195], v[116:119]
	v_mfma_f32_16x16x32_bf16 v[112:115], v[184:187], v[192:195], v[112:115]
	v_mfma_f32_16x16x32_bf16 v[100:103], v[176:179], v[200:203], v[100:103]
	v_mfma_f32_16x16x32_bf16 v[96:99], v[184:187], v[200:203], v[96:99]
	v_mfma_f32_16x16x32_bf16 v[84:87], v[176:179], v[208:211], v[84:87]
	v_mfma_f32_16x16x32_bf16 v[80:83], v[184:187], v[208:211], v[80:83]
	v_mfma_f32_16x16x32_bf16 v[68:71], v[176:179], v[216:219], v[68:71]
	v_mfma_f32_16x16x32_bf16 v[64:67], v[184:187], v[216:219], v[64:67]
	v_mfma_f32_16x16x32_bf16 v[116:119], v[180:183], v[196:199], v[116:119]
	v_mfma_f32_16x16x32_bf16 v[112:115], v[188:191], v[196:199], v[112:115]
	v_mfma_f32_16x16x32_bf16 v[100:103], v[180:183], v[204:207], v[100:103]
	v_mfma_f32_16x16x32_bf16 v[96:99], v[188:191], v[204:207], v[96:99]
	v_mfma_f32_16x16x32_bf16 v[84:87], v[180:183], v[212:215], v[84:87]
	v_mfma_f32_16x16x32_bf16 v[80:83], v[188:191], v[212:215], v[80:83]
	v_mfma_f32_16x16x32_bf16 v[68:71], v[180:183], v[220:223], v[68:71]
	v_mfma_f32_16x16x32_bf16 v[64:67], v[188:191], v[220:223], v[64:67]
	s_setprio 0
	s_barrier
	s_add_i32 s8, s8, s94
	v_lshl_add_u64 v[156:157], v[156:157], 0, s[20:21]
	s_mov_b32 m0, s8
	s_nop 0
	global_load_lds_dwordx4 v[156:157], off
	s_add_i32 m0, s8, 0x2000
	s_add_u32 s60, s72, 0x30080
	v_lshl_add_u64 v[156:157], v[224:225], 0, s[20:21]
	s_addc_u32 s61, s73, 0
	s_add_i32 s8, s9, s94
	global_load_lds_dwordx4 v[156:157], off
	v_lshl_add_u64 v[156:157], s[60:61], 0, v[130:131]
	s_mov_b32 m0, s8
	s_nop 0
	global_load_lds_dwordx4 v[156:157], off
	v_lshl_add_u64 v[156:157], s[60:61], 0, v[134:135]
	s_add_i32 m0, s8, 0x2000
	s_nop 0
	global_load_lds_dwordx4 v[156:157], off
	v_lshl_add_u64 v[156:157], v[226:227], 0, s[20:21]
	s_mov_b32 m0, s46
	s_nop 0
	global_load_lds_dwordx4 v[156:157], off
	v_lshl_add_u64 v[156:157], v[228:229], 0, s[20:21]
	s_mov_b32 m0, s56
	s_nop 0
	global_load_lds_dwordx4 v[156:157], off
	ds_read_b128 v[192:195], v165 offset:49152
	ds_read_b128 v[196:199], v165 offset:50176
	ds_read_b128 v[200:203], v165 offset:51200
	ds_read_b128 v[204:207], v165 offset:52224
	ds_read_b128 v[208:211], v165 offset:53248
	ds_read_b128 v[212:215], v165 offset:54272
	ds_read_b128 v[216:219], v165 offset:55296
	ds_read_b128 v[220:223], v165 offset:56320
	s_waitcnt vmcnt(8)
	s_waitcnt lgkmcnt(0)
	s_barrier
	s_setprio 1
	s_waitcnt lgkmcnt(0)
	v_mfma_f32_16x16x32_bf16 v[60:63], v[148:151], v[192:195], v[60:63]
	v_mfma_f32_16x16x32_bf16 v[56:59], v[168:171], v[192:195], v[56:59]
	v_mfma_f32_16x16x32_bf16 v[44:47], v[148:151], v[200:203], v[44:47]
	v_mfma_f32_16x16x32_bf16 v[40:43], v[168:171], v[200:203], v[40:43]
	v_mfma_f32_16x16x32_bf16 v[28:31], v[148:151], v[208:211], v[28:31]
	v_mfma_f32_16x16x32_bf16 v[24:27], v[168:171], v[208:211], v[24:27]
	v_mfma_f32_16x16x32_bf16 v[12:15], v[148:151], v[216:219], v[12:15]
	v_mfma_f32_16x16x32_bf16 v[8:11], v[168:171], v[216:219], v[8:11]
	v_mfma_f32_16x16x32_bf16 v[60:63], v[152:155], v[196:199], v[60:63]
	v_mfma_f32_16x16x32_bf16 v[56:59], v[172:175], v[196:199], v[56:59]
	v_mfma_f32_16x16x32_bf16 v[44:47], v[152:155], v[204:207], v[44:47]
	v_mfma_f32_16x16x32_bf16 v[40:43], v[172:175], v[204:207], v[40:43]
	v_mfma_f32_16x16x32_bf16 v[28:31], v[152:155], v[212:215], v[28:31]
	v_mfma_f32_16x16x32_bf16 v[24:27], v[172:175], v[212:215], v[24:27]
	v_mfma_f32_16x16x32_bf16 v[12:15], v[152:155], v[220:223], v[12:15]
	v_mfma_f32_16x16x32_bf16 v[8:11], v[172:175], v[220:223], v[8:11]
	v_mfma_f32_16x16x32_bf16 v[52:55], v[176:179], v[192:195], v[52:55]
	v_mfma_f32_16x16x32_bf16 v[48:51], v[184:187], v[192:195], v[48:51]
	v_mfma_f32_16x16x32_bf16 v[36:39], v[176:179], v[200:203], v[36:39]
	v_mfma_f32_16x16x32_bf16 v[32:35], v[184:187], v[200:203], v[32:35]
	v_mfma_f32_16x16x32_bf16 v[20:23], v[176:179], v[208:211], v[20:23]
	v_mfma_f32_16x16x32_bf16 v[16:19], v[184:187], v[208:211], v[16:19]
	v_mfma_f32_16x16x32_bf16 v[4:7], v[176:179], v[216:219], v[4:7]
	v_mfma_f32_16x16x32_bf16 v[0:3], v[184:187], v[216:219], v[0:3]
	v_mfma_f32_16x16x32_bf16 v[52:55], v[180:183], v[196:199], v[52:55]
	v_mfma_f32_16x16x32_bf16 v[48:51], v[188:191], v[196:199], v[48:51]
	v_mfma_f32_16x16x32_bf16 v[36:39], v[180:183], v[204:207], v[36:39]
	v_mfma_f32_16x16x32_bf16 v[32:35], v[188:191], v[204:207], v[32:35]
	v_mfma_f32_16x16x32_bf16 v[20:23], v[180:183], v[212:215], v[20:23]
	v_mfma_f32_16x16x32_bf16 v[16:19], v[188:191], v[212:215], v[16:19]
	v_mfma_f32_16x16x32_bf16 v[4:7], v[180:183], v[220:223], v[4:7]
	v_mfma_f32_16x16x32_bf16 v[0:3], v[188:191], v[220:223], v[0:3]
	s_setprio 0
	s_barrier
	s_add_i32 s86, s86, 2
	s_add_u32 s84, s84, 0x100
	s_addc_u32 s85, s85, 0
	s_cmp_gt_u32 s86, 9
	s_mov_b64 s[70:71], s[16:17]
	s_cbranch_scc0 .LBB0_2459
	s_and_b64 vcc, exec, s[58:59]
	s_cbranch_vccz .LBB0_2462
	s_barrier

.LBB0_2535:
	s_add_u32 s16, s68, 0x100
	s_addc_u32 s17, s69, 0
	s_cmp_eq_u32 s80, 4
	s_cselect_b32 s73, s49, s17
	s_cselect_b32 s72, s48, s16
	s_cselect_b32 s71, s43, s79
	s_cselect_b32 s70, s77, s78
	v_lshl_add_u64 v[220:221], s[68:69], 0, v[138:139]
	s_add_i32 m0, s29, 0xc000
	s_nop 0
	global_load_lds_dwordx4 v[220:221], off
	v_lshl_add_u64 v[220:221], s[68:69], 0, v[140:141]
	s_add_i32 m0, s29, 0xe000
	s_nop 0
	global_load_lds_dwordx4 v[220:221], off
	ds_read_b128 v[146:149], v155
	ds_read_b128 v[160:163], v155 offset:1024
	ds_read_b128 v[164:167], v155 offset:2048
	ds_read_b128 v[168:171], v155 offset:3072
	ds_read_b128 v[172:175], v156
	ds_read_b128 v[176:179], v156 offset:1024
	ds_read_b128 v[180:183], v156 offset:2048
	ds_read_b128 v[184:187], v156 offset:3072
	ds_read_b128 v[188:191], v157
	ds_read_b128 v[192:195], v157 offset:1024
	ds_read_b128 v[196:199], v157 offset:2048
	ds_read_b128 v[200:203], v157 offset:3072
	ds_read_b128 v[204:207], v157 offset:4096
	ds_read_b128 v[208:211], v157 offset:5120
	ds_read_b128 v[212:215], v157 offset:6144
	ds_read_b128 v[216:219], v157 offset:7168
	s_waitcnt vmcnt(8)
	s_waitcnt lgkmcnt(0)
	s_barrier
	s_setprio 1
	s_waitcnt lgkmcnt(0)
	v_mfma_f32_16x16x32_bf16 v[124:127], v[146:149], v[188:191], v[124:127]
	v_mfma_f32_16x16x32_bf16 v[120:123], v[164:167], v[188:191], v[120:123]
	v_mfma_f32_16x16x32_bf16 v[108:111], v[146:149], v[196:199], v[108:111]
	v_mfma_f32_16x16x32_bf16 v[104:107], v[164:167], v[196:199], v[104:107]
	v_mfma_f32_16x16x32_bf16 v[92:95], v[146:149], v[204:207], v[92:95]
	v_mfma_f32_16x16x32_bf16 v[88:91], v[164:167], v[204:207], v[88:91]
	v_mfma_f32_16x16x32_bf16 v[76:79], v[146:149], v[212:215], v[76:79]
	v_mfma_f32_16x16x32_bf16 v[72:75], v[164:167], v[212:215], v[72:75]
	v_mfma_f32_16x16x32_bf16 v[124:127], v[160:163], v[192:195], v[124:127]
	v_mfma_f32_16x16x32_bf16 v[120:123], v[168:171], v[192:195], v[120:123]
	v_mfma_f32_16x16x32_bf16 v[108:111], v[160:163], v[200:203], v[108:111]
	v_mfma_f32_16x16x32_bf16 v[104:107], v[168:171], v[200:203], v[104:107]
	v_mfma_f32_16x16x32_bf16 v[92:95], v[160:163], v[208:211], v[92:95]
	v_mfma_f32_16x16x32_bf16 v[88:91], v[168:171], v[208:211], v[88:91]
	v_mfma_f32_16x16x32_bf16 v[76:79], v[160:163], v[216:219], v[76:79]
	v_mfma_f32_16x16x32_bf16 v[72:75], v[168:171], v[216:219], v[72:75]
	v_mfma_f32_16x16x32_bf16 v[116:119], v[172:175], v[188:191], v[116:119]
	v_mfma_f32_16x16x32_bf16 v[112:115], v[180:183], v[188:191], v[112:115]
	v_mfma_f32_16x16x32_bf16 v[100:103], v[172:175], v[196:199], v[100:103]
	v_mfma_f32_16x16x32_bf16 v[96:99], v[180:183], v[196:199], v[96:99]
	v_mfma_f32_16x16x32_bf16 v[84:87], v[172:175], v[204:207], v[84:87]
	v_mfma_f32_16x16x32_bf16 v[80:83], v[180:183], v[204:207], v[80:83]
	v_mfma_f32_16x16x32_bf16 v[68:71], v[172:175], v[212:215], v[68:71]
	v_mfma_f32_16x16x32_bf16 v[64:67], v[180:183], v[212:215], v[64:67]
	v_mfma_f32_16x16x32_bf16 v[116:119], v[176:179], v[192:195], v[116:119]
	v_mfma_f32_16x16x32_bf16 v[112:115], v[184:187], v[192:195], v[112:115]
	v_mfma_f32_16x16x32_bf16 v[100:103], v[176:179], v[200:203], v[100:103]
	v_mfma_f32_16x16x32_bf16 v[96:99], v[184:187], v[200:203], v[96:99]
	v_mfma_f32_16x16x32_bf16 v[84:87], v[176:179], v[208:211], v[84:87]
	v_mfma_f32_16x16x32_bf16 v[80:83], v[184:187], v[208:211], v[80:83]
	v_mfma_f32_16x16x32_bf16 v[68:71], v[176:179], v[216:219], v[68:71]
	v_mfma_f32_16x16x32_bf16 v[64:67], v[184:187], v[216:219], v[64:67]
	s_setprio 0
	s_barrier
	s_add_i32 s8, s67, s94
	v_lshl_add_u64 v[220:221], s[70:71], 0, v[130:131]
	s_mov_b32 m0, s8
	s_nop 0
	global_load_lds_dwordx4 v[220:221], off
	s_add_i32 m0, s8, 0x2000
	s_add_u32 s60, s70, 0x20000
	v_lshl_add_u64 v[222:223], s[70:71], 0, v[134:135]
	s_addc_u32 s61, s71, 0
	s_add_i32 s8, s74, s94
	global_load_lds_dwordx4 v[222:223], off
	v_lshl_add_u64 v[224:225], s[60:61], 0, v[130:131]
	s_mov_b32 m0, s8
	v_lshl_add_u64 v[226:227], s[72:73], 0, v[132:133]
	global_load_lds_dwordx4 v[224:225], off
	v_lshl_add_u64 v[224:225], s[60:61], 0, v[134:135]
	s_add_i32 m0, s8, 0x2000
	s_nop 0
	global_load_lds_dwordx4 v[224:225], off
	v_lshl_add_u64 v[224:225], s[72:73], 0, v[128:129]
	s_mov_b32 m0, s29
	s_nop 0
	global_load_lds_dwordx4 v[224:225], off
	s_mov_b32 m0, s30
	s_nop 0
	global_load_lds_dwordx4 v[226:227], off
	ds_read_b128 v[188:191], v157 offset:16384
	ds_read_b128 v[192:195], v157 offset:17408
	ds_read_b128 v[196:199], v157 offset:18432
	ds_read_b128 v[200:203], v157 offset:19456
	ds_read_b128 v[204:207], v157 offset:20480
	ds_read_b128 v[208:211], v157 offset:21504
	ds_read_b128 v[212:215], v157 offset:22528
	ds_read_b128 v[216:219], v157 offset:23552
	s_waitcnt vmcnt(8)
	s_waitcnt lgkmcnt(0)
	s_barrier
	s_setprio 1
	s_waitcnt lgkmcnt(0)
	v_mfma_f32_16x16x32_bf16 v[60:63], v[146:149], v[188:191], v[60:63]
	v_mfma_f32_16x16x32_bf16 v[56:59], v[164:167], v[188:191], v[56:59]
	v_mfma_f32_16x16x32_bf16 v[44:47], v[146:149], v[196:199], v[44:47]
	v_mfma_f32_16x16x32_bf16 v[40:43], v[164:167], v[196:199], v[40:43]
	v_mfma_f32_16x16x32_bf16 v[28:31], v[146:149], v[204:207], v[28:31]
	v_mfma_f32_16x16x32_bf16 v[24:27], v[164:167], v[204:207], v[24:27]
	v_mfma_f32_16x16x32_bf16 v[12:15], v[146:149], v[212:215], v[12:15]
	v_mfma_f32_16x16x32_bf16 v[8:11], v[164:167], v[212:215], v[8:11]
	v_mfma_f32_16x16x32_bf16 v[60:63], v[160:163], v[192:195], v[60:63]
	v_mfma_f32_16x16x32_bf16 v[56:59], v[168:171], v[192:195], v[56:59]
	v_mfma_f32_16x16x32_bf16 v[44:47], v[160:163], v[200:203], v[44:47]
	v_mfma_f32_16x16x32_bf16 v[40:43], v[168:171], v[200:203], v[40:43]
	v_mfma_f32_16x16x32_bf16 v[28:31], v[160:163], v[208:211], v[28:31]
	v_mfma_f32_16x16x32_bf16 v[24:27], v[168:171], v[208:211], v[24:27]
	v_mfma_f32_16x16x32_bf16 v[12:15], v[160:163], v[216:219], v[12:15]
	v_mfma_f32_16x16x32_bf16 v[8:11], v[168:171], v[216:219], v[8:11]
	v_mfma_f32_16x16x32_bf16 v[52:55], v[172:175], v[188:191], v[52:55]
	v_mfma_f32_16x16x32_bf16 v[48:51], v[180:183], v[188:191], v[48:51]
	v_mfma_f32_16x16x32_bf16 v[36:39], v[172:175], v[196:199], v[36:39]
	v_mfma_f32_16x16x32_bf16 v[32:35], v[180:183], v[196:199], v[32:35]
	v_mfma_f32_16x16x32_bf16 v[20:23], v[172:175], v[204:207], v[20:23]
	v_mfma_f32_16x16x32_bf16 v[16:19], v[180:183], v[204:207], v[16:19]
	v_mfma_f32_16x16x32_bf16 v[4:7], v[172:175], v[212:215], v[4:7]
	v_mfma_f32_16x16x32_bf16 v[0:3], v[180:183], v[212:215], v[0:3]
	v_mfma_f32_16x16x32_bf16 v[52:55], v[176:179], v[192:195], v[52:55]
	v_mfma_f32_16x16x32_bf16 v[48:51], v[184:187], v[192:195], v[48:51]
	v_mfma_f32_16x16x32_bf16 v[36:39], v[176:179], v[200:203], v[36:39]
	v_mfma_f32_16x16x32_bf16 v[32:35], v[184:187], v[200:203], v[32:35]
	v_mfma_f32_16x16x32_bf16 v[20:23], v[176:179], v[208:211], v[20:23]
	v_mfma_f32_16x16x32_bf16 v[16:19], v[184:187], v[208:211], v[16:19]
	v_mfma_f32_16x16x32_bf16 v[4:7], v[176:179], v[216:219], v[4:7]
	v_mfma_f32_16x16x32_bf16 v[0:3], v[184:187], v[216:219], v[0:3]
	s_setprio 0
	s_barrier
	s_add_i32 s8, 0, 0x18000
	v_add_u32_e32 v159, s8, v151
	s_add_i32 s9, 0, 0x1c000
	ds_read_b128 v[146:149], v159
	ds_read_b128 v[160:163], v159 offset:1024
	ds_read_b128 v[164:167], v159 offset:2048
	ds_read_b128 v[168:171], v159 offset:3072
	v_add_u32_e32 v159, s9, v151
	s_add_u32 s60, s72, 0x60000
	s_addc_u32 s61, s73, 0
	s_mov_b32 m0, s34
	v_lshl_add_u64 v[228:229], s[60:61], 0, v[128:129]
	global_load_lds_dwordx4 v[228:229], off
	v_lshl_add_u64 v[228:229], s[60:61], 0, v[132:133]
	s_mov_b32 m0, s35
	s_nop 0
	global_load_lds_dwordx4 v[228:229], off
	ds_read_b128 v[172:175], v159
	ds_read_b128 v[176:179], v159 offset:1024
	ds_read_b128 v[180:183], v159 offset:2048
	ds_read_b128 v[184:187], v159 offset:3072
	ds_read_b128 v[188:191], v157 offset:32768
	ds_read_b128 v[192:195], v157 offset:33792
	ds_read_b128 v[196:199], v157 offset:34816
	ds_read_b128 v[200:203], v157 offset:35840
	ds_read_b128 v[204:207], v157 offset:36864
	ds_read_b128 v[208:211], v157 offset:37888
	ds_read_b128 v[212:215], v157 offset:38912
	ds_read_b128 v[216:219], v157 offset:39936
	s_waitcnt vmcnt(8)
	s_waitcnt lgkmcnt(0)
	s_barrier
	s_setprio 1
	s_waitcnt lgkmcnt(0)
	v_mfma_f32_16x16x32_bf16 v[124:127], v[146:149], v[188:191], v[124:127]
	v_mfma_f32_16x16x32_bf16 v[120:123], v[164:167], v[188:191], v[120:123]
	v_mfma_f32_16x16x32_bf16 v[108:111], v[146:149], v[196:199], v[108:111]
	v_mfma_f32_16x16x32_bf16 v[104:107], v[164:167], v[196:199], v[104:107]
	v_mfma_f32_16x16x32_bf16 v[92:95], v[146:149], v[204:207], v[92:95]
	v_mfma_f32_16x16x32_bf16 v[88:91], v[164:167], v[204:207], v[88:91]
	v_mfma_f32_16x16x32_bf16 v[76:79], v[146:149], v[212:215], v[76:79]
	v_mfma_f32_16x16x32_bf16 v[72:75], v[164:167], v[212:215], v[72:75]
	v_mfma_f32_16x16x32_bf16 v[124:127], v[160:163], v[192:195], v[124:127]
	v_mfma_f32_16x16x32_bf16 v[120:123], v[168:171], v[192:195], v[120:123]
	v_mfma_f32_16x16x32_bf16 v[108:111], v[160:163], v[200:203], v[108:111]
	v_mfma_f32_16x16x32_bf16 v[104:107], v[168:171], v[200:203], v[104:107]
	v_mfma_f32_16x16x32_bf16 v[92:95], v[160:163], v[208:211], v[92:95]
	v_mfma_f32_16x16x32_bf16 v[88:91], v[168:171], v[208:211], v[88:91]
	v_mfma_f32_16x16x32_bf16 v[76:79], v[160:163], v[216:219], v[76:79]
	v_mfma_f32_16x16x32_bf16 v[72:75], v[168:171], v[216:219], v[72:75]
	v_mfma_f32_16x16x32_bf16 v[116:119], v[172:175], v[188:191], v[116:119]
	v_mfma_f32_16x16x32_bf16 v[112:115], v[180:183], v[188:191], v[112:115]
	v_mfma_f32_16x16x32_bf16 v[100:103], v[172:175], v[196:199], v[100:103]
	v_mfma_f32_16x16x32_bf16 v[96:99], v[180:183], v[196:199], v[96:99]
	v_mfma_f32_16x16x32_bf16 v[84:87], v[172:175], v[204:207], v[84:87]
	v_mfma_f32_16x16x32_bf16 v[80:83], v[180:183], v[204:207], v[80:83]
	v_mfma_f32_16x16x32_bf16 v[68:71], v[172:175], v[212:215], v[68:71]
	v_mfma_f32_16x16x32_bf16 v[64:67], v[180:183], v[212:215], v[64:67]
	v_mfma_f32_16x16x32_bf16 v[116:119], v[176:179], v[192:195], v[116:119]
	v_mfma_f32_16x16x32_bf16 v[112:115], v[184:187], v[192:195], v[112:115]
	v_mfma_f32_16x16x32_bf16 v[100:103], v[176:179], v[200:203], v[100:103]
	v_mfma_f32_16x16x32_bf16 v[96:99], v[184:187], v[200:203], v[96:99]
	v_mfma_f32_16x16x32_bf16 v[84:87], v[176:179], v[208:211], v[84:87]
	v_mfma_f32_16x16x32_bf16 v[80:83], v[184:187], v[208:211], v[80:83]
	v_mfma_f32_16x16x32_bf16 v[68:71], v[176:179], v[216:219], v[68:71]
	v_mfma_f32_16x16x32_bf16 v[64:67], v[184:187], v[216:219], v[64:67]
	s_setprio 0
	s_barrier
	s_add_i32 s8, s8, s94
	v_lshl_add_u64 v[220:221], v[220:221], 0, s[22:23]
	s_mov_b32 m0, s8
	s_nop 0
	global_load_lds_dwordx4 v[220:221], off
	s_add_i32 m0, s8, 0x2000
	s_add_u32 s60, s70, 0x20080
	v_lshl_add_u64 v[220:221], v[222:223], 0, s[22:23]
	s_addc_u32 s61, s71, 0
	s_add_i32 s8, s9, s94
	global_load_lds_dwordx4 v[220:221], off
	v_lshl_add_u64 v[220:221], s[60:61], 0, v[130:131]
	s_mov_b32 m0, s8
	s_nop 0
	global_load_lds_dwordx4 v[220:221], off
	v_lshl_add_u64 v[220:221], s[60:61], 0, v[134:135]
	s_add_i32 m0, s8, 0x2000
	s_nop 0
	global_load_lds_dwordx4 v[220:221], off
	v_lshl_add_u64 v[220:221], v[224:225], 0, s[22:23]
	s_mov_b32 m0, s56
	s_nop 0
	global_load_lds_dwordx4 v[220:221], off
	v_lshl_add_u64 v[220:221], v[226:227], 0, s[22:23]
	s_mov_b32 m0, s57
	s_nop 0
	global_load_lds_dwordx4 v[220:221], off
	ds_read_b128 v[188:191], v157 offset:49152
	ds_read_b128 v[192:195], v157 offset:50176
	ds_read_b128 v[196:199], v157 offset:51200
	ds_read_b128 v[200:203], v157 offset:52224
	ds_read_b128 v[204:207], v157 offset:53248
	ds_read_b128 v[208:211], v157 offset:54272
	ds_read_b128 v[212:215], v157 offset:55296
	ds_read_b128 v[216:219], v157 offset:56320
	s_waitcnt vmcnt(8)
	s_waitcnt lgkmcnt(0)
	s_barrier
	s_setprio 1
	s_waitcnt lgkmcnt(0)
	v_mfma_f32_16x16x32_bf16 v[60:63], v[146:149], v[188:191], v[60:63]
	v_mfma_f32_16x16x32_bf16 v[56:59], v[164:167], v[188:191], v[56:59]
	v_mfma_f32_16x16x32_bf16 v[44:47], v[146:149], v[196:199], v[44:47]
	v_mfma_f32_16x16x32_bf16 v[40:43], v[164:167], v[196:199], v[40:43]
	v_mfma_f32_16x16x32_bf16 v[28:31], v[146:149], v[204:207], v[28:31]
	v_mfma_f32_16x16x32_bf16 v[24:27], v[164:167], v[204:207], v[24:27]
	v_mfma_f32_16x16x32_bf16 v[12:15], v[146:149], v[212:215], v[12:15]
	v_mfma_f32_16x16x32_bf16 v[8:11], v[164:167], v[212:215], v[8:11]
	v_mfma_f32_16x16x32_bf16 v[60:63], v[160:163], v[192:195], v[60:63]
	v_mfma_f32_16x16x32_bf16 v[56:59], v[168:171], v[192:195], v[56:59]
	v_mfma_f32_16x16x32_bf16 v[44:47], v[160:163], v[200:203], v[44:47]
	v_mfma_f32_16x16x32_bf16 v[40:43], v[168:171], v[200:203], v[40:43]
	v_mfma_f32_16x16x32_bf16 v[28:31], v[160:163], v[208:211], v[28:31]
	v_mfma_f32_16x16x32_bf16 v[24:27], v[168:171], v[208:211], v[24:27]
	v_mfma_f32_16x16x32_bf16 v[12:15], v[160:163], v[216:219], v[12:15]
	v_mfma_f32_16x16x32_bf16 v[8:11], v[168:171], v[216:219], v[8:11]
	v_mfma_f32_16x16x32_bf16 v[52:55], v[172:175], v[188:191], v[52:55]
	v_mfma_f32_16x16x32_bf16 v[48:51], v[180:183], v[188:191], v[48:51]
	v_mfma_f32_16x16x32_bf16 v[36:39], v[172:175], v[196:199], v[36:39]
	v_mfma_f32_16x16x32_bf16 v[32:35], v[180:183], v[196:199], v[32:35]
	v_mfma_f32_16x16x32_bf16 v[20:23], v[172:175], v[204:207], v[20:23]
	v_mfma_f32_16x16x32_bf16 v[16:19], v[180:183], v[204:207], v[16:19]
	v_mfma_f32_16x16x32_bf16 v[4:7], v[172:175], v[212:215], v[4:7]
	v_mfma_f32_16x16x32_bf16 v[0:3], v[180:183], v[212:215], v[0:3]
	v_mfma_f32_16x16x32_bf16 v[52:55], v[176:179], v[192:195], v[52:55]
	v_mfma_f32_16x16x32_bf16 v[48:51], v[184:187], v[192:195], v[48:51]
	v_mfma_f32_16x16x32_bf16 v[36:39], v[176:179], v[200:203], v[36:39]
	v_mfma_f32_16x16x32_bf16 v[32:35], v[184:187], v[200:203], v[32:35]
	v_mfma_f32_16x16x32_bf16 v[20:23], v[176:179], v[208:211], v[20:23]
	v_mfma_f32_16x16x32_bf16 v[16:19], v[184:187], v[208:211], v[16:19]
	v_mfma_f32_16x16x32_bf16 v[4:7], v[176:179], v[216:219], v[4:7]
	v_mfma_f32_16x16x32_bf16 v[0:3], v[184:187], v[216:219], v[0:3]
	s_setprio 0
	s_barrier
	s_add_i32 s80, s80, 2
	s_add_u32 s78, s78, 0x100
	s_addc_u32 s79, s79, 0
	s_cmp_gt_u32 s80, 5
	s_mov_b64 s[68:69], s[16:17]
	s_cbranch_scc0 .LBB0_2535
	s_and_b64 vcc, exec, s[58:59]
	s_cbranch_vccz .LBB0_2538
	s_barrier

.LBB0_2713:
	s_add_u32 s8, s62, 0xfff80080
	s_addc_u32 s9, s63, -1
	s_cmp_eq_u32 s72, 28
	s_cselect_b32 s67, s43, s9
	s_cselect_b32 s66, s57, s8
	s_cselect_b32 s65, s23, s71
	s_cselect_b32 s64, s69, s70
	v_lshl_add_u64 v[212:213], s[62:63], 0, v[132:133]
	s_add_i32 m0, s12, 0xc000
	s_nop 0
	global_load_lds_dwordx4 v[212:213], off
	v_lshl_add_u64 v[212:213], s[62:63], 0, v[134:135]
	s_add_i32 m0, s12, 0xe000
	s_nop 0
	global_load_lds_dwordx4 v[212:213], off
	ds_read_b128 v[140:143], v149
	ds_read_b128 v[152:155], v149 offset:1024
	ds_read_b128 v[156:159], v149 offset:2048
	ds_read_b128 v[160:163], v149 offset:3072
	ds_read_b128 v[164:167], v150
	ds_read_b128 v[168:171], v150 offset:1024
	ds_read_b128 v[172:175], v150 offset:2048
	ds_read_b128 v[176:179], v150 offset:3072
	ds_read_b128 v[180:183], v151
	ds_read_b128 v[184:187], v151 offset:1024
	ds_read_b128 v[188:191], v151 offset:2048
	ds_read_b128 v[192:195], v151 offset:3072
	ds_read_b128 v[196:199], v151 offset:4096
	ds_read_b128 v[200:203], v151 offset:5120
	ds_read_b128 v[204:207], v151 offset:6144
	ds_read_b128 v[208:211], v151 offset:7168
	s_waitcnt vmcnt(8)
	s_waitcnt lgkmcnt(0)
	s_barrier
	s_setprio 1
	s_waitcnt lgkmcnt(0)
	v_mfma_f32_16x16x32_bf16 v[124:127], v[140:143], v[180:183], v[124:127]
	v_mfma_f32_16x16x32_bf16 v[120:123], v[156:159], v[180:183], v[120:123]
	v_mfma_f32_16x16x32_bf16 v[108:111], v[140:143], v[188:191], v[108:111]
	v_mfma_f32_16x16x32_bf16 v[104:107], v[156:159], v[188:191], v[104:107]
	v_mfma_f32_16x16x32_bf16 v[92:95], v[140:143], v[196:199], v[92:95]
	v_mfma_f32_16x16x32_bf16 v[88:91], v[156:159], v[196:199], v[88:91]
	v_mfma_f32_16x16x32_bf16 v[76:79], v[140:143], v[204:207], v[76:79]
	v_mfma_f32_16x16x32_bf16 v[72:75], v[156:159], v[204:207], v[72:75]
	v_mfma_f32_16x16x32_bf16 v[124:127], v[152:155], v[184:187], v[124:127]
	v_mfma_f32_16x16x32_bf16 v[120:123], v[160:163], v[184:187], v[120:123]
	v_mfma_f32_16x16x32_bf16 v[108:111], v[152:155], v[192:195], v[108:111]
	v_mfma_f32_16x16x32_bf16 v[104:107], v[160:163], v[192:195], v[104:107]
	v_mfma_f32_16x16x32_bf16 v[92:95], v[152:155], v[200:203], v[92:95]
	v_mfma_f32_16x16x32_bf16 v[88:91], v[160:163], v[200:203], v[88:91]
	v_mfma_f32_16x16x32_bf16 v[76:79], v[152:155], v[208:211], v[76:79]
	v_mfma_f32_16x16x32_bf16 v[72:75], v[160:163], v[208:211], v[72:75]
	v_mfma_f32_16x16x32_bf16 v[116:119], v[164:167], v[180:183], v[116:119]
	v_mfma_f32_16x16x32_bf16 v[112:115], v[172:175], v[180:183], v[112:115]
	v_mfma_f32_16x16x32_bf16 v[100:103], v[164:167], v[188:191], v[100:103]
	v_mfma_f32_16x16x32_bf16 v[96:99], v[172:175], v[188:191], v[96:99]
	v_mfma_f32_16x16x32_bf16 v[84:87], v[164:167], v[196:199], v[84:87]
	v_mfma_f32_16x16x32_bf16 v[80:83], v[172:175], v[196:199], v[80:83]
	v_mfma_f32_16x16x32_bf16 v[68:71], v[164:167], v[204:207], v[68:71]
	v_mfma_f32_16x16x32_bf16 v[64:67], v[172:175], v[204:207], v[64:67]
	v_mfma_f32_16x16x32_bf16 v[116:119], v[168:171], v[184:187], v[116:119]
	v_mfma_f32_16x16x32_bf16 v[112:115], v[176:179], v[184:187], v[112:115]
	v_mfma_f32_16x16x32_bf16 v[100:103], v[168:171], v[192:195], v[100:103]
	v_mfma_f32_16x16x32_bf16 v[96:99], v[176:179], v[192:195], v[96:99]
	v_mfma_f32_16x16x32_bf16 v[84:87], v[168:171], v[200:203], v[84:87]
	v_mfma_f32_16x16x32_bf16 v[80:83], v[176:179], v[200:203], v[80:83]
	v_mfma_f32_16x16x32_bf16 v[68:71], v[168:171], v[208:211], v[68:71]
	v_mfma_f32_16x16x32_bf16 v[64:67], v[176:179], v[208:211], v[64:67]
	s_setprio 0
	s_barrier
	s_add_i32 s8, s46, s94
	v_lshl_add_u64 v[212:213], s[64:65], 0, v[128:129]
	s_mov_b32 m0, s8
	s_nop 0
	global_load_lds_dwordx4 v[212:213], off
	s_add_i32 m0, s8, 0x2000
	s_add_u32 s60, s64, 0x80000
	v_lshl_add_u64 v[214:215], s[64:65], 0, v[130:131]
	s_addc_u32 s61, s65, 0
	s_add_i32 s8, s47, s94
	global_load_lds_dwordx4 v[214:215], off
	v_lshl_add_u64 v[216:217], s[60:61], 0, v[128:129]
	s_mov_b32 m0, s8
	v_lshl_add_u64 v[218:219], s[66:67], 0, v[130:131]
	global_load_lds_dwordx4 v[216:217], off
	v_lshl_add_u64 v[216:217], s[60:61], 0, v[130:131]
	s_add_i32 m0, s8, 0x2000
	s_nop 0
	global_load_lds_dwordx4 v[216:217], off
	v_lshl_add_u64 v[216:217], s[66:67], 0, v[128:129]
	s_mov_b32 m0, s12
	s_nop 0
	global_load_lds_dwordx4 v[216:217], off
	s_mov_b32 m0, s13
	s_nop 0
	global_load_lds_dwordx4 v[218:219], off
	ds_read_b128 v[180:183], v151 offset:16384
	ds_read_b128 v[184:187], v151 offset:17408
	ds_read_b128 v[188:191], v151 offset:18432
	ds_read_b128 v[192:195], v151 offset:19456
	ds_read_b128 v[196:199], v151 offset:20480
	ds_read_b128 v[200:203], v151 offset:21504
	ds_read_b128 v[204:207], v151 offset:22528
	ds_read_b128 v[208:211], v151 offset:23552
	s_waitcnt vmcnt(8)
	s_waitcnt lgkmcnt(0)
	s_barrier
	s_setprio 1
	s_waitcnt lgkmcnt(0)
	v_mfma_f32_16x16x32_bf16 v[60:63], v[140:143], v[180:183], v[60:63]
	v_mfma_f32_16x16x32_bf16 v[56:59], v[156:159], v[180:183], v[56:59]
	v_mfma_f32_16x16x32_bf16 v[44:47], v[140:143], v[188:191], v[44:47]
	v_mfma_f32_16x16x32_bf16 v[40:43], v[156:159], v[188:191], v[40:43]
	v_mfma_f32_16x16x32_bf16 v[28:31], v[140:143], v[196:199], v[28:31]
	v_mfma_f32_16x16x32_bf16 v[24:27], v[156:159], v[196:199], v[24:27]
	v_mfma_f32_16x16x32_bf16 v[12:15], v[140:143], v[204:207], v[12:15]
	v_mfma_f32_16x16x32_bf16 v[8:11], v[156:159], v[204:207], v[8:11]
	v_mfma_f32_16x16x32_bf16 v[60:63], v[152:155], v[184:187], v[60:63]
	v_mfma_f32_16x16x32_bf16 v[56:59], v[160:163], v[184:187], v[56:59]
	v_mfma_f32_16x16x32_bf16 v[44:47], v[152:155], v[192:195], v[44:47]
	v_mfma_f32_16x16x32_bf16 v[40:43], v[160:163], v[192:195], v[40:43]
	v_mfma_f32_16x16x32_bf16 v[28:31], v[152:155], v[200:203], v[28:31]
	v_mfma_f32_16x16x32_bf16 v[24:27], v[160:163], v[200:203], v[24:27]
	v_mfma_f32_16x16x32_bf16 v[12:15], v[152:155], v[208:211], v[12:15]
	v_mfma_f32_16x16x32_bf16 v[8:11], v[160:163], v[208:211], v[8:11]
	v_mfma_f32_16x16x32_bf16 v[52:55], v[164:167], v[180:183], v[52:55]
	v_mfma_f32_16x16x32_bf16 v[48:51], v[172:175], v[180:183], v[48:51]
	v_mfma_f32_16x16x32_bf16 v[36:39], v[164:167], v[188:191], v[36:39]
	v_mfma_f32_16x16x32_bf16 v[32:35], v[172:175], v[188:191], v[32:35]
	v_mfma_f32_16x16x32_bf16 v[20:23], v[164:167], v[196:199], v[20:23]
	v_mfma_f32_16x16x32_bf16 v[16:19], v[172:175], v[196:199], v[16:19]
	v_mfma_f32_16x16x32_bf16 v[4:7], v[164:167], v[204:207], v[4:7]
	v_mfma_f32_16x16x32_bf16 v[0:3], v[172:175], v[204:207], v[0:3]
	v_mfma_f32_16x16x32_bf16 v[52:55], v[168:171], v[184:187], v[52:55]
	v_mfma_f32_16x16x32_bf16 v[48:51], v[176:179], v[184:187], v[48:51]
	v_mfma_f32_16x16x32_bf16 v[36:39], v[168:171], v[192:195], v[36:39]
	v_mfma_f32_16x16x32_bf16 v[32:35], v[176:179], v[192:195], v[32:35]
	v_mfma_f32_16x16x32_bf16 v[20:23], v[168:171], v[200:203], v[20:23]
	v_mfma_f32_16x16x32_bf16 v[16:19], v[176:179], v[200:203], v[16:19]
	v_mfma_f32_16x16x32_bf16 v[4:7], v[168:171], v[208:211], v[4:7]
	v_mfma_f32_16x16x32_bf16 v[0:3], v[176:179], v[208:211], v[0:3]
	s_setprio 0
	s_barrier
	s_add_i32 s8, 0, 0x18000
	s_add_i32 s9, 0, 0x1c000
	v_add_u32_e32 v160, s8, v145
	v_add_u32_e32 v176, s9, v145
	s_add_u32 s60, s66, 0x80000
	s_addc_u32 s61, s67, 0
	s_mov_b32 m0, s29
	v_lshl_add_u64 v[220:221], s[60:61], 0, v[128:129]
	global_load_lds_dwordx4 v[220:221], off
	v_lshl_add_u64 v[220:221], s[60:61], 0, v[130:131]
	s_mov_b32 m0, s30
	s_nop 0
	global_load_lds_dwordx4 v[220:221], off
	ds_read_b128 v[140:143], v160
	ds_read_b128 v[152:155], v160 offset:1024
	ds_read_b128 v[156:159], v160 offset:2048
	ds_read_b128 v[160:163], v160 offset:3072
	ds_read_b128 v[164:167], v176
	ds_read_b128 v[168:171], v176 offset:1024
	ds_read_b128 v[172:175], v176 offset:2048
	ds_read_b128 v[176:179], v176 offset:3072
	ds_read_b128 v[180:183], v151 offset:32768
	ds_read_b128 v[184:187], v151 offset:33792
	ds_read_b128 v[188:191], v151 offset:34816
	ds_read_b128 v[192:195], v151 offset:35840
	ds_read_b128 v[196:199], v151 offset:36864
	ds_read_b128 v[200:203], v151 offset:37888
	ds_read_b128 v[204:207], v151 offset:38912
	ds_read_b128 v[208:211], v151 offset:39936
	s_waitcnt vmcnt(8)
	s_waitcnt lgkmcnt(0)
	s_barrier
	s_setprio 1
	s_waitcnt lgkmcnt(0)
	v_mfma_f32_16x16x32_bf16 v[124:127], v[140:143], v[180:183], v[124:127]
	v_mfma_f32_16x16x32_bf16 v[120:123], v[156:159], v[180:183], v[120:123]
	v_mfma_f32_16x16x32_bf16 v[108:111], v[140:143], v[188:191], v[108:111]
	v_mfma_f32_16x16x32_bf16 v[104:107], v[156:159], v[188:191], v[104:107]
	v_mfma_f32_16x16x32_bf16 v[92:95], v[140:143], v[196:199], v[92:95]
	v_mfma_f32_16x16x32_bf16 v[88:91], v[156:159], v[196:199], v[88:91]
	v_mfma_f32_16x16x32_bf16 v[76:79], v[140:143], v[204:207], v[76:79]
	v_mfma_f32_16x16x32_bf16 v[72:75], v[156:159], v[204:207], v[72:75]
	v_mfma_f32_16x16x32_bf16 v[124:127], v[152:155], v[184:187], v[124:127]
	v_mfma_f32_16x16x32_bf16 v[120:123], v[160:163], v[184:187], v[120:123]
	v_mfma_f32_16x16x32_bf16 v[108:111], v[152:155], v[192:195], v[108:111]
	v_mfma_f32_16x16x32_bf16 v[104:107], v[160:163], v[192:195], v[104:107]
	v_mfma_f32_16x16x32_bf16 v[92:95], v[152:155], v[200:203], v[92:95]
	v_mfma_f32_16x16x32_bf16 v[88:91], v[160:163], v[200:203], v[88:91]
	v_mfma_f32_16x16x32_bf16 v[76:79], v[152:155], v[208:211], v[76:79]
	v_mfma_f32_16x16x32_bf16 v[72:75], v[160:163], v[208:211], v[72:75]
	v_mfma_f32_16x16x32_bf16 v[116:119], v[164:167], v[180:183], v[116:119]
	v_mfma_f32_16x16x32_bf16 v[112:115], v[172:175], v[180:183], v[112:115]
	v_mfma_f32_16x16x32_bf16 v[100:103], v[164:167], v[188:191], v[100:103]
	v_mfma_f32_16x16x32_bf16 v[96:99], v[172:175], v[188:191], v[96:99]
	v_mfma_f32_16x16x32_bf16 v[84:87], v[164:167], v[196:199], v[84:87]
	v_mfma_f32_16x16x32_bf16 v[80:83], v[172:175], v[196:199], v[80:83]
	v_mfma_f32_16x16x32_bf16 v[68:71], v[164:167], v[204:207], v[68:71]
	v_mfma_f32_16x16x32_bf16 v[64:67], v[172:175], v[204:207], v[64:67]
	v_mfma_f32_16x16x32_bf16 v[116:119], v[168:171], v[184:187], v[116:119]
	v_mfma_f32_16x16x32_bf16 v[112:115], v[176:179], v[184:187], v[112:115]
	v_mfma_f32_16x16x32_bf16 v[100:103], v[168:171], v[192:195], v[100:103]
	v_mfma_f32_16x16x32_bf16 v[96:99], v[176:179], v[192:195], v[96:99]
	v_mfma_f32_16x16x32_bf16 v[84:87], v[168:171], v[200:203], v[84:87]
	v_mfma_f32_16x16x32_bf16 v[80:83], v[176:179], v[200:203], v[80:83]
	v_mfma_f32_16x16x32_bf16 v[68:71], v[168:171], v[208:211], v[68:71]
	v_mfma_f32_16x16x32_bf16 v[64:67], v[176:179], v[208:211], v[64:67]
	s_setprio 0
	s_barrier
	s_add_i32 s8, s8, s94
	v_lshl_add_u64 v[212:213], v[212:213], 0, s[20:21]
	s_mov_b32 m0, s8
	s_nop 0
	global_load_lds_dwordx4 v[212:213], off
	s_add_i32 m0, s8, 0x2000
	s_add_u32 s60, s64, 0x80080
	v_lshl_add_u64 v[212:213], v[214:215], 0, s[20:21]
	s_addc_u32 s61, s65, 0
	s_add_i32 s8, s9, s94
	global_load_lds_dwordx4 v[212:213], off
	v_lshl_add_u64 v[212:213], s[60:61], 0, v[128:129]
	s_mov_b32 m0, s8
	s_nop 0
	global_load_lds_dwordx4 v[212:213], off
	v_lshl_add_u64 v[212:213], s[60:61], 0, v[130:131]
	s_add_i32 m0, s8, 0x2000
	s_nop 0
	global_load_lds_dwordx4 v[212:213], off
	v_lshl_add_u64 v[212:213], v[216:217], 0, s[20:21]
	s_mov_b32 m0, s34
	s_nop 0
	global_load_lds_dwordx4 v[212:213], off
	v_lshl_add_u64 v[212:213], v[218:219], 0, s[20:21]
	s_mov_b32 m0, s35
	s_nop 0
	global_load_lds_dwordx4 v[212:213], off
	ds_read_b128 v[180:183], v151 offset:49152
	ds_read_b128 v[184:187], v151 offset:50176
	ds_read_b128 v[188:191], v151 offset:51200
	ds_read_b128 v[192:195], v151 offset:52224
	ds_read_b128 v[196:199], v151 offset:53248
	ds_read_b128 v[200:203], v151 offset:54272
	ds_read_b128 v[204:207], v151 offset:55296
	ds_read_b128 v[208:211], v151 offset:56320
	s_waitcnt vmcnt(8)
	s_waitcnt lgkmcnt(0)
	s_barrier
	s_setprio 1
	s_waitcnt lgkmcnt(0)
	v_mfma_f32_16x16x32_bf16 v[60:63], v[140:143], v[180:183], v[60:63]
	v_mfma_f32_16x16x32_bf16 v[56:59], v[156:159], v[180:183], v[56:59]
	v_mfma_f32_16x16x32_bf16 v[44:47], v[140:143], v[188:191], v[44:47]
	v_mfma_f32_16x16x32_bf16 v[40:43], v[156:159], v[188:191], v[40:43]
	v_mfma_f32_16x16x32_bf16 v[28:31], v[140:143], v[196:199], v[28:31]
	v_mfma_f32_16x16x32_bf16 v[24:27], v[156:159], v[196:199], v[24:27]
	v_mfma_f32_16x16x32_bf16 v[12:15], v[140:143], v[204:207], v[12:15]
	v_mfma_f32_16x16x32_bf16 v[8:11], v[156:159], v[204:207], v[8:11]
	v_mfma_f32_16x16x32_bf16 v[60:63], v[152:155], v[184:187], v[60:63]
	v_mfma_f32_16x16x32_bf16 v[56:59], v[160:163], v[184:187], v[56:59]
	v_mfma_f32_16x16x32_bf16 v[44:47], v[152:155], v[192:195], v[44:47]
	v_mfma_f32_16x16x32_bf16 v[40:43], v[160:163], v[192:195], v[40:43]
	v_mfma_f32_16x16x32_bf16 v[28:31], v[152:155], v[200:203], v[28:31]
	v_mfma_f32_16x16x32_bf16 v[24:27], v[160:163], v[200:203], v[24:27]
	v_mfma_f32_16x16x32_bf16 v[12:15], v[152:155], v[208:211], v[12:15]
	v_mfma_f32_16x16x32_bf16 v[8:11], v[160:163], v[208:211], v[8:11]
	v_mfma_f32_16x16x32_bf16 v[52:55], v[164:167], v[180:183], v[52:55]
	v_mfma_f32_16x16x32_bf16 v[48:51], v[172:175], v[180:183], v[48:51]
	v_mfma_f32_16x16x32_bf16 v[36:39], v[164:167], v[188:191], v[36:39]
	v_mfma_f32_16x16x32_bf16 v[32:35], v[172:175], v[188:191], v[32:35]
	v_mfma_f32_16x16x32_bf16 v[20:23], v[164:167], v[196:199], v[20:23]
	v_mfma_f32_16x16x32_bf16 v[16:19], v[172:175], v[196:199], v[16:19]
	v_mfma_f32_16x16x32_bf16 v[4:7], v[164:167], v[204:207], v[4:7]
	v_mfma_f32_16x16x32_bf16 v[0:3], v[172:175], v[204:207], v[0:3]
	v_mfma_f32_16x16x32_bf16 v[52:55], v[168:171], v[184:187], v[52:55]
	v_mfma_f32_16x16x32_bf16 v[48:51], v[176:179], v[184:187], v[48:51]
	v_mfma_f32_16x16x32_bf16 v[36:39], v[168:171], v[192:195], v[36:39]
	v_mfma_f32_16x16x32_bf16 v[32:35], v[176:179], v[192:195], v[32:35]
	v_mfma_f32_16x16x32_bf16 v[20:23], v[168:171], v[200:203], v[20:23]
	v_mfma_f32_16x16x32_bf16 v[16:19], v[176:179], v[200:203], v[16:19]
	v_mfma_f32_16x16x32_bf16 v[4:7], v[168:171], v[208:211], v[4:7]
	v_mfma_f32_16x16x32_bf16 v[0:3], v[176:179], v[208:211], v[0:3]
	s_setprio 0
	s_barrier
	s_add_i32 s72, s72, 2
	s_add_u32 s62, s62, 0x100
	s_addc_u32 s63, s63, 0
	s_add_u32 s70, s70, 0x100
	s_addc_u32 s71, s71, 0
	s_cmp_gt_u32 s72, 29
	s_cbranch_scc0 .LBB0_2713
	s_and_b64 vcc, exec, s[58:59]
	s_cbranch_vccz .LBB0_2716
	s_barrier

.LBB0_2805:
	s_add_u32 s8, s48, 0xfff80080
	s_addc_u32 s9, s49, -1
	s_cmp_eq_u32 s67, 28
	s_cselect_b32 s61, s21, s9
	s_cselect_b32 s60, s43, s8
	s_cselect_b32 s57, s19, s66
	s_cselect_b32 s56, s45, s65
	v_lshl_add_u64 v[220:221], s[48:49], 0, v[138:139]
	s_add_i32 m0, s29, 0xc000
	s_nop 0
	global_load_lds_dwordx4 v[220:221], off
	v_lshl_add_u64 v[220:221], s[48:49], 0, v[140:141]
	s_add_i32 m0, s29, 0xe000
	s_nop 0
	global_load_lds_dwordx4 v[220:221], off
	ds_read_b128 v[146:149], v155
	ds_read_b128 v[160:163], v155 offset:1024
	ds_read_b128 v[164:167], v155 offset:2048
	ds_read_b128 v[168:171], v155 offset:3072
	ds_read_b128 v[172:175], v156
	ds_read_b128 v[176:179], v156 offset:1024
	ds_read_b128 v[180:183], v156 offset:2048
	ds_read_b128 v[184:187], v156 offset:3072
	ds_read_b128 v[188:191], v157
	ds_read_b128 v[192:195], v157 offset:1024
	ds_read_b128 v[196:199], v157 offset:2048
	ds_read_b128 v[200:203], v157 offset:3072
	ds_read_b128 v[204:207], v157 offset:4096
	ds_read_b128 v[208:211], v157 offset:5120
	ds_read_b128 v[212:215], v157 offset:6144
	ds_read_b128 v[216:219], v157 offset:7168
	s_waitcnt vmcnt(8)
	s_waitcnt lgkmcnt(0)
	s_barrier
	s_setprio 1
	s_waitcnt lgkmcnt(0)
	v_mfma_f32_16x16x32_bf16 v[124:127], v[146:149], v[188:191], v[124:127]
	v_mfma_f32_16x16x32_bf16 v[120:123], v[164:167], v[188:191], v[120:123]
	v_mfma_f32_16x16x32_bf16 v[108:111], v[146:149], v[196:199], v[108:111]
	v_mfma_f32_16x16x32_bf16 v[104:107], v[164:167], v[196:199], v[104:107]
	v_mfma_f32_16x16x32_bf16 v[92:95], v[146:149], v[204:207], v[92:95]
	v_mfma_f32_16x16x32_bf16 v[88:91], v[164:167], v[204:207], v[88:91]
	v_mfma_f32_16x16x32_bf16 v[76:79], v[146:149], v[212:215], v[76:79]
	v_mfma_f32_16x16x32_bf16 v[72:75], v[164:167], v[212:215], v[72:75]
	v_mfma_f32_16x16x32_bf16 v[124:127], v[160:163], v[192:195], v[124:127]
	v_mfma_f32_16x16x32_bf16 v[120:123], v[168:171], v[192:195], v[120:123]
	v_mfma_f32_16x16x32_bf16 v[108:111], v[160:163], v[200:203], v[108:111]
	v_mfma_f32_16x16x32_bf16 v[104:107], v[168:171], v[200:203], v[104:107]
	v_mfma_f32_16x16x32_bf16 v[92:95], v[160:163], v[208:211], v[92:95]
	v_mfma_f32_16x16x32_bf16 v[88:91], v[168:171], v[208:211], v[88:91]
	v_mfma_f32_16x16x32_bf16 v[76:79], v[160:163], v[216:219], v[76:79]
	v_mfma_f32_16x16x32_bf16 v[72:75], v[168:171], v[216:219], v[72:75]
	v_mfma_f32_16x16x32_bf16 v[116:119], v[172:175], v[188:191], v[116:119]
	v_mfma_f32_16x16x32_bf16 v[112:115], v[180:183], v[188:191], v[112:115]
	v_mfma_f32_16x16x32_bf16 v[100:103], v[172:175], v[196:199], v[100:103]
	v_mfma_f32_16x16x32_bf16 v[96:99], v[180:183], v[196:199], v[96:99]
	v_mfma_f32_16x16x32_bf16 v[84:87], v[172:175], v[204:207], v[84:87]
	v_mfma_f32_16x16x32_bf16 v[80:83], v[180:183], v[204:207], v[80:83]
	v_mfma_f32_16x16x32_bf16 v[68:71], v[172:175], v[212:215], v[68:71]
	v_mfma_f32_16x16x32_bf16 v[64:67], v[180:183], v[212:215], v[64:67]
	v_mfma_f32_16x16x32_bf16 v[116:119], v[176:179], v[192:195], v[116:119]
	v_mfma_f32_16x16x32_bf16 v[112:115], v[184:187], v[192:195], v[112:115]
	v_mfma_f32_16x16x32_bf16 v[100:103], v[176:179], v[200:203], v[100:103]
	v_mfma_f32_16x16x32_bf16 v[96:99], v[184:187], v[200:203], v[96:99]
	v_mfma_f32_16x16x32_bf16 v[84:87], v[176:179], v[208:211], v[84:87]
	v_mfma_f32_16x16x32_bf16 v[80:83], v[184:187], v[208:211], v[80:83]
	v_mfma_f32_16x16x32_bf16 v[68:71], v[176:179], v[216:219], v[68:71]
	v_mfma_f32_16x16x32_bf16 v[64:67], v[184:187], v[216:219], v[64:67]
	s_setprio 0
	s_barrier
	s_add_i32 s8, s63, s94
	v_lshl_add_u64 v[220:221], s[56:57], 0, v[130:131]
	s_mov_b32 m0, s8
	s_nop 0
	global_load_lds_dwordx4 v[220:221], off
	s_add_i32 m0, s8, 0x2000
	s_add_u32 s68, s56, 0x80000
	v_lshl_add_u64 v[222:223], s[56:57], 0, v[134:135]
	s_addc_u32 s69, s57, 0
	s_add_i32 s8, s64, s94
	global_load_lds_dwordx4 v[222:223], off
	v_lshl_add_u64 v[224:225], s[68:69], 0, v[130:131]
	s_mov_b32 m0, s8
	v_lshl_add_u64 v[226:227], s[60:61], 0, v[132:133]
	global_load_lds_dwordx4 v[224:225], off
	v_lshl_add_u64 v[224:225], s[68:69], 0, v[134:135]
	s_add_i32 m0, s8, 0x2000
	s_nop 0
	global_load_lds_dwordx4 v[224:225], off
	v_lshl_add_u64 v[224:225], s[60:61], 0, v[128:129]
	s_mov_b32 m0, s29
	s_nop 0
	global_load_lds_dwordx4 v[224:225], off
	s_mov_b32 m0, s30
	s_nop 0
	global_load_lds_dwordx4 v[226:227], off
	ds_read_b128 v[188:191], v157 offset:16384
	ds_read_b128 v[192:195], v157 offset:17408
	ds_read_b128 v[196:199], v157 offset:18432
	ds_read_b128 v[200:203], v157 offset:19456
	ds_read_b128 v[204:207], v157 offset:20480
	ds_read_b128 v[208:211], v157 offset:21504
	ds_read_b128 v[212:215], v157 offset:22528
	ds_read_b128 v[216:219], v157 offset:23552
	s_waitcnt vmcnt(8)
	s_waitcnt lgkmcnt(0)
	s_barrier
	s_setprio 1
	s_waitcnt lgkmcnt(0)
	v_mfma_f32_16x16x32_bf16 v[60:63], v[146:149], v[188:191], v[60:63]
	v_mfma_f32_16x16x32_bf16 v[56:59], v[164:167], v[188:191], v[56:59]
	v_mfma_f32_16x16x32_bf16 v[44:47], v[146:149], v[196:199], v[44:47]
	v_mfma_f32_16x16x32_bf16 v[40:43], v[164:167], v[196:199], v[40:43]
	v_mfma_f32_16x16x32_bf16 v[28:31], v[146:149], v[204:207], v[28:31]
	v_mfma_f32_16x16x32_bf16 v[24:27], v[164:167], v[204:207], v[24:27]
	v_mfma_f32_16x16x32_bf16 v[12:15], v[146:149], v[212:215], v[12:15]
	v_mfma_f32_16x16x32_bf16 v[8:11], v[164:167], v[212:215], v[8:11]
	v_mfma_f32_16x16x32_bf16 v[60:63], v[160:163], v[192:195], v[60:63]
	v_mfma_f32_16x16x32_bf16 v[56:59], v[168:171], v[192:195], v[56:59]
	v_mfma_f32_16x16x32_bf16 v[44:47], v[160:163], v[200:203], v[44:47]
	v_mfma_f32_16x16x32_bf16 v[40:43], v[168:171], v[200:203], v[40:43]
	v_mfma_f32_16x16x32_bf16 v[28:31], v[160:163], v[208:211], v[28:31]
	v_mfma_f32_16x16x32_bf16 v[24:27], v[168:171], v[208:211], v[24:27]
	v_mfma_f32_16x16x32_bf16 v[12:15], v[160:163], v[216:219], v[12:15]
	v_mfma_f32_16x16x32_bf16 v[8:11], v[168:171], v[216:219], v[8:11]
	v_mfma_f32_16x16x32_bf16 v[52:55], v[172:175], v[188:191], v[52:55]
	v_mfma_f32_16x16x32_bf16 v[48:51], v[180:183], v[188:191], v[48:51]
	v_mfma_f32_16x16x32_bf16 v[36:39], v[172:175], v[196:199], v[36:39]
	v_mfma_f32_16x16x32_bf16 v[32:35], v[180:183], v[196:199], v[32:35]
	v_mfma_f32_16x16x32_bf16 v[20:23], v[172:175], v[204:207], v[20:23]
	v_mfma_f32_16x16x32_bf16 v[16:19], v[180:183], v[204:207], v[16:19]
	v_mfma_f32_16x16x32_bf16 v[4:7], v[172:175], v[212:215], v[4:7]
	v_mfma_f32_16x16x32_bf16 v[0:3], v[180:183], v[212:215], v[0:3]
	v_mfma_f32_16x16x32_bf16 v[52:55], v[176:179], v[192:195], v[52:55]
	v_mfma_f32_16x16x32_bf16 v[48:51], v[184:187], v[192:195], v[48:51]
	v_mfma_f32_16x16x32_bf16 v[36:39], v[176:179], v[200:203], v[36:39]
	v_mfma_f32_16x16x32_bf16 v[32:35], v[184:187], v[200:203], v[32:35]
	v_mfma_f32_16x16x32_bf16 v[20:23], v[176:179], v[208:211], v[20:23]
	v_mfma_f32_16x16x32_bf16 v[16:19], v[184:187], v[208:211], v[16:19]
	v_mfma_f32_16x16x32_bf16 v[4:7], v[176:179], v[216:219], v[4:7]
	v_mfma_f32_16x16x32_bf16 v[0:3], v[184:187], v[216:219], v[0:3]
	s_setprio 0
	s_barrier
	s_add_i32 s8, 0, 0x18000
	v_add_u32_e32 v159, s8, v151
	s_add_i32 s9, 0, 0x1c000
	ds_read_b128 v[146:149], v159
	ds_read_b128 v[160:163], v159 offset:1024
	ds_read_b128 v[164:167], v159 offset:2048
	ds_read_b128 v[168:171], v159 offset:3072
	v_add_u32_e32 v159, s9, v151
	s_add_u32 s60, s60, 0x80000
	s_addc_u32 s61, s61, 0
	s_mov_b32 m0, s34
	v_lshl_add_u64 v[228:229], s[60:61], 0, v[128:129]
	global_load_lds_dwordx4 v[228:229], off
	v_lshl_add_u64 v[228:229], s[60:61], 0, v[132:133]
	s_mov_b32 m0, s35
	s_nop 0
	global_load_lds_dwordx4 v[228:229], off
	ds_read_b128 v[172:175], v159
	ds_read_b128 v[176:179], v159 offset:1024
	ds_read_b128 v[180:183], v159 offset:2048
	ds_read_b128 v[184:187], v159 offset:3072
	ds_read_b128 v[188:191], v157 offset:32768
	ds_read_b128 v[192:195], v157 offset:33792
	ds_read_b128 v[196:199], v157 offset:34816
	ds_read_b128 v[200:203], v157 offset:35840
	ds_read_b128 v[204:207], v157 offset:36864
	ds_read_b128 v[208:211], v157 offset:37888
	ds_read_b128 v[212:215], v157 offset:38912
	ds_read_b128 v[216:219], v157 offset:39936
	s_waitcnt vmcnt(8)
	s_waitcnt lgkmcnt(0)
	s_barrier
	s_setprio 1
	s_waitcnt lgkmcnt(0)
	v_mfma_f32_16x16x32_bf16 v[124:127], v[146:149], v[188:191], v[124:127]
	v_mfma_f32_16x16x32_bf16 v[120:123], v[164:167], v[188:191], v[120:123]
	v_mfma_f32_16x16x32_bf16 v[108:111], v[146:149], v[196:199], v[108:111]
	v_mfma_f32_16x16x32_bf16 v[104:107], v[164:167], v[196:199], v[104:107]
	v_mfma_f32_16x16x32_bf16 v[92:95], v[146:149], v[204:207], v[92:95]
	v_mfma_f32_16x16x32_bf16 v[88:91], v[164:167], v[204:207], v[88:91]
	v_mfma_f32_16x16x32_bf16 v[76:79], v[146:149], v[212:215], v[76:79]
	v_mfma_f32_16x16x32_bf16 v[72:75], v[164:167], v[212:215], v[72:75]
	v_mfma_f32_16x16x32_bf16 v[124:127], v[160:163], v[192:195], v[124:127]
	v_mfma_f32_16x16x32_bf16 v[120:123], v[168:171], v[192:195], v[120:123]
	v_mfma_f32_16x16x32_bf16 v[108:111], v[160:163], v[200:203], v[108:111]
	v_mfma_f32_16x16x32_bf16 v[104:107], v[168:171], v[200:203], v[104:107]
	v_mfma_f32_16x16x32_bf16 v[92:95], v[160:163], v[208:211], v[92:95]
	v_mfma_f32_16x16x32_bf16 v[88:91], v[168:171], v[208:211], v[88:91]
	v_mfma_f32_16x16x32_bf16 v[76:79], v[160:163], v[216:219], v[76:79]
	v_mfma_f32_16x16x32_bf16 v[72:75], v[168:171], v[216:219], v[72:75]
	v_mfma_f32_16x16x32_bf16 v[116:119], v[172:175], v[188:191], v[116:119]
	v_mfma_f32_16x16x32_bf16 v[112:115], v[180:183], v[188:191], v[112:115]
	v_mfma_f32_16x16x32_bf16 v[100:103], v[172:175], v[196:199], v[100:103]
	v_mfma_f32_16x16x32_bf16 v[96:99], v[180:183], v[196:199], v[96:99]
	v_mfma_f32_16x16x32_bf16 v[84:87], v[172:175], v[204:207], v[84:87]
	v_mfma_f32_16x16x32_bf16 v[80:83], v[180:183], v[204:207], v[80:83]
	v_mfma_f32_16x16x32_bf16 v[68:71], v[172:175], v[212:215], v[68:71]
	v_mfma_f32_16x16x32_bf16 v[64:67], v[180:183], v[212:215], v[64:67]
	v_mfma_f32_16x16x32_bf16 v[116:119], v[176:179], v[192:195], v[116:119]
	v_mfma_f32_16x16x32_bf16 v[112:115], v[184:187], v[192:195], v[112:115]
	v_mfma_f32_16x16x32_bf16 v[100:103], v[176:179], v[200:203], v[100:103]
	v_mfma_f32_16x16x32_bf16 v[96:99], v[184:187], v[200:203], v[96:99]
	v_mfma_f32_16x16x32_bf16 v[84:87], v[176:179], v[208:211], v[84:87]
	v_mfma_f32_16x16x32_bf16 v[80:83], v[184:187], v[208:211], v[80:83]
	v_mfma_f32_16x16x32_bf16 v[68:71], v[176:179], v[216:219], v[68:71]
	v_mfma_f32_16x16x32_bf16 v[64:67], v[184:187], v[216:219], v[64:67]
	s_setprio 0
	s_barrier
	s_add_i32 s8, s8, s94
	v_lshl_add_u64 v[220:221], v[220:221], 0, s[16:17]
	s_mov_b32 m0, s8
	s_nop 0
	global_load_lds_dwordx4 v[220:221], off
	s_add_i32 m0, s8, 0x2000
	s_add_u32 s56, s56, 0x80080
	v_lshl_add_u64 v[220:221], v[222:223], 0, s[16:17]
	s_addc_u32 s57, s57, 0
	s_add_i32 s8, s9, s94
	global_load_lds_dwordx4 v[220:221], off
	v_lshl_add_u64 v[220:221], s[56:57], 0, v[130:131]
	s_mov_b32 m0, s8
	s_nop 0
	global_load_lds_dwordx4 v[220:221], off
	v_lshl_add_u64 v[220:221], s[56:57], 0, v[134:135]
	s_add_i32 m0, s8, 0x2000
	s_nop 0
	global_load_lds_dwordx4 v[220:221], off
	v_lshl_add_u64 v[220:221], v[224:225], 0, s[16:17]
	s_mov_b32 m0, s47
	s_nop 0
	global_load_lds_dwordx4 v[220:221], off
	v_lshl_add_u64 v[220:221], v[226:227], 0, s[16:17]
	s_mov_b32 m0, s62
	s_nop 0
	global_load_lds_dwordx4 v[220:221], off
	ds_read_b128 v[188:191], v157 offset:49152
	ds_read_b128 v[192:195], v157 offset:50176
	ds_read_b128 v[196:199], v157 offset:51200
	ds_read_b128 v[200:203], v157 offset:52224
	ds_read_b128 v[204:207], v157 offset:53248
	ds_read_b128 v[208:211], v157 offset:54272
	ds_read_b128 v[212:215], v157 offset:55296
	ds_read_b128 v[216:219], v157 offset:56320
	s_waitcnt vmcnt(8)
	s_waitcnt lgkmcnt(0)
	s_barrier
	s_setprio 1
	s_waitcnt lgkmcnt(0)
	v_mfma_f32_16x16x32_bf16 v[60:63], v[146:149], v[188:191], v[60:63]
	v_mfma_f32_16x16x32_bf16 v[56:59], v[164:167], v[188:191], v[56:59]
	v_mfma_f32_16x16x32_bf16 v[44:47], v[146:149], v[196:199], v[44:47]
	v_mfma_f32_16x16x32_bf16 v[40:43], v[164:167], v[196:199], v[40:43]
	v_mfma_f32_16x16x32_bf16 v[28:31], v[146:149], v[204:207], v[28:31]
	v_mfma_f32_16x16x32_bf16 v[24:27], v[164:167], v[204:207], v[24:27]
	v_mfma_f32_16x16x32_bf16 v[12:15], v[146:149], v[212:215], v[12:15]
	v_mfma_f32_16x16x32_bf16 v[8:11], v[164:167], v[212:215], v[8:11]
	v_mfma_f32_16x16x32_bf16 v[60:63], v[160:163], v[192:195], v[60:63]
	v_mfma_f32_16x16x32_bf16 v[56:59], v[168:171], v[192:195], v[56:59]
	v_mfma_f32_16x16x32_bf16 v[44:47], v[160:163], v[200:203], v[44:47]
	v_mfma_f32_16x16x32_bf16 v[40:43], v[168:171], v[200:203], v[40:43]
	v_mfma_f32_16x16x32_bf16 v[28:31], v[160:163], v[208:211], v[28:31]
	v_mfma_f32_16x16x32_bf16 v[24:27], v[168:171], v[208:211], v[24:27]
	v_mfma_f32_16x16x32_bf16 v[12:15], v[160:163], v[216:219], v[12:15]
	v_mfma_f32_16x16x32_bf16 v[8:11], v[168:171], v[216:219], v[8:11]
	v_mfma_f32_16x16x32_bf16 v[52:55], v[172:175], v[188:191], v[52:55]
	v_mfma_f32_16x16x32_bf16 v[48:51], v[180:183], v[188:191], v[48:51]
	v_mfma_f32_16x16x32_bf16 v[36:39], v[172:175], v[196:199], v[36:39]
	v_mfma_f32_16x16x32_bf16 v[32:35], v[180:183], v[196:199], v[32:35]
	v_mfma_f32_16x16x32_bf16 v[20:23], v[172:175], v[204:207], v[20:23]
	v_mfma_f32_16x16x32_bf16 v[16:19], v[180:183], v[204:207], v[16:19]
	v_mfma_f32_16x16x32_bf16 v[4:7], v[172:175], v[212:215], v[4:7]
	v_mfma_f32_16x16x32_bf16 v[0:3], v[180:183], v[212:215], v[0:3]
	v_mfma_f32_16x16x32_bf16 v[52:55], v[176:179], v[192:195], v[52:55]
	v_mfma_f32_16x16x32_bf16 v[48:51], v[184:187], v[192:195], v[48:51]
	v_mfma_f32_16x16x32_bf16 v[36:39], v[176:179], v[200:203], v[36:39]
	v_mfma_f32_16x16x32_bf16 v[32:35], v[184:187], v[200:203], v[32:35]
	v_mfma_f32_16x16x32_bf16 v[20:23], v[176:179], v[208:211], v[20:23]
	v_mfma_f32_16x16x32_bf16 v[16:19], v[184:187], v[208:211], v[16:19]
	v_mfma_f32_16x16x32_bf16 v[4:7], v[176:179], v[216:219], v[4:7]
	v_mfma_f32_16x16x32_bf16 v[0:3], v[184:187], v[216:219], v[0:3]
	s_setprio 0
	s_barrier
	s_add_i32 s67, s67, 2
	s_add_u32 s48, s48, 0x100
	s_addc_u32 s49, s49, 0
	s_add_u32 s65, s65, 0x100
	s_addc_u32 s66, s66, 0
	s_cmp_gt_u32 s67, 29
	s_cbranch_scc0 .LBB0_2805
	s_and_b64 vcc, exec, s[58:59]
	s_cbranch_vccz .LBB0_2808
	s_barrier

.LBB0_2917:
	s_add_u32 s42, s40, 0xffe00080
	s_addc_u32 s43, s41, -1
	s_cmpk_eq_i32 s64, 0x7c
	s_cselect_b32 s45, s21, s43
	s_cselect_b32 s44, s39, s42
	s_cselect_b32 s43, s19, s63
	s_cselect_b32 s42, s61, s62
	v_lshl_add_u64 v[212:213], s[40:41], 0, v[132:133]
	s_add_i32 m0, s29, 0xc000
	s_nop 0
	global_load_lds_dwordx4 v[212:213], off
	v_lshl_add_u64 v[212:213], s[40:41], 0, v[134:135]
	s_add_i32 m0, s29, 0xe000
	s_nop 0
	global_load_lds_dwordx4 v[212:213], off
	ds_read_b128 v[140:143], v149
	ds_read_b128 v[152:155], v149 offset:1024
	ds_read_b128 v[156:159], v149 offset:2048
	ds_read_b128 v[160:163], v149 offset:3072
	ds_read_b128 v[164:167], v150
	ds_read_b128 v[168:171], v150 offset:1024
	ds_read_b128 v[172:175], v150 offset:2048
	ds_read_b128 v[176:179], v150 offset:3072
	ds_read_b128 v[180:183], v151
	ds_read_b128 v[184:187], v151 offset:1024
	ds_read_b128 v[188:191], v151 offset:2048
	ds_read_b128 v[192:195], v151 offset:3072
	ds_read_b128 v[196:199], v151 offset:4096
	ds_read_b128 v[200:203], v151 offset:5120
	ds_read_b128 v[204:207], v151 offset:6144
	ds_read_b128 v[208:211], v151 offset:7168
	s_waitcnt vmcnt(8)
	s_waitcnt lgkmcnt(0)
	s_barrier
	s_setprio 1
	s_waitcnt lgkmcnt(0)
	v_mfma_f32_16x16x32_bf16 v[124:127], v[140:143], v[180:183], v[124:127]
	v_mfma_f32_16x16x32_bf16 v[120:123], v[156:159], v[180:183], v[120:123]
	v_mfma_f32_16x16x32_bf16 v[108:111], v[140:143], v[188:191], v[108:111]
	v_mfma_f32_16x16x32_bf16 v[104:107], v[156:159], v[188:191], v[104:107]
	v_mfma_f32_16x16x32_bf16 v[92:95], v[140:143], v[196:199], v[92:95]
	v_mfma_f32_16x16x32_bf16 v[88:91], v[156:159], v[196:199], v[88:91]
	v_mfma_f32_16x16x32_bf16 v[76:79], v[140:143], v[204:207], v[76:79]
	v_mfma_f32_16x16x32_bf16 v[72:75], v[156:159], v[204:207], v[72:75]
	v_mfma_f32_16x16x32_bf16 v[124:127], v[152:155], v[184:187], v[124:127]
	v_mfma_f32_16x16x32_bf16 v[120:123], v[160:163], v[184:187], v[120:123]
	v_mfma_f32_16x16x32_bf16 v[108:111], v[152:155], v[192:195], v[108:111]
	v_mfma_f32_16x16x32_bf16 v[104:107], v[160:163], v[192:195], v[104:107]
	v_mfma_f32_16x16x32_bf16 v[92:95], v[152:155], v[200:203], v[92:95]
	v_mfma_f32_16x16x32_bf16 v[88:91], v[160:163], v[200:203], v[88:91]
	v_mfma_f32_16x16x32_bf16 v[76:79], v[152:155], v[208:211], v[76:79]
	v_mfma_f32_16x16x32_bf16 v[72:75], v[160:163], v[208:211], v[72:75]
	v_mfma_f32_16x16x32_bf16 v[116:119], v[164:167], v[180:183], v[116:119]
	v_mfma_f32_16x16x32_bf16 v[112:115], v[172:175], v[180:183], v[112:115]
	v_mfma_f32_16x16x32_bf16 v[100:103], v[164:167], v[188:191], v[100:103]
	v_mfma_f32_16x16x32_bf16 v[96:99], v[172:175], v[188:191], v[96:99]
	v_mfma_f32_16x16x32_bf16 v[84:87], v[164:167], v[196:199], v[84:87]
	v_mfma_f32_16x16x32_bf16 v[80:83], v[172:175], v[196:199], v[80:83]
	v_mfma_f32_16x16x32_bf16 v[68:71], v[164:167], v[204:207], v[68:71]
	v_mfma_f32_16x16x32_bf16 v[64:67], v[172:175], v[204:207], v[64:67]
	v_mfma_f32_16x16x32_bf16 v[116:119], v[168:171], v[184:187], v[116:119]
	v_mfma_f32_16x16x32_bf16 v[112:115], v[176:179], v[184:187], v[112:115]
	v_mfma_f32_16x16x32_bf16 v[100:103], v[168:171], v[192:195], v[100:103]
	v_mfma_f32_16x16x32_bf16 v[96:99], v[176:179], v[192:195], v[96:99]
	v_mfma_f32_16x16x32_bf16 v[84:87], v[168:171], v[200:203], v[84:87]
	v_mfma_f32_16x16x32_bf16 v[80:83], v[176:179], v[200:203], v[80:83]
	v_mfma_f32_16x16x32_bf16 v[68:71], v[168:171], v[208:211], v[68:71]
	v_mfma_f32_16x16x32_bf16 v[64:67], v[176:179], v[208:211], v[64:67]
	s_setprio 0
	s_barrier
	s_add_i32 s65, s56, s94
	v_lshl_add_u64 v[212:213], s[42:43], 0, v[128:129]
	s_mov_b32 m0, s65
	s_nop 0
	global_load_lds_dwordx4 v[212:213], off
	s_add_i32 m0, s65, 0x2000
	s_add_u32 s66, s42, 0x200000
	v_lshl_add_u64 v[214:215], s[42:43], 0, v[130:131]
	s_addc_u32 s67, s43, 0
	s_add_i32 s65, s57, s94
	global_load_lds_dwordx4 v[214:215], off
	v_lshl_add_u64 v[216:217], s[66:67], 0, v[128:129]
	s_mov_b32 m0, s65
	v_lshl_add_u64 v[218:219], s[44:45], 0, v[130:131]
	global_load_lds_dwordx4 v[216:217], off
	v_lshl_add_u64 v[216:217], s[66:67], 0, v[130:131]
	s_add_i32 m0, s65, 0x2000
	s_nop 0
	global_load_lds_dwordx4 v[216:217], off
	v_lshl_add_u64 v[216:217], s[44:45], 0, v[128:129]
	s_mov_b32 m0, s29
	s_nop 0
	global_load_lds_dwordx4 v[216:217], off
	s_mov_b32 m0, s30
	s_nop 0
	global_load_lds_dwordx4 v[218:219], off
	ds_read_b128 v[180:183], v151 offset:16384
	ds_read_b128 v[184:187], v151 offset:17408
	ds_read_b128 v[188:191], v151 offset:18432
	ds_read_b128 v[192:195], v151 offset:19456
	ds_read_b128 v[196:199], v151 offset:20480
	ds_read_b128 v[200:203], v151 offset:21504
	ds_read_b128 v[204:207], v151 offset:22528
	ds_read_b128 v[208:211], v151 offset:23552
	s_waitcnt vmcnt(8)
	s_waitcnt lgkmcnt(0)
	s_barrier
	s_setprio 1
	s_waitcnt lgkmcnt(0)
	v_mfma_f32_16x16x32_bf16 v[60:63], v[140:143], v[180:183], v[60:63]
	v_mfma_f32_16x16x32_bf16 v[56:59], v[156:159], v[180:183], v[56:59]
	v_mfma_f32_16x16x32_bf16 v[44:47], v[140:143], v[188:191], v[44:47]
	v_mfma_f32_16x16x32_bf16 v[40:43], v[156:159], v[188:191], v[40:43]
	v_mfma_f32_16x16x32_bf16 v[28:31], v[140:143], v[196:199], v[28:31]
	v_mfma_f32_16x16x32_bf16 v[24:27], v[156:159], v[196:199], v[24:27]
	v_mfma_f32_16x16x32_bf16 v[12:15], v[140:143], v[204:207], v[12:15]
	v_mfma_f32_16x16x32_bf16 v[8:11], v[156:159], v[204:207], v[8:11]
	v_mfma_f32_16x16x32_bf16 v[60:63], v[152:155], v[184:187], v[60:63]
	v_mfma_f32_16x16x32_bf16 v[56:59], v[160:163], v[184:187], v[56:59]
	v_mfma_f32_16x16x32_bf16 v[44:47], v[152:155], v[192:195], v[44:47]
	v_mfma_f32_16x16x32_bf16 v[40:43], v[160:163], v[192:195], v[40:43]
	v_mfma_f32_16x16x32_bf16 v[28:31], v[152:155], v[200:203], v[28:31]
	v_mfma_f32_16x16x32_bf16 v[24:27], v[160:163], v[200:203], v[24:27]
	v_mfma_f32_16x16x32_bf16 v[12:15], v[152:155], v[208:211], v[12:15]
	v_mfma_f32_16x16x32_bf16 v[8:11], v[160:163], v[208:211], v[8:11]
	v_mfma_f32_16x16x32_bf16 v[52:55], v[164:167], v[180:183], v[52:55]
	v_mfma_f32_16x16x32_bf16 v[48:51], v[172:175], v[180:183], v[48:51]
	v_mfma_f32_16x16x32_bf16 v[36:39], v[164:167], v[188:191], v[36:39]
	v_mfma_f32_16x16x32_bf16 v[32:35], v[172:175], v[188:191], v[32:35]
	v_mfma_f32_16x16x32_bf16 v[20:23], v[164:167], v[196:199], v[20:23]
	v_mfma_f32_16x16x32_bf16 v[16:19], v[172:175], v[196:199], v[16:19]
	v_mfma_f32_16x16x32_bf16 v[4:7], v[164:167], v[204:207], v[4:7]
	v_mfma_f32_16x16x32_bf16 v[0:3], v[172:175], v[204:207], v[0:3]
	v_mfma_f32_16x16x32_bf16 v[52:55], v[168:171], v[184:187], v[52:55]
	v_mfma_f32_16x16x32_bf16 v[48:51], v[176:179], v[184:187], v[48:51]
	v_mfma_f32_16x16x32_bf16 v[36:39], v[168:171], v[192:195], v[36:39]
	v_mfma_f32_16x16x32_bf16 v[32:35], v[176:179], v[192:195], v[32:35]
	v_mfma_f32_16x16x32_bf16 v[20:23], v[168:171], v[200:203], v[20:23]
	v_mfma_f32_16x16x32_bf16 v[16:19], v[176:179], v[200:203], v[16:19]
	v_mfma_f32_16x16x32_bf16 v[4:7], v[168:171], v[208:211], v[4:7]
	v_mfma_f32_16x16x32_bf16 v[0:3], v[176:179], v[208:211], v[0:3]
	s_setprio 0
	s_barrier
	s_add_i32 s65, 0, 0x18000
	s_add_i32 s66, 0, 0x1c000
	v_add_u32_e32 v160, s65, v145
	v_add_u32_e32 v176, s66, v145
	s_add_u32 s44, s44, 0x200000
	s_addc_u32 s45, s45, 0
	s_mov_b32 m0, s46
	v_lshl_add_u64 v[220:221], s[44:45], 0, v[128:129]
	global_load_lds_dwordx4 v[220:221], off
	v_lshl_add_u64 v[220:221], s[44:45], 0, v[130:131]
	s_mov_b32 m0, s47
	s_nop 0
	global_load_lds_dwordx4 v[220:221], off
	ds_read_b128 v[140:143], v160
	ds_read_b128 v[152:155], v160 offset:1024
	ds_read_b128 v[156:159], v160 offset:2048
	ds_read_b128 v[160:163], v160 offset:3072
	ds_read_b128 v[164:167], v176
	ds_read_b128 v[168:171], v176 offset:1024
	ds_read_b128 v[172:175], v176 offset:2048
	ds_read_b128 v[176:179], v176 offset:3072
	ds_read_b128 v[180:183], v151 offset:32768
	ds_read_b128 v[184:187], v151 offset:33792
	ds_read_b128 v[188:191], v151 offset:34816
	ds_read_b128 v[192:195], v151 offset:35840
	ds_read_b128 v[196:199], v151 offset:36864
	ds_read_b128 v[200:203], v151 offset:37888
	ds_read_b128 v[204:207], v151 offset:38912
	ds_read_b128 v[208:211], v151 offset:39936
	s_waitcnt vmcnt(8)
	s_waitcnt lgkmcnt(0)
	s_barrier
	s_setprio 1
	s_waitcnt lgkmcnt(0)
	v_mfma_f32_16x16x32_bf16 v[124:127], v[140:143], v[180:183], v[124:127]
	v_mfma_f32_16x16x32_bf16 v[120:123], v[156:159], v[180:183], v[120:123]
	v_mfma_f32_16x16x32_bf16 v[108:111], v[140:143], v[188:191], v[108:111]
	v_mfma_f32_16x16x32_bf16 v[104:107], v[156:159], v[188:191], v[104:107]
	v_mfma_f32_16x16x32_bf16 v[92:95], v[140:143], v[196:199], v[92:95]
	v_mfma_f32_16x16x32_bf16 v[88:91], v[156:159], v[196:199], v[88:91]
	v_mfma_f32_16x16x32_bf16 v[76:79], v[140:143], v[204:207], v[76:79]
	v_mfma_f32_16x16x32_bf16 v[72:75], v[156:159], v[204:207], v[72:75]
	v_mfma_f32_16x16x32_bf16 v[124:127], v[152:155], v[184:187], v[124:127]
	v_mfma_f32_16x16x32_bf16 v[120:123], v[160:163], v[184:187], v[120:123]
	v_mfma_f32_16x16x32_bf16 v[108:111], v[152:155], v[192:195], v[108:111]
	v_mfma_f32_16x16x32_bf16 v[104:107], v[160:163], v[192:195], v[104:107]
	v_mfma_f32_16x16x32_bf16 v[92:95], v[152:155], v[200:203], v[92:95]
	v_mfma_f32_16x16x32_bf16 v[88:91], v[160:163], v[200:203], v[88:91]
	v_mfma_f32_16x16x32_bf16 v[76:79], v[152:155], v[208:211], v[76:79]
	v_mfma_f32_16x16x32_bf16 v[72:75], v[160:163], v[208:211], v[72:75]
	v_mfma_f32_16x16x32_bf16 v[116:119], v[164:167], v[180:183], v[116:119]
	v_mfma_f32_16x16x32_bf16 v[112:115], v[172:175], v[180:183], v[112:115]
	v_mfma_f32_16x16x32_bf16 v[100:103], v[164:167], v[188:191], v[100:103]
	v_mfma_f32_16x16x32_bf16 v[96:99], v[172:175], v[188:191], v[96:99]
	v_mfma_f32_16x16x32_bf16 v[84:87], v[164:167], v[196:199], v[84:87]
	v_mfma_f32_16x16x32_bf16 v[80:83], v[172:175], v[196:199], v[80:83]
	v_mfma_f32_16x16x32_bf16 v[68:71], v[164:167], v[204:207], v[68:71]
	v_mfma_f32_16x16x32_bf16 v[64:67], v[172:175], v[204:207], v[64:67]
	v_mfma_f32_16x16x32_bf16 v[116:119], v[168:171], v[184:187], v[116:119]
	v_mfma_f32_16x16x32_bf16 v[112:115], v[176:179], v[184:187], v[112:115]
	v_mfma_f32_16x16x32_bf16 v[100:103], v[168:171], v[192:195], v[100:103]
	v_mfma_f32_16x16x32_bf16 v[96:99], v[176:179], v[192:195], v[96:99]
	v_mfma_f32_16x16x32_bf16 v[84:87], v[168:171], v[200:203], v[84:87]
	v_mfma_f32_16x16x32_bf16 v[80:83], v[176:179], v[200:203], v[80:83]
	v_mfma_f32_16x16x32_bf16 v[68:71], v[168:171], v[208:211], v[68:71]
	v_mfma_f32_16x16x32_bf16 v[64:67], v[176:179], v[208:211], v[64:67]
	s_setprio 0
	s_barrier
	s_add_i32 s44, s65, s94
	v_lshl_add_u64 v[212:213], v[212:213], 0, s[16:17]
	s_mov_b32 m0, s44
	s_nop 0
	global_load_lds_dwordx4 v[212:213], off
	s_add_i32 m0, s44, 0x2000
	s_add_u32 s42, s42, 0x200080
	v_lshl_add_u64 v[212:213], v[214:215], 0, s[16:17]
	s_addc_u32 s43, s43, 0
	s_add_i32 s44, s66, s94
	global_load_lds_dwordx4 v[212:213], off
	v_lshl_add_u64 v[212:213], s[42:43], 0, v[128:129]
	s_mov_b32 m0, s44
	s_nop 0
	global_load_lds_dwordx4 v[212:213], off
	v_lshl_add_u64 v[212:213], s[42:43], 0, v[130:131]
	s_add_i32 m0, s44, 0x2000
	s_nop 0
	global_load_lds_dwordx4 v[212:213], off
	v_lshl_add_u64 v[212:213], v[216:217], 0, s[16:17]
	s_mov_b32 m0, s48
	s_nop 0
	global_load_lds_dwordx4 v[212:213], off
	v_lshl_add_u64 v[212:213], v[218:219], 0, s[16:17]
	s_mov_b32 m0, s49
	s_nop 0
	global_load_lds_dwordx4 v[212:213], off
	ds_read_b128 v[180:183], v151 offset:49152
	ds_read_b128 v[184:187], v151 offset:50176
	ds_read_b128 v[188:191], v151 offset:51200
	ds_read_b128 v[192:195], v151 offset:52224
	ds_read_b128 v[196:199], v151 offset:53248
	ds_read_b128 v[200:203], v151 offset:54272
	ds_read_b128 v[204:207], v151 offset:55296
	ds_read_b128 v[208:211], v151 offset:56320
	s_waitcnt vmcnt(8)
	s_waitcnt lgkmcnt(0)
	s_barrier
	s_setprio 1
	s_waitcnt lgkmcnt(0)
	v_mfma_f32_16x16x32_bf16 v[60:63], v[140:143], v[180:183], v[60:63]
	v_mfma_f32_16x16x32_bf16 v[56:59], v[156:159], v[180:183], v[56:59]
	v_mfma_f32_16x16x32_bf16 v[44:47], v[140:143], v[188:191], v[44:47]
	v_mfma_f32_16x16x32_bf16 v[40:43], v[156:159], v[188:191], v[40:43]
	v_mfma_f32_16x16x32_bf16 v[28:31], v[140:143], v[196:199], v[28:31]
	v_mfma_f32_16x16x32_bf16 v[24:27], v[156:159], v[196:199], v[24:27]
	v_mfma_f32_16x16x32_bf16 v[12:15], v[140:143], v[204:207], v[12:15]
	v_mfma_f32_16x16x32_bf16 v[8:11], v[156:159], v[204:207], v[8:11]
	v_mfma_f32_16x16x32_bf16 v[60:63], v[152:155], v[184:187], v[60:63]
	v_mfma_f32_16x16x32_bf16 v[56:59], v[160:163], v[184:187], v[56:59]
	v_mfma_f32_16x16x32_bf16 v[44:47], v[152:155], v[192:195], v[44:47]
	v_mfma_f32_16x16x32_bf16 v[40:43], v[160:163], v[192:195], v[40:43]
	v_mfma_f32_16x16x32_bf16 v[28:31], v[152:155], v[200:203], v[28:31]
	v_mfma_f32_16x16x32_bf16 v[24:27], v[160:163], v[200:203], v[24:27]
	v_mfma_f32_16x16x32_bf16 v[12:15], v[152:155], v[208:211], v[12:15]
	v_mfma_f32_16x16x32_bf16 v[8:11], v[160:163], v[208:211], v[8:11]
	v_mfma_f32_16x16x32_bf16 v[52:55], v[164:167], v[180:183], v[52:55]
	v_mfma_f32_16x16x32_bf16 v[48:51], v[172:175], v[180:183], v[48:51]
	v_mfma_f32_16x16x32_bf16 v[36:39], v[164:167], v[188:191], v[36:39]
	v_mfma_f32_16x16x32_bf16 v[32:35], v[172:175], v[188:191], v[32:35]
	v_mfma_f32_16x16x32_bf16 v[20:23], v[164:167], v[196:199], v[20:23]
	v_mfma_f32_16x16x32_bf16 v[16:19], v[172:175], v[196:199], v[16:19]
	v_mfma_f32_16x16x32_bf16 v[4:7], v[164:167], v[204:207], v[4:7]
	v_mfma_f32_16x16x32_bf16 v[0:3], v[172:175], v[204:207], v[0:3]
	v_mfma_f32_16x16x32_bf16 v[52:55], v[168:171], v[184:187], v[52:55]
	v_mfma_f32_16x16x32_bf16 v[48:51], v[176:179], v[184:187], v[48:51]
	v_mfma_f32_16x16x32_bf16 v[36:39], v[168:171], v[192:195], v[36:39]
	v_mfma_f32_16x16x32_bf16 v[32:35], v[176:179], v[192:195], v[32:35]
	v_mfma_f32_16x16x32_bf16 v[20:23], v[168:171], v[200:203], v[20:23]
	v_mfma_f32_16x16x32_bf16 v[16:19], v[176:179], v[200:203], v[16:19]
	v_mfma_f32_16x16x32_bf16 v[4:7], v[168:171], v[208:211], v[4:7]
	v_mfma_f32_16x16x32_bf16 v[0:3], v[176:179], v[208:211], v[0:3]
	s_setprio 0
	s_barrier
	s_add_i32 s64, s64, 2
	s_add_u32 s40, s40, 0x100
	s_addc_u32 s41, s41, 0
	s_add_u32 s62, s62, 0x100
	s_addc_u32 s63, s63, 0
	s_cmpk_gt_u32 s64, 0x7d
	s_cbranch_scc0 .LBB0_2917
	s_and_b64 vcc, exec, s[58:59]
	s_cbranch_vccz .LBB0_2920
	s_barrier
